# all in-loop global loads bypass L1 (sc1), in-loop grid barrier drops buffer_inv; on top of v14
# baseline (speedup 1.0000x reference)
.LBB0_144:
	v_cmp_ne_u32_e32 vcc, 1, v225
	s_cbranch_vccnz .LBB0_187
	v_ashrrev_i32_e32 v3, 31, v0
	v_lshrrev_b32_e32 v3, 26, v3
	v_add_u32_e32 v3, v0, v3
	v_ashrrev_i32_e32 v10, 6, v3
	v_bfe_i32 v3, v0, 27, 1
	v_lshlrev_b32_e32 v2, 4, v0
	v_lshrrev_b32_e32 v3, 22, v3
	v_add_u32_e32 v3, v2, v3
	v_and_b32_e32 v3, 0xfffffc00, v3
	s_load_dwordx2 s[12:13], s[10:11], 0x0
	v_sub_u32_e32 v3, v2, v3
	v_lshrrev_b32_e32 v4, 4, v3
	v_bitop3_b32 v3, v4, v3, 32 bitop3:0x6c
	v_writelane_b32 v248, s28, 8
	s_and_b64 s[10:11], s[28:29], exec
	v_ashrrev_i32_e32 v5, 31, v3
	s_cselect_b32 s10, 0x2580000, 0
	v_lshrrev_b32_e32 v5, 26, v5
	s_waitcnt lgkmcnt(0)
	s_add_u32 s10, s12, s10
	v_add_u32_e32 v5, v3, v5
	s_addc_u32 s11, s13, 0
	v_lshlrev_b32_e32 v4, 3, v10
	v_ashrrev_i32_e32 v11, 6, v5
	v_and_b32_e32 v5, 0xc0, v5
	s_add_u32 s34, s12, 0x9000000
	v_and_b32_e32 v4, -16, v4
	v_sub_u32_e32 v3, v3, v5
	s_addc_u32 s35, s13, 0
	v_add_u32_e32 v4, v11, v4
	v_ashrrev_i16_sdwa v3, v230, sext(v3) dst_sel:DWORD dst_unused:UNUSED_PAD src0_sel:DWORD src1_sel:BYTE_0
	s_add_u32 s36, s10, 0x1180000
	v_lshlrev_b32_e32 v6, 5, v10
	v_bfe_i32 v12, v3, 0, 16
	v_lshlrev_b32_e32 v3, 1, v4
	v_lshrrev_b32_e32 v5, 2, v4
	v_and_b32_e32 v7, 3, v11
	s_mov_b32 s10, 0x1fffe0
	v_and_b32_e32 v6, 32, v6
	v_and_b32_e32 v3, 24, v3
	v_and_b32_e32 v5, 4, v5
	v_and_or_b32 v7, v4, s10, v7
	v_or3_b32 v3, v7, v5, v3
	v_add_lshl_u32 v5, v6, v12, 1
	v_add_u32_e32 v2, 0x2000, v2
	v_lshl_add_u32 v132, v3, 11, v5
	v_ashrrev_i32_e32 v3, 31, v2
	v_lshrrev_b32_e32 v3, 22, v3
	v_add_u32_e32 v3, v2, v3
	v_ashrrev_i32_e32 v13, 10, v3
	v_mul_i32_i24_e32 v3, 0x400, v13
	v_sub_u32_e32 v2, v2, v3
	v_lshrrev_b32_e32 v3, 4, v2
	v_bitop3_b32 v2, v3, v2, 32 bitop3:0x6c
	v_lshl_add_u32 v130, v4, 11, v5
	v_ashrrev_i32_e32 v4, 31, v2
	v_lshrrev_b32_e32 v4, 26, v4
	v_lshlrev_b32_e32 v3, 3, v13
	v_add_u32_e32 v4, v2, v4
	v_and_b32_e32 v3, -16, v3
	v_ashrrev_i32_e32 v14, 6, v4
	s_addc_u32 s37, s11, 0
	s_ashr_i32 s15, s14, 6
	v_add_u32_e32 v3, v14, v3
	v_and_b32_e32 v6, 3, v14
	s_ashr_i32 s23, s22, 31
	v_and_or_b32 v6, v3, s10, v6
	s_ashr_i32 s16, s14, 8
	s_lshl_b32 s44, s15, 10
	s_lshl_b64 s[10:11], s[22:23], 19
	s_add_u32 s40, s34, s10
	v_and_b32_e32 v4, 0xc0, v4
	s_addc_u32 s41, s35, s11
	s_ashr_i32 s43, s42, 31
	v_sub_u32_e32 v2, v2, v4
	s_lshl_b64 s[10:11], s[42:43], 19
	v_ashrrev_i16_sdwa v2, v230, sext(v2) dst_sel:DWORD dst_unused:UNUSED_PAD src0_sel:DWORD src1_sel:BYTE_0
	s_add_u32 s26, s36, s10
	v_lshlrev_b32_e32 v5, 5, v13
	v_bfe_i32 v15, v2, 0, 16
	v_lshlrev_b32_e32 v2, 1, v3
	v_lshrrev_b32_e32 v4, 2, v3
	s_addc_u32 s27, s37, s11
	s_add_i32 s23, s44, 0
	v_and_b32_e32 v5, 32, v5
	v_and_b32_e32 v2, 24, v2
	v_and_b32_e32 v4, 4, v4
	s_add_i32 m0, s23, 0x10000
	v_or3_b32 v2, v6, v4, v2
	v_add_lshl_u32 v4, v5, v15, 1
	global_load_lds_dwordx4 v132, s[26:27] sc1
	s_add_i32 m0, s23, 0x12000
	v_lshl_add_u32 v136, v2, 11, v4
	s_add_u32 s10, s26, 0x40000
	global_load_lds_dwordx4 v136, s[26:27] sc1
	s_addc_u32 s11, s27, 0
	s_add_i32 m0, s23, 0x14000
	s_add_i32 s45, s23, 0x2000
	global_load_lds_dwordx4 v132, s[10:11] sc1
	s_add_i32 m0, s23, 0x16000
	v_lshl_add_u32 v134, v3, 11, v4
	global_load_lds_dwordx4 v136, s[10:11] sc1
	s_mov_b32 m0, s23
	s_add_u32 s10, s40, 0x40000
	global_load_lds_dwordx4 v130, s[40:41] sc1
	s_mov_b32 m0, s45
	s_addc_u32 s11, s41, 0
	s_add_i32 s47, s23, 0x4000
	global_load_lds_dwordx4 v134, s[40:41] sc1
	s_mov_b32 m0, s47
	s_add_i32 s49, s23, 0x6000
	global_load_lds_dwordx4 v130, s[10:11] sc1
	s_mov_b32 m0, s49
	v_mov_b32_e32 v133, v1
	global_load_lds_dwordx4 v134, s[10:11] sc1
	v_mov_b32_e32 v137, v1
	v_mov_b32_e32 v131, v1
	v_mov_b32_e32 v135, v1
	s_cmp_eq_u32 s16, 1
	v_lshl_add_u64 v[8:9], s[26:27], 0, v[132:133]
	v_lshl_add_u64 v[6:7], s[26:27], 0, v[136:137]
	v_lshl_add_u64 v[2:3], s[40:41], 0, v[130:131]
	s_cselect_b64 s[10:11], -1, 0
	s_cmp_lg_u32 s16, 1
	v_lshl_add_u64 v[4:5], s[40:41], 0, v[134:135]
	v_writelane_b32 v248, s29, 9
	s_cbranch_scc1 .LBB0_147
	s_barrier
.LBB0_147:
	v_bfe_u32 v16, v0, 4, 2
	s_add_u32 s12, s12, 0xb200000
	v_and_b32_e32 v166, 15, v0
	v_lshlrev_b32_e32 v18, 4, v16
	v_lshlrev_b32_e32 v19, 2, v0
	s_addc_u32 s13, s13, 0
	s_and_b32 s18, s15, 3
	v_lshl_or_b32 v18, v166, 6, v18
	s_lshl_b32 s15, s16, 13
	v_and_b32_e32 v19, 32, v19
	s_add_i32 m0, s23, 0x18000
	v_lshl_add_u64 v[8:9], v[8:9], 0, s[98:99]
	s_lshl_b32 s51, s16, 6
	v_bitop3_b32 v20, v18, s15, v19 bitop3:0xde
	s_lshl_b32 s19, s18, 5
	s_lshl_b32 s15, s18, 12
	s_waitcnt vmcnt(2)
	s_barrier
	global_load_lds_dwordx4 v[8:9], off sc1
	v_lshl_add_u64 v[6:7], v[6:7], 0, s[98:99]
	s_add_i32 m0, s23, 0x1a000
	s_add_i32 s52, s23, 0x8000
	s_add_i32 s53, s23, 0xa000
	global_load_lds_dwordx4 v[6:7], off sc1
	v_lshl_add_u64 v[2:3], v[2:3], 0, s[98:99]
	s_mov_b32 m0, s52
	s_add_u32 s16, s26, 0x40080
	global_load_lds_dwordx4 v[2:3], off sc1
	v_lshl_add_u64 v[2:3], v[4:5], 0, s[98:99]
	s_mov_b32 m0, s53
	s_addc_u32 s17, s27, 0
	global_load_lds_dwordx4 v[2:3], off sc1
	s_add_i32 m0, s23, 0x1c000
	v_lshl_add_u64 v[2:3], s[16:17], 0, v[132:133]
	global_load_lds_dwordx4 v[2:3], off sc1
	v_lshl_add_u64 v[2:3], s[16:17], 0, v[136:137]
	s_add_i32 m0, s23, 0x1e000
	v_and_b32_e32 v0, 16, v0
	global_load_lds_dwordx4 v[2:3], off sc1
	v_cmp_eq_u32_e32 vcc, 0, v0
	v_lshlrev_b32_e32 v0, 14, v10
	v_and_b32_e32 v0, 0xffff8000, v0
	v_lshl_add_u32 v0, v11, 11, v0
	v_and_b32_e32 v2, 1, v10
	v_lshl_or_b32 v0, v2, 6, v0
	s_cmpk_lt_u32 s14, 0x100
	v_lshl_add_u32 v138, v12, 1, v0
	v_lshlrev_b32_e32 v0, 14, v13
	v_bitop3_b32 v167, v18, s15, v19 bitop3:0xde
	s_cselect_b64 s[14:15], -1, 0
	s_cmp_gt_u32 s18, 1
	v_and_b32_e32 v0, 0xffff8000, v0
	v_lshlrev_b32_e32 v17, 3, v16
	s_waitcnt vmcnt(6)
	s_cselect_b64 s[16:17], -1, 0
	s_add_i32 s20, s19, 0x440
	v_lshl_add_u32 v0, v14, 11, v0
	v_and_b32_e32 v2, 1, v13
	v_or_b32_e32 v169, s20, v17
	v_lshl_or_b32 v0, v2, 6, v0
	v_cmp_gt_u32_e64 s[38:39], 2, v16
	s_mov_b32 s54, 0
	v_cndmask_b32_e64 v168, v231, 1.0, vcc
	v_add_u32_e32 v170, 64, v169
	v_lshl_or_b32 v171, s18, 6, v17
	v_or_b32_e32 v172, s19, v17
	v_mov_b32_e32 v139, v1
	v_lshl_add_u32 v140, v15, 1, v0
	v_mov_b32_e32 v141, v1
	v_add_u32_e32 v173, 0, v20
	s_barrier
	s_branch .LBB0_150

.LBB0_160:
	s_add_u32 s26, s40, 0xfffc0080
	s_addc_u32 s27, s41, -1
	s_add_i32 s59, 0, 0x10000
	s_cmp_eq_u32 s58, 12
	s_cselect_b32 vcc_hi, s29, s27
	s_cselect_b32 vcc_lo, s43, s26
	v_add_u32_e32 v0, s59, v167
	s_cselect_b32 s27, s21, s57
	s_cselect_b32 s26, s55, s56
	s_add_i32 s62, 0, 0x14000
	ds_read_b128 v[142:145], v0
	ds_read_b128 v[146:149], v0 offset:1024
	ds_read_b128 v[150:153], v0 offset:2048
	ds_read_b128 v[154:157], v0 offset:3072
	v_add_u32_e32 v0, s62, v167
	ds_read_b128 v[158:161], v0
	ds_read_b128 v[162:165], v0 offset:1024
	ds_read_b128 v[174:177], v0 offset:2048
	ds_read_b128 v[178:181], v0 offset:3072
	v_lshl_add_u64 v[214:215], s[40:41], 0, v[138:139]
	s_add_i32 m0, s23, 0xc000
	ds_read_b128 v[182:185], v173
	ds_read_b128 v[186:189], v173 offset:1024
	ds_read_b128 v[190:193], v173 offset:2048
	ds_read_b128 v[194:197], v173 offset:3072
	ds_read_b128 v[198:201], v173 offset:4096
	ds_read_b128 v[202:205], v173 offset:5120
	ds_read_b128 v[206:209], v173 offset:6144
	ds_read_b128 v[210:213], v173 offset:7168
	global_load_lds_dwordx4 v[214:215], off sc1
	v_lshl_add_u64 v[214:215], s[40:41], 0, v[140:141]
	s_add_i32 m0, s23, 0xe000
	s_nop 0
	global_load_lds_dwordx4 v[214:215], off sc1
	s_waitcnt vmcnt(8)
	s_waitcnt lgkmcnt(0)
	s_barrier
	s_setprio 1
	s_waitcnt lgkmcnt(0)
	v_mfma_f32_16x16x32_bf16 v[126:129], v[142:145], v[182:185], v[126:129]
	v_mfma_f32_16x16x32_bf16 v[122:125], v[150:153], v[182:185], v[122:125]
	v_mfma_f32_16x16x32_bf16 v[118:121], v[142:145], v[190:193], v[118:121]
	v_mfma_f32_16x16x32_bf16 v[114:117], v[150:153], v[190:193], v[114:117]
	v_mfma_f32_16x16x32_bf16 v[110:113], v[142:145], v[198:201], v[110:113]
	v_mfma_f32_16x16x32_bf16 v[106:109], v[150:153], v[198:201], v[106:109]
	v_mfma_f32_16x16x32_bf16 v[102:105], v[142:145], v[206:209], v[102:105]
	v_mfma_f32_16x16x32_bf16 v[98:101], v[150:153], v[206:209], v[98:101]
	v_mfma_f32_16x16x32_bf16 v[126:129], v[146:149], v[186:189], v[126:129]
	v_mfma_f32_16x16x32_bf16 v[122:125], v[154:157], v[186:189], v[122:125]
	v_mfma_f32_16x16x32_bf16 v[118:121], v[146:149], v[194:197], v[118:121]
	v_mfma_f32_16x16x32_bf16 v[114:117], v[154:157], v[194:197], v[114:117]
	v_mfma_f32_16x16x32_bf16 v[110:113], v[146:149], v[202:205], v[110:113]
	v_mfma_f32_16x16x32_bf16 v[106:109], v[154:157], v[202:205], v[106:109]
	v_mfma_f32_16x16x32_bf16 v[102:105], v[146:149], v[210:213], v[102:105]
	v_mfma_f32_16x16x32_bf16 v[98:101], v[154:157], v[210:213], v[98:101]
	s_setprio 0
	s_setprio 1
	v_mfma_f32_16x16x32_bf16 v[82:85], v[158:161], v[182:185], v[82:85]
	v_mfma_f32_16x16x32_bf16 v[74:77], v[174:177], v[182:185], v[74:77]
	v_mfma_f32_16x16x32_bf16 v[70:73], v[158:161], v[190:193], v[70:73]
	v_mfma_f32_16x16x32_bf16 v[62:65], v[174:177], v[190:193], v[62:65]
	v_mfma_f32_16x16x32_bf16 v[54:57], v[158:161], v[198:201], v[54:57]
	v_mfma_f32_16x16x32_bf16 v[46:49], v[174:177], v[198:201], v[46:49]
	v_mfma_f32_16x16x32_bf16 v[38:41], v[158:161], v[206:209], v[38:41]
	v_mfma_f32_16x16x32_bf16 v[34:37], v[174:177], v[206:209], v[34:37]
	v_mfma_f32_16x16x32_bf16 v[82:85], v[162:165], v[186:189], v[82:85]
	v_mfma_f32_16x16x32_bf16 v[74:77], v[178:181], v[186:189], v[74:77]
	v_mfma_f32_16x16x32_bf16 v[70:73], v[162:165], v[194:197], v[70:73]
	v_mfma_f32_16x16x32_bf16 v[62:65], v[178:181], v[194:197], v[62:65]
	v_mfma_f32_16x16x32_bf16 v[54:57], v[162:165], v[202:205], v[54:57]
	v_mfma_f32_16x16x32_bf16 v[46:49], v[178:181], v[202:205], v[46:49]
	v_mfma_f32_16x16x32_bf16 v[38:41], v[162:165], v[210:213], v[38:41]
	v_mfma_f32_16x16x32_bf16 v[34:37], v[178:181], v[210:213], v[34:37]
	s_setprio 0
	s_barrier
	s_add_i32 s59, s59, s44
	v_lshl_add_u64 v[214:215], s[26:27], 0, v[132:133]
	s_mov_b32 m0, s59
	ds_read_b128 v[182:185], v173 offset:16384
	ds_read_b128 v[186:189], v173 offset:17408
	ds_read_b128 v[190:193], v173 offset:18432
	ds_read_b128 v[194:197], v173 offset:19456
	ds_read_b128 v[198:201], v173 offset:20480
	ds_read_b128 v[202:205], v173 offset:21504
	ds_read_b128 v[206:209], v173 offset:22528
	ds_read_b128 v[210:213], v173 offset:23552
	global_load_lds_dwordx4 v[214:215], off sc1
	s_add_i32 m0, s59, 0x2000
	s_add_u32 s60, s26, 0x40000
	v_lshl_add_u64 v[216:217], s[26:27], 0, v[136:137]
	s_addc_u32 s61, s27, 0
	s_add_i32 s59, s62, s44
	global_load_lds_dwordx4 v[216:217], off sc1
	v_lshl_add_u64 v[218:219], s[60:61], 0, v[132:133]
	s_mov_b32 m0, s59
	v_lshl_add_u64 v[220:221], vcc, 0, v[134:135]
	global_load_lds_dwordx4 v[218:219], off sc1
	v_lshl_add_u64 v[218:219], s[60:61], 0, v[136:137]
	s_add_i32 m0, s59, 0x2000
	s_nop 0
	global_load_lds_dwordx4 v[218:219], off sc1
	v_lshl_add_u64 v[218:219], vcc, 0, v[130:131]
	s_mov_b32 m0, s23
	s_nop 0
	global_load_lds_dwordx4 v[218:219], off sc1
	s_mov_b32 m0, s45
	s_nop 0
	global_load_lds_dwordx4 v[220:221], off sc1
	s_waitcnt vmcnt(8)
	s_waitcnt lgkmcnt(0)
	s_barrier
	s_setprio 1
	s_waitcnt lgkmcnt(0)
	v_mfma_f32_16x16x32_bf16 v[94:97], v[142:145], v[182:185], v[94:97]
	v_mfma_f32_16x16x32_bf16 v[90:93], v[150:153], v[182:185], v[90:93]
	v_mfma_f32_16x16x32_bf16 v[86:89], v[142:145], v[190:193], v[86:89]
	v_mfma_f32_16x16x32_bf16 v[78:81], v[150:153], v[190:193], v[78:81]
	v_mfma_f32_16x16x32_bf16 v[66:69], v[142:145], v[198:201], v[66:69]
	v_mfma_f32_16x16x32_bf16 v[58:61], v[150:153], v[198:201], v[58:61]
	v_mfma_f32_16x16x32_bf16 v[50:53], v[142:145], v[206:209], v[50:53]
	v_mfma_f32_16x16x32_bf16 v[42:45], v[150:153], v[206:209], v[42:45]
	v_mfma_f32_16x16x32_bf16 v[94:97], v[146:149], v[186:189], v[94:97]
	v_mfma_f32_16x16x32_bf16 v[90:93], v[154:157], v[186:189], v[90:93]
	v_mfma_f32_16x16x32_bf16 v[86:89], v[146:149], v[194:197], v[86:89]
	v_mfma_f32_16x16x32_bf16 v[78:81], v[154:157], v[194:197], v[78:81]
	v_mfma_f32_16x16x32_bf16 v[66:69], v[146:149], v[202:205], v[66:69]
	v_mfma_f32_16x16x32_bf16 v[58:61], v[154:157], v[202:205], v[58:61]
	v_mfma_f32_16x16x32_bf16 v[50:53], v[146:149], v[210:213], v[50:53]
	v_mfma_f32_16x16x32_bf16 v[42:45], v[154:157], v[210:213], v[42:45]
	s_setprio 0
	s_setprio 1
	v_mfma_f32_16x16x32_bf16 v[30:33], v[158:161], v[182:185], v[30:33]
	v_mfma_f32_16x16x32_bf16 v[26:29], v[174:177], v[182:185], v[26:29]
	v_mfma_f32_16x16x32_bf16 v[22:25], v[158:161], v[190:193], v[22:25]
	v_mfma_f32_16x16x32_bf16 v[18:21], v[174:177], v[190:193], v[18:21]
	v_mfma_f32_16x16x32_bf16 v[14:17], v[158:161], v[198:201], v[14:17]
	v_mfma_f32_16x16x32_bf16 v[10:13], v[174:177], v[198:201], v[10:13]
	v_mfma_f32_16x16x32_bf16 v[6:9], v[158:161], v[206:209], v[6:9]
	v_mfma_f32_16x16x32_bf16 v[2:5], v[174:177], v[206:209], v[2:5]
	v_mfma_f32_16x16x32_bf16 v[30:33], v[162:165], v[186:189], v[30:33]
	v_mfma_f32_16x16x32_bf16 v[26:29], v[178:181], v[186:189], v[26:29]
	v_mfma_f32_16x16x32_bf16 v[22:25], v[162:165], v[194:197], v[22:25]
	v_mfma_f32_16x16x32_bf16 v[18:21], v[178:181], v[194:197], v[18:21]
	v_mfma_f32_16x16x32_bf16 v[14:17], v[162:165], v[202:205], v[14:17]
	v_mfma_f32_16x16x32_bf16 v[10:13], v[178:181], v[202:205], v[10:13]
	v_mfma_f32_16x16x32_bf16 v[6:9], v[162:165], v[210:213], v[6:9]
	v_mfma_f32_16x16x32_bf16 v[2:5], v[178:181], v[210:213], v[2:5]
	s_setprio 0
	s_barrier
	s_add_i32 s59, 0, 0x18000
	v_add_u32_e32 v0, s59, v167
	s_add_i32 s62, 0, 0x1c000
	ds_read_b128 v[142:145], v0
	ds_read_b128 v[146:149], v0 offset:1024
	ds_read_b128 v[150:153], v0 offset:2048
	ds_read_b128 v[154:157], v0 offset:3072
	v_add_u32_e32 v0, s62, v167
	ds_read_b128 v[158:161], v0
	ds_read_b128 v[162:165], v0 offset:1024
	ds_read_b128 v[174:177], v0 offset:2048
	ds_read_b128 v[178:181], v0 offset:3072
	s_add_u32 s60, vcc_lo, 0x40000
	s_addc_u32 s61, vcc_hi, 0
	s_mov_b32 m0, s47
	v_lshl_add_u64 v[222:223], s[60:61], 0, v[130:131]
	ds_read_b128 v[182:185], v173 offset:32768
	ds_read_b128 v[186:189], v173 offset:33792
	ds_read_b128 v[190:193], v173 offset:34816
	ds_read_b128 v[194:197], v173 offset:35840
	ds_read_b128 v[198:201], v173 offset:36864
	ds_read_b128 v[202:205], v173 offset:37888
	ds_read_b128 v[206:209], v173 offset:38912
	ds_read_b128 v[210:213], v173 offset:39936
	global_load_lds_dwordx4 v[222:223], off sc1
	v_lshl_add_u64 v[222:223], s[60:61], 0, v[134:135]
	s_mov_b32 m0, s49
	s_nop 0
	global_load_lds_dwordx4 v[222:223], off sc1
	s_waitcnt vmcnt(8)
	s_waitcnt lgkmcnt(0)
	s_barrier
	s_setprio 1
	s_waitcnt lgkmcnt(0)
	v_mfma_f32_16x16x32_bf16 v[126:129], v[142:145], v[182:185], v[126:129]
	v_mfma_f32_16x16x32_bf16 v[122:125], v[150:153], v[182:185], v[122:125]
	v_mfma_f32_16x16x32_bf16 v[118:121], v[142:145], v[190:193], v[118:121]
	v_mfma_f32_16x16x32_bf16 v[114:117], v[150:153], v[190:193], v[114:117]
	v_mfma_f32_16x16x32_bf16 v[110:113], v[142:145], v[198:201], v[110:113]
	v_mfma_f32_16x16x32_bf16 v[106:109], v[150:153], v[198:201], v[106:109]
	v_mfma_f32_16x16x32_bf16 v[102:105], v[142:145], v[206:209], v[102:105]
	v_mfma_f32_16x16x32_bf16 v[98:101], v[150:153], v[206:209], v[98:101]
	v_mfma_f32_16x16x32_bf16 v[126:129], v[146:149], v[186:189], v[126:129]
	v_mfma_f32_16x16x32_bf16 v[122:125], v[154:157], v[186:189], v[122:125]
	v_mfma_f32_16x16x32_bf16 v[118:121], v[146:149], v[194:197], v[118:121]
	v_mfma_f32_16x16x32_bf16 v[114:117], v[154:157], v[194:197], v[114:117]
	v_mfma_f32_16x16x32_bf16 v[110:113], v[146:149], v[202:205], v[110:113]
	v_mfma_f32_16x16x32_bf16 v[106:109], v[154:157], v[202:205], v[106:109]
	v_mfma_f32_16x16x32_bf16 v[102:105], v[146:149], v[210:213], v[102:105]
	v_mfma_f32_16x16x32_bf16 v[98:101], v[154:157], v[210:213], v[98:101]
	s_setprio 0
	s_setprio 1
	v_mfma_f32_16x16x32_bf16 v[82:85], v[158:161], v[182:185], v[82:85]
	v_mfma_f32_16x16x32_bf16 v[74:77], v[174:177], v[182:185], v[74:77]
	v_mfma_f32_16x16x32_bf16 v[70:73], v[158:161], v[190:193], v[70:73]
	v_mfma_f32_16x16x32_bf16 v[62:65], v[174:177], v[190:193], v[62:65]
	v_mfma_f32_16x16x32_bf16 v[54:57], v[158:161], v[198:201], v[54:57]
	v_mfma_f32_16x16x32_bf16 v[46:49], v[174:177], v[198:201], v[46:49]
	v_mfma_f32_16x16x32_bf16 v[38:41], v[158:161], v[206:209], v[38:41]
	v_mfma_f32_16x16x32_bf16 v[34:37], v[174:177], v[206:209], v[34:37]
	v_mfma_f32_16x16x32_bf16 v[82:85], v[162:165], v[186:189], v[82:85]
	v_mfma_f32_16x16x32_bf16 v[74:77], v[178:181], v[186:189], v[74:77]
	v_mfma_f32_16x16x32_bf16 v[70:73], v[162:165], v[194:197], v[70:73]
	v_mfma_f32_16x16x32_bf16 v[62:65], v[178:181], v[194:197], v[62:65]
	v_mfma_f32_16x16x32_bf16 v[54:57], v[162:165], v[202:205], v[54:57]
	v_mfma_f32_16x16x32_bf16 v[46:49], v[178:181], v[202:205], v[46:49]
	v_mfma_f32_16x16x32_bf16 v[38:41], v[162:165], v[210:213], v[38:41]
	v_mfma_f32_16x16x32_bf16 v[34:37], v[178:181], v[210:213], v[34:37]
	s_setprio 0
	s_barrier
	s_add_i32 s59, s59, s44
	v_lshl_add_u64 v[214:215], v[214:215], 0, s[98:99]
	s_mov_b32 m0, s59
	ds_read_b128 v[182:185], v173 offset:49152
	ds_read_b128 v[186:189], v173 offset:50176
	ds_read_b128 v[190:193], v173 offset:51200
	ds_read_b128 v[194:197], v173 offset:52224
	ds_read_b128 v[198:201], v173 offset:53248
	ds_read_b128 v[202:205], v173 offset:54272
	ds_read_b128 v[206:209], v173 offset:55296
	ds_read_b128 v[210:213], v173 offset:56320
	global_load_lds_dwordx4 v[214:215], off sc1
	s_add_i32 m0, s59, 0x2000
	s_add_u32 s26, s26, 0x40080
	v_lshl_add_u64 v[214:215], v[216:217], 0, s[98:99]
	s_addc_u32 s27, s27, 0
	s_add_i32 s59, s62, s44
	global_load_lds_dwordx4 v[214:215], off sc1
	v_lshl_add_u64 v[214:215], s[26:27], 0, v[132:133]
	s_mov_b32 m0, s59
	s_nop 0
	global_load_lds_dwordx4 v[214:215], off sc1
	v_lshl_add_u64 v[214:215], s[26:27], 0, v[136:137]
	s_add_i32 m0, s59, 0x2000
	s_nop 0
	global_load_lds_dwordx4 v[214:215], off sc1
	v_lshl_add_u64 v[214:215], v[218:219], 0, s[98:99]
	s_mov_b32 m0, s52
	s_nop 0
	global_load_lds_dwordx4 v[214:215], off sc1
	v_lshl_add_u64 v[214:215], v[220:221], 0, s[98:99]
	s_mov_b32 m0, s53
	s_nop 0
	global_load_lds_dwordx4 v[214:215], off sc1
	s_waitcnt vmcnt(8)
	s_waitcnt lgkmcnt(0)
	s_barrier
	s_setprio 1
	s_waitcnt lgkmcnt(0)
	v_mfma_f32_16x16x32_bf16 v[94:97], v[142:145], v[182:185], v[94:97]
	v_mfma_f32_16x16x32_bf16 v[90:93], v[150:153], v[182:185], v[90:93]
	v_mfma_f32_16x16x32_bf16 v[86:89], v[142:145], v[190:193], v[86:89]
	v_mfma_f32_16x16x32_bf16 v[78:81], v[150:153], v[190:193], v[78:81]
	v_mfma_f32_16x16x32_bf16 v[66:69], v[142:145], v[198:201], v[66:69]
	v_mfma_f32_16x16x32_bf16 v[58:61], v[150:153], v[198:201], v[58:61]
	v_mfma_f32_16x16x32_bf16 v[50:53], v[142:145], v[206:209], v[50:53]
	v_mfma_f32_16x16x32_bf16 v[42:45], v[150:153], v[206:209], v[42:45]
	v_mfma_f32_16x16x32_bf16 v[94:97], v[146:149], v[186:189], v[94:97]
	v_mfma_f32_16x16x32_bf16 v[90:93], v[154:157], v[186:189], v[90:93]
	v_mfma_f32_16x16x32_bf16 v[86:89], v[146:149], v[194:197], v[86:89]
	v_mfma_f32_16x16x32_bf16 v[78:81], v[154:157], v[194:197], v[78:81]
	v_mfma_f32_16x16x32_bf16 v[66:69], v[146:149], v[202:205], v[66:69]
	v_mfma_f32_16x16x32_bf16 v[58:61], v[154:157], v[202:205], v[58:61]
	v_mfma_f32_16x16x32_bf16 v[50:53], v[146:149], v[210:213], v[50:53]
	v_mfma_f32_16x16x32_bf16 v[42:45], v[154:157], v[210:213], v[42:45]
	s_setprio 0
	s_setprio 1
	v_mfma_f32_16x16x32_bf16 v[30:33], v[158:161], v[182:185], v[30:33]
	v_mfma_f32_16x16x32_bf16 v[26:29], v[174:177], v[182:185], v[26:29]
	v_mfma_f32_16x16x32_bf16 v[22:25], v[158:161], v[190:193], v[22:25]
	v_mfma_f32_16x16x32_bf16 v[18:21], v[174:177], v[190:193], v[18:21]
	v_mfma_f32_16x16x32_bf16 v[14:17], v[158:161], v[198:201], v[14:17]
	v_mfma_f32_16x16x32_bf16 v[10:13], v[174:177], v[198:201], v[10:13]
	v_mfma_f32_16x16x32_bf16 v[6:9], v[158:161], v[206:209], v[6:9]
	v_mfma_f32_16x16x32_bf16 v[2:5], v[174:177], v[206:209], v[2:5]
	v_mfma_f32_16x16x32_bf16 v[30:33], v[162:165], v[186:189], v[30:33]
	v_mfma_f32_16x16x32_bf16 v[26:29], v[178:181], v[186:189], v[26:29]
	v_mfma_f32_16x16x32_bf16 v[22:25], v[162:165], v[194:197], v[22:25]
	v_mfma_f32_16x16x32_bf16 v[18:21], v[178:181], v[194:197], v[18:21]
	v_mfma_f32_16x16x32_bf16 v[14:17], v[162:165], v[202:205], v[14:17]
	v_mfma_f32_16x16x32_bf16 v[10:13], v[178:181], v[202:205], v[10:13]
	v_mfma_f32_16x16x32_bf16 v[6:9], v[162:165], v[210:213], v[6:9]
	v_mfma_f32_16x16x32_bf16 v[2:5], v[178:181], v[210:213], v[2:5]
	s_setprio 0
	s_barrier
	s_add_i32 s58, s58, 2
	s_add_u32 s40, s40, 0x100
	s_addc_u32 s41, s41, 0
	s_add_u32 s56, s56, 0x100
	s_addc_u32 s57, s57, 0
	s_cmp_gt_u32 s58, 13
	s_cbranch_scc0 .LBB0_160
	s_and_b64 vcc, exec, s[14:15]
	s_cbranch_vccz .LBB0_163
	s_barrier

.LBB0_199:
	s_andn2_b64 vcc, exec, s[14:15]
	s_cbranch_vccnz .LBB0_357
	v_bfe_i32 v3, v14, 27, 1
	v_lshlrev_b32_e32 v2, 4, v14
	v_lshrrev_b32_e32 v3, 22, v3
	v_add_u32_e32 v3, v2, v3
	v_and_b32_e32 v3, 0xfffffc00, v3
	v_sub_u32_e32 v3, v2, v3
	v_ashrrev_i32_e32 v0, 31, v14
	v_lshrrev_b32_e32 v4, 4, v3
	v_lshrrev_b32_e32 v0, 26, v0
	v_bitop3_b32 v3, v4, v3, 32 bitop3:0x6c
	v_add_u32_e32 v0, v14, v0
	v_ashrrev_i32_e32 v5, 31, v3
	v_ashrrev_i32_e32 v0, 6, v0
	v_lshrrev_b32_e32 v5, 26, v5
	v_lshlrev_b32_e32 v4, 3, v0
	v_add_u32_e32 v5, v3, v5
	v_and_b32_e32 v4, -16, v4
	v_ashrrev_i32_e32 v6, 6, v5
	v_lshlrev_b32_e32 v0, 5, v0
	v_add_u32_e32 v4, v6, v4
	v_and_b32_e32 v15, 32, v0
	v_and_b32_e32 v0, 0xc0, v5
	v_sub_u32_e32 v0, v3, v0
	v_lshlrev_b32_e32 v3, 1, v4
	v_lshrrev_b32_e32 v5, 2, v4
	v_and_b32_e32 v6, 3, v6
	s_mov_b32 s14, 0x7fffffe0
	v_ashrrev_i16_sdwa v0, v230, sext(v0) dst_sel:DWORD dst_unused:UNUSED_PAD src0_sel:DWORD src1_sel:BYTE_0
	v_and_b32_e32 v3, 24, v3
	v_and_b32_e32 v5, 4, v5
	v_and_or_b32 v6, v4, s14, v6
	v_bfe_i32 v16, v0, 0, 16
	v_or3_b32 v3, v6, v5, v3
	v_add_u32_e32 v0, v15, v16
	v_mul_lo_u32 v17, v4, s13
	v_mul_lo_u32 v3, v3, s13
	v_add_u32_e32 v2, 0x2000, v2
	v_add_lshl_u32 v138, v0, v17, 1
	v_add_lshl_u32 v0, v3, v0, 1
	v_ashrrev_i32_e32 v3, 31, v2
	v_lshrrev_b32_e32 v3, 22, v3
	v_add_u32_e32 v3, v2, v3
	v_ashrrev_i32_e32 v3, 10, v3
	v_mul_i32_i24_e32 v4, 0x400, v3
	v_sub_u32_e32 v2, v2, v4
	v_lshrrev_b32_e32 v4, 4, v2
	v_bitop3_b32 v2, v4, v2, 32 bitop3:0x6c
	v_ashrrev_i32_e32 v5, 31, v2
	v_lshrrev_b32_e32 v5, 26, v5
	v_lshlrev_b32_e32 v4, 3, v3
	v_add_u32_e32 v5, v2, v5
	v_and_b32_e32 v4, -16, v4
	v_ashrrev_i32_e32 v6, 6, v5
	s_ashr_i32 s16, s24, 6
	s_ashr_i32 s25, s24, 8
	v_add_u32_e32 v4, v6, v4
	v_and_b32_e32 v6, 3, v6
	s_lshl_b32 s49, s16, 10
	v_and_or_b32 v6, v4, s14, v6
	v_writelane_b32 v248, s28, 8
	s_and_b64 s[14:15], s[28:29], exec
	s_cselect_b32 s17, 0x2580000, 0
	s_and_b64 s[14:15], s[18:19], exec
	s_mov_b32 s14, 0x9000000
	v_lshlrev_b32_e32 v3, 5, v3
	s_cselect_b32 s26, s14, 0xb200000
	s_mov_b32 s14, 0x1300000
	v_and_b32_e32 v18, 32, v3
	v_and_b32_e32 v3, 0xc0, v5
	s_cselect_b32 s27, s14, 0x2000000
	s_cmp_eq_u32 s50, 2
	v_sub_u32_e32 v2, v2, v3
	v_lshlrev_b32_e32 v3, 1, v4
	v_lshrrev_b32_e32 v5, 2, v4
	s_cselect_b64 s[22:23], -1, 0
	v_and_b32_e32 v3, 24, v3
	v_and_b32_e32 v5, 4, v5
	s_and_b64 s[14:15], s[22:23], exec
	v_or3_b32 v3, v6, v5, v3
	s_cselect_b32 s14, 0xb00000, s27
	s_lshl_b32 s96, s13, 8
	s_lshl_b32 s34, s13, 9
	v_mul_lo_u32 v20, v4, s13
	v_mul_lo_u32 v3, v3, s13
	s_waitcnt lgkmcnt(0)
	s_add_u32 s13, s20, s17
	s_addc_u32 s15, s21, 0
	s_add_u32 s44, s20, s26
	s_addc_u32 s45, s21, 0
	s_add_u32 s13, s13, s14
	s_addc_u32 s14, s15, 0
	s_add_u32 s37, s13, 0x100000
	s_addc_u32 s92, s14, 0
	s_ashr_i32 s13, s12, 31
	s_lshl_b64 s[14:15], s[12:13], 7
	s_mul_i32 s27, s34, s58
	s_mul_hi_i32 s13, s34, s58
	s_add_u32 s27, s37, s27
	s_addc_u32 s13, s92, s13
	s_add_u32 s40, s27, s14
	s_addc_u32 s41, s13, s15
	s_add_i32 s93, s49, 0
	s_add_i32 m0, s93, 0x10000
	v_ashrrev_i16_sdwa v2, v230, sext(v2) dst_sel:DWORD dst_unused:UNUSED_PAD src0_sel:DWORD src1_sel:BYTE_0
	s_mul_i32 s26, s34, s43
	global_load_lds_dwordx4 v0, s[40:41] sc1
	s_add_i32 m0, s93, 0x12000
	v_bfe_i32 v19, v2, 0, 16
	s_mul_hi_i32 s17, s34, s43
	s_add_u32 s13, s44, s26
	v_add_u32_e32 v2, v18, v19
	s_addc_u32 s17, s45, s17
	v_add_lshl_u32 v142, v3, v2, 1
	s_add_u32 s26, s40, s96
	global_load_lds_dwordx4 v142, s[40:41] sc1
	s_addc_u32 s27, s41, 0
	s_add_i32 m0, s93, 0x14000
	v_writelane_b32 v248, s29, 9
	global_load_lds_dwordx4 v0, s[26:27] sc1
	s_add_i32 m0, s93, 0x16000
	s_add_u32 s28, s13, s14
	s_addc_u32 s29, s17, s15
	s_add_i32 s88, s93, 0x2000
	global_load_lds_dwordx4 v142, s[26:27] sc1
	s_mov_b32 m0, s93
	s_add_u32 s14, s28, s96
	v_add_lshl_u32 v140, v2, v20, 1
	global_load_lds_dwordx4 v138, s[28:29] sc1
	s_mov_b32 m0, s88
	s_addc_u32 s15, s29, 0
	s_add_i32 s89, s93, 0x4000
	global_load_lds_dwordx4 v140, s[28:29] sc1
	s_mov_b32 m0, s89
	s_add_i32 s52, s93, 0x6000
	global_load_lds_dwordx4 v138, s[14:15] sc1
	s_mov_b32 m0, s52
	v_mov_b32_e32 v143, v1
	global_load_lds_dwordx4 v140, s[14:15] sc1
	v_mov_b32_e32 v139, v1
	v_mov_b32_e32 v141, v1
	s_cmp_eq_u32 s25, 1
	v_lshl_add_u64 v[2:3], s[40:41], 0, v[0:1]
	v_lshl_add_u64 v[4:5], s[40:41], 0, v[142:143]
	v_lshl_add_u64 v[6:7], s[26:27], 0, v[0:1]
	v_lshl_add_u64 v[8:9], s[26:27], 0, v[142:143]
	v_lshl_add_u64 v[10:11], s[28:29], 0, v[138:139]
	v_lshl_add_u64 v[12:13], s[28:29], 0, v[140:141]
	s_cselect_b64 s[14:15], -1, 0
	s_cmp_lg_u32 s25, 1
	s_cbranch_scc1 .LBB0_202
	s_barrier
.LBB0_202:
	s_lshl_b32 s16, s16, 5
	s_and_b32 s26, s16, 0x60
	s_lshl_b32 s13, s25, 13
	s_lshl_b32 s27, s26, 7
	s_and_b64 s[16:17], s[18:19], exec
	s_movk_i32 s16, 0x1400
	s_cselect_b32 s30, s16, 0x2000
	v_readlane_b32 s16, v248, 8
	v_readlane_b32 s17, v248, 9
	s_and_b64 s[16:17], s[16:17], exec
	s_cselect_b32 s31, 0x2d000, 0
	s_add_u32 s16, s20, 0x4c00000
	s_addc_u32 s17, s21, 0
	s_add_u32 s31, s20, s31
	s_addc_u32 s38, s21, 0
	s_and_b64 s[20:21], s[22:23], exec
	s_cselect_b32 s20, 0x800, s30
	s_lshl_b32 s20, s20, 2
	s_add_u32 s53, s31, s20
	s_addc_u32 s94, s38, 0
	s_add_i32 m0, s93, 0x18000
	v_lshl_add_u64 v[2:3], v[2:3], 0, s[98:99]
	s_waitcnt vmcnt(2)
	s_barrier
	global_load_lds_dwordx4 v[2:3], off sc1
	v_lshl_add_u64 v[2:3], v[4:5], 0, s[98:99]
	s_add_i32 m0, s93, 0x1a000
	s_add_i32 s95, s93, 0x8000
	global_load_lds_dwordx4 v[2:3], off sc1
	v_lshl_add_u64 v[2:3], v[10:11], 0, s[98:99]
	s_mov_b32 m0, s95
	s_add_i32 s54, s93, 0xa000
	global_load_lds_dwordx4 v[2:3], off sc1
	v_lshl_add_u64 v[2:3], v[12:13], 0, s[98:99]
	s_mov_b32 m0, s54
	v_cndmask_b32_e64 v144, 0.5, 1.0, s[18:19]
	global_load_lds_dwordx4 v[2:3], off sc1
	s_add_i32 m0, s93, 0x1c000
	v_lshl_add_u64 v[2:3], v[6:7], 0, s[98:99]
	global_load_lds_dwordx4 v[2:3], off sc1
	v_lshl_add_u64 v[2:3], v[8:9], 0, s[98:99]
	s_add_i32 m0, s93, 0x1e000
	s_cmpk_lt_u32 s24, 0x100
	global_load_lds_dwordx4 v[2:3], off sc1
	v_lshrrev_b32_e32 v3, 1, v14
	v_and_b32_e32 v3, 24, v3
	v_and_b32_e32 v2, 15, v14
	v_lshlrev_b32_e32 v4, 1, v3
	v_lshl_or_b32 v174, s25, 6, v2
	v_lshl_or_b32 v2, v2, 6, v4
	v_lshlrev_b32_e32 v4, 2, v14
	v_and_b32_e32 v4, 32, v4
	v_bitop3_b32 v5, v2, s13, v4 bitop3:0xde
	v_bitop3_b32 v175, v2, s27, v4 bitop3:0xde
	v_cvt_f32_ubyte0_e32 v2, s51
	v_rcp_iflag_f32_e32 v2, v2
	s_cselect_b64 s[18:19], -1, 0
	s_cmp_lg_u64 s[8:9], 0
	s_cselect_b64 s[20:21], -1, 0
	v_mul_f32_e32 v2, 0x4f7ffffe, v2
	v_cvt_u32_f32_e32 v2, v2
	v_or_b32_e32 v183, s26, v3
	s_sub_i32 s13, 0, s51
	v_mov_b32_e32 v3, v1
	v_readfirstlane_b32 s22, v2
	v_add_u32_e32 v2, v17, v15
	v_add_lshl_u32 v2, v2, v16, 1
	s_waitcnt vmcnt(6)
	s_mul_i32 s13, s13, s22
	v_lshl_add_u64 v[148:149], s[96:97], 0, v[2:3]
	v_add_u32_e32 v2, v20, v18
	s_mul_hi_u32 s13, s22, s13
	v_add_lshl_u32 v2, v2, v19, 1
	s_mov_b32 s55, 0
	v_mov_b32_e32 v146, v144
	v_mov_b32_e32 v147, v144
	v_or_b32_e32 v176, 16, v174
	v_or_b32_e32 v177, 32, v174
	v_or_b32_e32 v178, 48, v174
	v_add_u32_e32 v179, 0x80, v174
	v_add_u32_e32 v180, 0x90, v174
	v_add_u32_e32 v181, 0xa0, v174
	v_add_u32_e32 v182, 0xb0, v174
	s_add_i32 s56, s22, s13
	v_lshl_add_u64 v[150:151], s[96:97], 0, v[2:3]
	v_add_u32_e32 v184, 0, v5
	s_xor_b64 s[20:21], s[20:21], -1
	s_barrier
	s_branch .LBB0_205

.LBB0_217:
	s_add_i32 s41, s30, 2
	s_add_u32 vcc_lo, s28, 0x80
	s_addc_u32 s31, s29, 0
	s_add_i32 s62, 0, 0x10000
	s_cmp_eq_u32 s13, s30
	s_cselect_b32 s31, s25, s31
	s_cselect_b32 s30, s24, vcc_lo
	v_add_u32_e32 v145, s62, v175
	s_cselect_b32 vcc_hi, s27, s40
	s_cselect_b32 vcc_lo, s26, s23
	s_add_i32 s63, 0, 0x14000
	ds_read_b128 v[130:133], v145
	ds_read_b128 v[134:137], v145 offset:1024
	ds_read_b128 v[152:155], v145 offset:2048
	ds_read_b128 v[156:159], v145 offset:3072
	v_add_u32_e32 v145, s63, v175
	ds_read_b128 v[160:163], v145
	ds_read_b128 v[164:167], v145 offset:1024
	ds_read_b128 v[168:171], v145 offset:2048
	ds_read_b128 v[186:189], v145 offset:3072
	v_lshl_add_u64 v[172:173], s[28:29], 0, v[148:149]
	s_add_i32 m0, s93, 0xc000
	ds_read_b128 v[190:193], v184
	ds_read_b128 v[194:197], v184 offset:1024
	ds_read_b128 v[198:201], v184 offset:2048
	ds_read_b128 v[202:205], v184 offset:3072
	ds_read_b128 v[206:209], v184 offset:4096
	ds_read_b128 v[210:213], v184 offset:5120
	ds_read_b128 v[214:217], v184 offset:6144
	ds_read_b128 v[218:221], v184 offset:7168
	global_load_lds_dwordx4 v[172:173], off sc1
	v_lshl_add_u64 v[172:173], s[28:29], 0, v[150:151]
	s_add_i32 m0, s93, 0xe000
	s_nop 0
	global_load_lds_dwordx4 v[172:173], off sc1
	s_waitcnt vmcnt(8)
	s_waitcnt lgkmcnt(0)
	s_barrier
	s_setprio 1
	s_waitcnt lgkmcnt(0)
	v_mfma_f32_16x16x32_bf16 v[126:129], v[130:133], v[190:193], v[126:129]
	v_mfma_f32_16x16x32_bf16 v[122:125], v[152:155], v[190:193], v[122:125]
	v_mfma_f32_16x16x32_bf16 v[110:113], v[130:133], v[198:201], v[110:113]
	v_mfma_f32_16x16x32_bf16 v[106:109], v[152:155], v[198:201], v[106:109]
	v_mfma_f32_16x16x32_bf16 v[94:97], v[130:133], v[206:209], v[94:97]
	v_mfma_f32_16x16x32_bf16 v[90:93], v[152:155], v[206:209], v[90:93]
	v_mfma_f32_16x16x32_bf16 v[78:81], v[130:133], v[214:217], v[78:81]
	v_mfma_f32_16x16x32_bf16 v[74:77], v[152:155], v[214:217], v[74:77]
	v_mfma_f32_16x16x32_bf16 v[126:129], v[134:137], v[194:197], v[126:129]
	v_mfma_f32_16x16x32_bf16 v[122:125], v[156:159], v[194:197], v[122:125]
	v_mfma_f32_16x16x32_bf16 v[110:113], v[134:137], v[202:205], v[110:113]
	v_mfma_f32_16x16x32_bf16 v[106:109], v[156:159], v[202:205], v[106:109]
	v_mfma_f32_16x16x32_bf16 v[94:97], v[134:137], v[210:213], v[94:97]
	v_mfma_f32_16x16x32_bf16 v[90:93], v[156:159], v[210:213], v[90:93]
	v_mfma_f32_16x16x32_bf16 v[78:81], v[134:137], v[218:221], v[78:81]
	v_mfma_f32_16x16x32_bf16 v[74:77], v[156:159], v[218:221], v[74:77]
	s_setprio 0
	s_setprio 1
	v_mfma_f32_16x16x32_bf16 v[118:121], v[160:163], v[190:193], v[118:121]
	v_mfma_f32_16x16x32_bf16 v[114:117], v[168:171], v[190:193], v[114:117]
	v_mfma_f32_16x16x32_bf16 v[102:105], v[160:163], v[198:201], v[102:105]
	v_mfma_f32_16x16x32_bf16 v[98:101], v[168:171], v[198:201], v[98:101]
	v_mfma_f32_16x16x32_bf16 v[86:89], v[160:163], v[206:209], v[86:89]
	v_mfma_f32_16x16x32_bf16 v[82:85], v[168:171], v[206:209], v[82:85]
	v_mfma_f32_16x16x32_bf16 v[70:73], v[160:163], v[214:217], v[70:73]
	v_mfma_f32_16x16x32_bf16 v[66:69], v[168:171], v[214:217], v[66:69]
	v_mfma_f32_16x16x32_bf16 v[118:121], v[164:167], v[194:197], v[118:121]
	v_mfma_f32_16x16x32_bf16 v[114:117], v[186:189], v[194:197], v[114:117]
	v_mfma_f32_16x16x32_bf16 v[102:105], v[164:167], v[202:205], v[102:105]
	v_mfma_f32_16x16x32_bf16 v[98:101], v[186:189], v[202:205], v[98:101]
	v_mfma_f32_16x16x32_bf16 v[86:89], v[164:167], v[210:213], v[86:89]
	v_mfma_f32_16x16x32_bf16 v[82:85], v[186:189], v[210:213], v[82:85]
	v_mfma_f32_16x16x32_bf16 v[70:73], v[164:167], v[218:221], v[70:73]
	v_mfma_f32_16x16x32_bf16 v[66:69], v[186:189], v[218:221], v[66:69]
	s_setprio 0
	s_barrier
	s_add_i32 s62, s62, s49
	v_lshl_add_u64 v[172:173], vcc, 0, v[0:1]
	s_mov_b32 m0, s62
	ds_read_b128 v[190:193], v184 offset:16384
	ds_read_b128 v[194:197], v184 offset:17408
	ds_read_b128 v[198:201], v184 offset:18432
	ds_read_b128 v[202:205], v184 offset:19456
	ds_read_b128 v[206:209], v184 offset:20480
	ds_read_b128 v[210:213], v184 offset:21504
	ds_read_b128 v[214:217], v184 offset:22528
	ds_read_b128 v[218:221], v184 offset:23552
	global_load_lds_dwordx4 v[172:173], off sc1
	s_add_i32 m0, s62, 0x2000
	v_lshl_add_u64 v[222:223], vcc, 0, v[142:143]
	s_add_u32 vcc_lo, vcc_lo, s96
	s_addc_u32 vcc_hi, vcc_hi, 0
	s_add_i32 s62, s63, s49
	global_load_lds_dwordx4 v[222:223], off sc1
	v_lshl_add_u64 v[236:237], vcc, 0, v[0:1]
	s_mov_b32 m0, s62
	v_lshl_add_u64 v[238:239], vcc, 0, v[142:143]
	global_load_lds_dwordx4 v[236:237], off sc1
	s_add_i32 m0, s62, 0x2000
	v_lshl_add_u64 v[240:241], s[30:31], 0, v[138:139]
	global_load_lds_dwordx4 v[238:239], off sc1
	s_mov_b32 m0, s93
	v_lshl_add_u64 v[242:243], s[30:31], 0, v[140:141]
	global_load_lds_dwordx4 v[240:241], off sc1
	s_mov_b32 m0, s88
	s_nop 0
	global_load_lds_dwordx4 v[242:243], off sc1
	s_waitcnt vmcnt(8)
	s_waitcnt lgkmcnt(0)
	s_barrier
	s_setprio 1
	s_waitcnt lgkmcnt(0)
	v_mfma_f32_16x16x32_bf16 v[62:65], v[130:133], v[190:193], v[62:65]
	v_mfma_f32_16x16x32_bf16 v[58:61], v[152:155], v[190:193], v[58:61]
	v_mfma_f32_16x16x32_bf16 v[46:49], v[130:133], v[198:201], v[46:49]
	v_mfma_f32_16x16x32_bf16 v[42:45], v[152:155], v[198:201], v[42:45]
	v_mfma_f32_16x16x32_bf16 v[30:33], v[130:133], v[206:209], v[30:33]
	v_mfma_f32_16x16x32_bf16 v[26:29], v[152:155], v[206:209], v[26:29]
	v_mfma_f32_16x16x32_bf16 v[14:17], v[130:133], v[214:217], v[14:17]
	v_mfma_f32_16x16x32_bf16 v[10:13], v[152:155], v[214:217], v[10:13]
	v_mfma_f32_16x16x32_bf16 v[62:65], v[134:137], v[194:197], v[62:65]
	v_mfma_f32_16x16x32_bf16 v[58:61], v[156:159], v[194:197], v[58:61]
	v_mfma_f32_16x16x32_bf16 v[46:49], v[134:137], v[202:205], v[46:49]
	v_mfma_f32_16x16x32_bf16 v[42:45], v[156:159], v[202:205], v[42:45]
	v_mfma_f32_16x16x32_bf16 v[30:33], v[134:137], v[210:213], v[30:33]
	v_mfma_f32_16x16x32_bf16 v[26:29], v[156:159], v[210:213], v[26:29]
	v_mfma_f32_16x16x32_bf16 v[14:17], v[134:137], v[218:221], v[14:17]
	v_mfma_f32_16x16x32_bf16 v[10:13], v[156:159], v[218:221], v[10:13]
	s_setprio 0
	s_setprio 1
	v_mfma_f32_16x16x32_bf16 v[54:57], v[160:163], v[190:193], v[54:57]
	v_mfma_f32_16x16x32_bf16 v[50:53], v[168:171], v[190:193], v[50:53]
	v_mfma_f32_16x16x32_bf16 v[38:41], v[160:163], v[198:201], v[38:41]
	v_mfma_f32_16x16x32_bf16 v[34:37], v[168:171], v[198:201], v[34:37]
	v_mfma_f32_16x16x32_bf16 v[22:25], v[160:163], v[206:209], v[22:25]
	v_mfma_f32_16x16x32_bf16 v[18:21], v[168:171], v[206:209], v[18:21]
	v_mfma_f32_16x16x32_bf16 v[6:9], v[160:163], v[214:217], v[6:9]
	v_mfma_f32_16x16x32_bf16 v[2:5], v[168:171], v[214:217], v[2:5]
	v_mfma_f32_16x16x32_bf16 v[54:57], v[164:167], v[194:197], v[54:57]
	v_mfma_f32_16x16x32_bf16 v[50:53], v[186:189], v[194:197], v[50:53]
	v_mfma_f32_16x16x32_bf16 v[38:41], v[164:167], v[202:205], v[38:41]
	v_mfma_f32_16x16x32_bf16 v[34:37], v[186:189], v[202:205], v[34:37]
	v_mfma_f32_16x16x32_bf16 v[22:25], v[164:167], v[210:213], v[22:25]
	v_mfma_f32_16x16x32_bf16 v[18:21], v[186:189], v[210:213], v[18:21]
	v_mfma_f32_16x16x32_bf16 v[6:9], v[164:167], v[218:221], v[6:9]
	v_mfma_f32_16x16x32_bf16 v[2:5], v[186:189], v[218:221], v[2:5]
	s_setprio 0
	s_barrier
	s_add_i32 s62, 0, 0x18000
	v_add_u32_e32 v145, s62, v175
	s_add_i32 s63, 0, 0x1c000
	ds_read_b128 v[130:133], v145
	ds_read_b128 v[134:137], v145 offset:1024
	ds_read_b128 v[152:155], v145 offset:2048
	ds_read_b128 v[156:159], v145 offset:3072
	v_add_u32_e32 v145, s63, v175
	ds_read_b128 v[160:163], v145
	ds_read_b128 v[164:167], v145 offset:1024
	ds_read_b128 v[168:171], v145 offset:2048
	ds_read_b128 v[186:189], v145 offset:3072
	s_add_u32 s30, s30, s96
	s_addc_u32 s31, s31, 0
	s_mov_b32 m0, s89
	v_lshl_add_u64 v[244:245], s[30:31], 0, v[138:139]
	ds_read_b128 v[190:193], v184 offset:32768
	ds_read_b128 v[194:197], v184 offset:33792
	ds_read_b128 v[198:201], v184 offset:34816
	ds_read_b128 v[202:205], v184 offset:35840
	ds_read_b128 v[206:209], v184 offset:36864
	ds_read_b128 v[210:213], v184 offset:37888
	ds_read_b128 v[214:217], v184 offset:38912
	ds_read_b128 v[218:221], v184 offset:39936
	global_load_lds_dwordx4 v[244:245], off sc1
	v_lshl_add_u64 v[244:245], s[30:31], 0, v[140:141]
	s_mov_b32 m0, s52
	s_nop 0
	global_load_lds_dwordx4 v[244:245], off sc1
	s_waitcnt vmcnt(8)
	s_waitcnt lgkmcnt(0)
	s_barrier
	s_setprio 1
	s_waitcnt lgkmcnt(0)
	v_mfma_f32_16x16x32_bf16 v[126:129], v[130:133], v[190:193], v[126:129]
	v_mfma_f32_16x16x32_bf16 v[122:125], v[152:155], v[190:193], v[122:125]
	v_mfma_f32_16x16x32_bf16 v[110:113], v[130:133], v[198:201], v[110:113]
	v_mfma_f32_16x16x32_bf16 v[106:109], v[152:155], v[198:201], v[106:109]
	v_mfma_f32_16x16x32_bf16 v[94:97], v[130:133], v[206:209], v[94:97]
	v_mfma_f32_16x16x32_bf16 v[90:93], v[152:155], v[206:209], v[90:93]
	v_mfma_f32_16x16x32_bf16 v[78:81], v[130:133], v[214:217], v[78:81]
	v_mfma_f32_16x16x32_bf16 v[74:77], v[152:155], v[214:217], v[74:77]
	v_mfma_f32_16x16x32_bf16 v[126:129], v[134:137], v[194:197], v[126:129]
	v_mfma_f32_16x16x32_bf16 v[122:125], v[156:159], v[194:197], v[122:125]
	v_mfma_f32_16x16x32_bf16 v[110:113], v[134:137], v[202:205], v[110:113]
	v_mfma_f32_16x16x32_bf16 v[106:109], v[156:159], v[202:205], v[106:109]
	v_mfma_f32_16x16x32_bf16 v[94:97], v[134:137], v[210:213], v[94:97]
	v_mfma_f32_16x16x32_bf16 v[90:93], v[156:159], v[210:213], v[90:93]
	v_mfma_f32_16x16x32_bf16 v[78:81], v[134:137], v[218:221], v[78:81]
	v_mfma_f32_16x16x32_bf16 v[74:77], v[156:159], v[218:221], v[74:77]
	s_setprio 0
	s_setprio 1
	v_mfma_f32_16x16x32_bf16 v[118:121], v[160:163], v[190:193], v[118:121]
	v_mfma_f32_16x16x32_bf16 v[114:117], v[168:171], v[190:193], v[114:117]
	v_mfma_f32_16x16x32_bf16 v[102:105], v[160:163], v[198:201], v[102:105]
	v_mfma_f32_16x16x32_bf16 v[98:101], v[168:171], v[198:201], v[98:101]
	v_mfma_f32_16x16x32_bf16 v[86:89], v[160:163], v[206:209], v[86:89]
	v_mfma_f32_16x16x32_bf16 v[82:85], v[168:171], v[206:209], v[82:85]
	v_mfma_f32_16x16x32_bf16 v[70:73], v[160:163], v[214:217], v[70:73]
	v_mfma_f32_16x16x32_bf16 v[66:69], v[168:171], v[214:217], v[66:69]
	v_mfma_f32_16x16x32_bf16 v[118:121], v[164:167], v[194:197], v[118:121]
	v_mfma_f32_16x16x32_bf16 v[114:117], v[186:189], v[194:197], v[114:117]
	v_mfma_f32_16x16x32_bf16 v[102:105], v[164:167], v[202:205], v[102:105]
	v_mfma_f32_16x16x32_bf16 v[98:101], v[186:189], v[202:205], v[98:101]
	v_mfma_f32_16x16x32_bf16 v[86:89], v[164:167], v[210:213], v[86:89]
	v_mfma_f32_16x16x32_bf16 v[82:85], v[186:189], v[210:213], v[82:85]
	v_mfma_f32_16x16x32_bf16 v[70:73], v[164:167], v[218:221], v[70:73]
	v_mfma_f32_16x16x32_bf16 v[66:69], v[186:189], v[218:221], v[66:69]
	s_setprio 0
	s_barrier
	s_add_i32 s30, s62, s49
	v_lshl_add_u64 v[172:173], v[172:173], 0, s[98:99]
	s_mov_b32 m0, s30
	ds_read_b128 v[190:193], v184 offset:49152
	ds_read_b128 v[194:197], v184 offset:50176
	ds_read_b128 v[198:201], v184 offset:51200
	ds_read_b128 v[202:205], v184 offset:52224
	ds_read_b128 v[206:209], v184 offset:53248
	ds_read_b128 v[210:213], v184 offset:54272
	ds_read_b128 v[214:217], v184 offset:55296
	ds_read_b128 v[218:221], v184 offset:56320
	global_load_lds_dwordx4 v[172:173], off sc1
	v_lshl_add_u64 v[172:173], v[222:223], 0, s[98:99]
	s_add_i32 m0, s30, 0x2000
	s_add_i32 s30, s63, s49
	global_load_lds_dwordx4 v[172:173], off sc1
	v_lshl_add_u64 v[172:173], v[236:237], 0, s[98:99]
	s_mov_b32 m0, s30
	s_nop 0
	global_load_lds_dwordx4 v[172:173], off sc1
	v_lshl_add_u64 v[172:173], v[238:239], 0, s[98:99]
	s_add_i32 m0, s30, 0x2000
	s_nop 0
	global_load_lds_dwordx4 v[172:173], off sc1
	v_lshl_add_u64 v[172:173], v[240:241], 0, s[98:99]
	s_mov_b32 m0, s95
	s_nop 0
	global_load_lds_dwordx4 v[172:173], off sc1
	v_lshl_add_u64 v[172:173], v[242:243], 0, s[98:99]
	s_mov_b32 m0, s54
	s_nop 0
	global_load_lds_dwordx4 v[172:173], off sc1
	s_waitcnt vmcnt(8)
	s_waitcnt lgkmcnt(0)
	s_barrier
	s_setprio 1
	s_waitcnt lgkmcnt(0)
	v_mfma_f32_16x16x32_bf16 v[62:65], v[130:133], v[190:193], v[62:65]
	v_mfma_f32_16x16x32_bf16 v[58:61], v[152:155], v[190:193], v[58:61]
	v_mfma_f32_16x16x32_bf16 v[46:49], v[130:133], v[198:201], v[46:49]
	v_mfma_f32_16x16x32_bf16 v[42:45], v[152:155], v[198:201], v[42:45]
	v_mfma_f32_16x16x32_bf16 v[30:33], v[130:133], v[206:209], v[30:33]
	v_mfma_f32_16x16x32_bf16 v[26:29], v[152:155], v[206:209], v[26:29]
	v_mfma_f32_16x16x32_bf16 v[14:17], v[130:133], v[214:217], v[14:17]
	v_mfma_f32_16x16x32_bf16 v[10:13], v[152:155], v[214:217], v[10:13]
	v_mfma_f32_16x16x32_bf16 v[62:65], v[134:137], v[194:197], v[62:65]
	v_mfma_f32_16x16x32_bf16 v[58:61], v[156:159], v[194:197], v[58:61]
	v_mfma_f32_16x16x32_bf16 v[46:49], v[134:137], v[202:205], v[46:49]
	v_mfma_f32_16x16x32_bf16 v[42:45], v[156:159], v[202:205], v[42:45]
	v_mfma_f32_16x16x32_bf16 v[30:33], v[134:137], v[210:213], v[30:33]
	v_mfma_f32_16x16x32_bf16 v[26:29], v[156:159], v[210:213], v[26:29]
	v_mfma_f32_16x16x32_bf16 v[14:17], v[134:137], v[218:221], v[14:17]
	v_mfma_f32_16x16x32_bf16 v[10:13], v[156:159], v[218:221], v[10:13]
	s_setprio 0
	s_setprio 1
	v_mfma_f32_16x16x32_bf16 v[54:57], v[160:163], v[190:193], v[54:57]
	v_mfma_f32_16x16x32_bf16 v[50:53], v[168:171], v[190:193], v[50:53]
	v_mfma_f32_16x16x32_bf16 v[38:41], v[160:163], v[198:201], v[38:41]
	v_mfma_f32_16x16x32_bf16 v[34:37], v[168:171], v[198:201], v[34:37]
	v_mfma_f32_16x16x32_bf16 v[22:25], v[160:163], v[206:209], v[22:25]
	v_mfma_f32_16x16x32_bf16 v[18:21], v[168:171], v[206:209], v[18:21]
	v_mfma_f32_16x16x32_bf16 v[6:9], v[160:163], v[214:217], v[6:9]
	v_mfma_f32_16x16x32_bf16 v[2:5], v[168:171], v[214:217], v[2:5]
	v_mfma_f32_16x16x32_bf16 v[54:57], v[164:167], v[194:197], v[54:57]
	v_mfma_f32_16x16x32_bf16 v[50:53], v[186:189], v[194:197], v[50:53]
	v_mfma_f32_16x16x32_bf16 v[38:41], v[164:167], v[202:205], v[38:41]
	v_mfma_f32_16x16x32_bf16 v[34:37], v[186:189], v[202:205], v[34:37]
	v_mfma_f32_16x16x32_bf16 v[22:25], v[164:167], v[210:213], v[22:25]
	v_mfma_f32_16x16x32_bf16 v[18:21], v[186:189], v[210:213], v[18:21]
	v_mfma_f32_16x16x32_bf16 v[6:9], v[164:167], v[218:221], v[6:9]
	v_mfma_f32_16x16x32_bf16 v[2:5], v[186:189], v[218:221], v[2:5]
	s_setprio 0
	s_barrier
	s_add_u32 s28, s28, 0x100
	s_addc_u32 s29, s29, 0
	s_add_u32 s23, s23, 0x100
	s_addc_u32 s40, s40, 0
	s_cmp_ge_i32 s41, s61
	s_mov_b32 s30, s41
	s_cbranch_scc0 .LBB0_217
	s_and_b64 vcc, exec, s[18:19]
	s_cbranch_vccz .LBB0_220
	s_barrier
.LBB0_220:
	s_min_i32 s13, s43, 64
	s_ashr_i32 s13, s13, 4
	s_mul_hi_i32 s23, s13, 0x9000
	s_mul_i32 s13, s13, 0x9000
	s_add_u32 s28, s53, s13
	v_lshl_or_b32 v154, s58, 8, v183
	s_addc_u32 s29, s94, s23
	v_ashrrev_i32_e32 v155, 31, v154
	v_lshl_add_u64 v[162:163], v[154:155], 2, s[28:29]
	global_load_dwordx4 v[130:133], v[162:163], off offset:16 sc1
	global_load_dwordx4 v[134:137], v[162:163], off sc1
	v_mov_b32_e32 v145, v144
	s_cmp_gt_i32 s43, 63
	s_cselect_b64 s[30:31], -1, 0
	s_lshl_b32 s13, s43, 8
	s_cmp_lg_u32 s42, 0
	s_mov_b64 s[40:41], -1
	s_cselect_b64 s[28:29], -1, 0
	s_cmp_eq_u32 s42, 0
	s_waitcnt vmcnt(0)
	v_pk_mul_f32 v[156:157], v[144:145], v[132:133]
	v_pk_mul_f32 v[158:159], v[144:145], v[136:137]
	v_pk_mul_f32 v[160:161], v[146:147], v[134:135]
	v_pk_mul_f32 v[152:153], v[146:147], v[130:131]
	global_load_dwordx4 v[130:133], v[162:163], off offset:528 sc1
	global_load_dwordx4 v[134:137], v[162:163], off offset:512 sc1
	v_add_u32_e32 v162, s13, v174
	v_ashrrev_i32_e32 v163, 31, v162
	v_lshlrev_b64 v[162:163], 10, v[162:163]
	v_lshl_add_u64 v[162:163], v[162:163], 0, v[154:155]
	v_pk_mul_f32 v[168:169], v[128:129], v[158:159]
	v_pk_mul_f32 v[170:171], v[126:127], v[160:161]
	v_pk_mul_f32 v[164:165], v[124:125], v[156:157]
	v_pk_mul_f32 v[166:167], v[122:123], v[152:153]
	s_cbranch_scc1 .LBB0_222
	s_ashr_i32 s40, s12, 2
	s_ashr_i32 s41, s40, 31
	s_lshl_b64 s[40:41], s[40:41], 21
	s_add_u32 s40, s10, s40
	s_addc_u32 s41, s11, s41
	v_lshl_add_u64 v[126:127], v[162:163], 1, s[40:41]
	v_add_co_u32_e32 v126, vcc, 0xfe000000, v126
	v_cvt_pk_bf16_f32 v122, v170, v171
	v_cvt_pk_bf16_f32 v123, v168, v169
	v_cvt_pk_bf16_f32 v124, v166, v167
	v_cvt_pk_bf16_f32 v125, v164, v165
	v_addc_co_u32_e32 v127, vcc, -1, v127, vcc
	s_mov_b64 s[40:41], 0
	global_store_dwordx4 v[126:127], v[122:125], off sc1
.LBB0_222:
	s_andn2_b64 vcc, exec, s[40:41]
	s_or_b64 s[30:31], s[20:21], s[30:31]
	s_cbranch_vccnz .LBB0_228
	s_mov_b64 s[40:41], -1
	s_and_b64 vcc, exec, s[30:31]
	v_lshl_add_u64 v[172:173], v[162:163], 1, s[16:17]
	s_cbranch_vccz .LBB0_225
	global_load_dwordx4 v[126:129], v[172:173], off sc1
	s_mov_b64 s[40:41], 0
	s_waitcnt vmcnt(0)
	v_lshlrev_b32_e32 v122, 16, v126
	v_and_b32_e32 v123, 0xffff0000, v126
	v_lshlrev_b32_e32 v124, 16, v127
	v_and_b32_e32 v125, 0xffff0000, v127
	v_lshlrev_b32_e32 v126, 16, v128
	v_and_b32_e32 v127, 0xffff0000, v128
	v_lshlrev_b32_e32 v128, 16, v129
	v_and_b32_e32 v129, 0xffff0000, v129

.LBB0_231:
	v_or_b32_e32 v114, 0x80, v162
	v_mov_b32_e32 v115, v163
	s_mov_b64 s[28:29], -1
	s_and_b64 vcc, exec, s[40:41]
	v_lshl_add_u64 v[164:165], v[114:115], 1, s[16:17]
	s_cbranch_vccnz .LBB0_233
	global_load_dwordx4 v[118:121], v[164:165], off sc1
	s_mov_b64 s[28:29], 0
	s_waitcnt vmcnt(0)
	v_lshlrev_b32_e32 v114, 16, v118
	v_and_b32_e32 v115, 0xffff0000, v118
	v_lshlrev_b32_e32 v116, 16, v119
	v_and_b32_e32 v117, 0xffff0000, v119
	v_lshlrev_b32_e32 v118, 16, v120
	v_and_b32_e32 v119, 0xffff0000, v120
	v_lshlrev_b32_e32 v120, 16, v121
	v_and_b32_e32 v121, 0xffff0000, v121

.LBB0_238:
.LBB0_239:
	s_mov_b64 s[28:29], -1
	s_and_b64 vcc, exec, s[40:41]
	v_lshl_add_u64 v[132:133], v[114:115], 1, s[16:17]
	s_cbranch_vccnz .LBB0_241
	global_load_dwordx4 v[110:113], v[132:133], off sc1
	s_mov_b64 s[28:29], 0
	s_waitcnt vmcnt(0)
	v_lshlrev_b32_e32 v106, 16, v110
	v_and_b32_e32 v107, 0xffff0000, v110
	v_lshlrev_b32_e32 v108, 16, v111
	v_and_b32_e32 v109, 0xffff0000, v111
	v_lshlrev_b32_e32 v110, 16, v112
	v_and_b32_e32 v111, 0xffff0000, v112
	v_lshlrev_b32_e32 v112, 16, v113
	v_and_b32_e32 v113, 0xffff0000, v113

.LBB0_246:
.LBB0_247:
	v_or_b32_e32 v98, 0x80, v114
	v_mov_b32_e32 v99, v115
	s_mov_b64 s[28:29], -1
	s_and_b64 vcc, exec, s[40:41]
	v_lshl_add_u64 v[116:117], v[98:99], 1, s[16:17]
	s_cbranch_vccnz .LBB0_249
	global_load_dwordx4 v[102:105], v[116:117], off sc1
	s_mov_b64 s[28:29], 0
	s_waitcnt vmcnt(0)
	v_lshlrev_b32_e32 v98, 16, v102
	v_and_b32_e32 v99, 0xffff0000, v102
	v_lshlrev_b32_e32 v100, 16, v103
	v_and_b32_e32 v101, 0xffff0000, v103
	v_lshlrev_b32_e32 v102, 16, v104
	v_and_b32_e32 v103, 0xffff0000, v104
	v_lshlrev_b32_e32 v104, 16, v105
	v_and_b32_e32 v105, 0xffff0000, v105

.LBB0_254:
.LBB0_255:
	s_mov_b64 s[28:29], -1
	s_and_b64 vcc, exec, s[40:41]
	v_lshl_add_u64 v[108:109], v[98:99], 1, s[16:17]
	s_cbranch_vccnz .LBB0_257
	global_load_dwordx4 v[94:97], v[108:109], off sc1
	s_mov_b64 s[28:29], 0
	s_waitcnt vmcnt(0)
	v_lshlrev_b32_e32 v90, 16, v94
	v_and_b32_e32 v91, 0xffff0000, v94
	v_lshlrev_b32_e32 v92, 16, v95
	v_and_b32_e32 v93, 0xffff0000, v95
	v_lshlrev_b32_e32 v94, 16, v96
	v_and_b32_e32 v95, 0xffff0000, v96
	v_lshlrev_b32_e32 v96, 16, v97
	v_and_b32_e32 v97, 0xffff0000, v97

.LBB0_262:
.LBB0_263:
	v_or_b32_e32 v82, 0x80, v98
	v_mov_b32_e32 v83, v99
	s_mov_b64 s[28:29], -1
	s_and_b64 vcc, exec, s[40:41]
	v_lshl_add_u64 v[100:101], v[82:83], 1, s[16:17]
	s_cbranch_vccnz .LBB0_265
	global_load_dwordx4 v[86:89], v[100:101], off sc1
	s_mov_b64 s[28:29], 0
	s_waitcnt vmcnt(0)
	v_lshlrev_b32_e32 v82, 16, v86
	v_and_b32_e32 v83, 0xffff0000, v86
	v_lshlrev_b32_e32 v84, 16, v87
	v_and_b32_e32 v85, 0xffff0000, v87
	v_lshlrev_b32_e32 v86, 16, v88
	v_and_b32_e32 v87, 0xffff0000, v88
	v_lshlrev_b32_e32 v88, 16, v89
	v_and_b32_e32 v89, 0xffff0000, v89

.LBB0_270:
.LBB0_271:
	s_mov_b64 s[28:29], -1
	s_and_b64 vcc, exec, s[40:41]
	v_lshl_add_u64 v[92:93], v[82:83], 1, s[16:17]
	s_cbranch_vccnz .LBB0_273
	global_load_dwordx4 v[78:81], v[92:93], off sc1
	s_mov_b64 s[28:29], 0
	s_waitcnt vmcnt(0)
	v_lshlrev_b32_e32 v74, 16, v78
	v_and_b32_e32 v75, 0xffff0000, v78
	v_lshlrev_b32_e32 v76, 16, v79
	v_and_b32_e32 v77, 0xffff0000, v79
	v_lshlrev_b32_e32 v78, 16, v80
	v_and_b32_e32 v79, 0xffff0000, v80
	v_lshlrev_b32_e32 v80, 16, v81
	v_and_b32_e32 v81, 0xffff0000, v81

.LBB0_278:
.LBB0_279:
	v_or_b32_e32 v66, 0x80, v82
	v_mov_b32_e32 v67, v83
	s_mov_b64 s[28:29], -1
	s_and_b64 vcc, exec, s[40:41]
	v_lshl_add_u64 v[84:85], v[66:67], 1, s[16:17]
	s_cbranch_vccnz .LBB0_281
	global_load_dwordx4 v[70:73], v[84:85], off sc1
	s_mov_b64 s[28:29], 0
	s_waitcnt vmcnt(0)
	v_lshlrev_b32_e32 v66, 16, v70
	v_and_b32_e32 v67, 0xffff0000, v70
	v_lshlrev_b32_e32 v68, 16, v71
	v_and_b32_e32 v69, 0xffff0000, v71
	v_lshlrev_b32_e32 v70, 16, v72
	v_and_b32_e32 v71, 0xffff0000, v72
	v_lshlrev_b32_e32 v72, 16, v73
	v_and_b32_e32 v73, 0xffff0000, v73

.LBB0_286:
.LBB0_287:
	s_mov_b64 s[28:29], -1
	s_and_b64 vcc, exec, s[40:41]
	v_lshl_add_u64 v[76:77], v[66:67], 1, s[16:17]
	s_cbranch_vccnz .LBB0_289
	global_load_dwordx4 v[62:65], v[76:77], off sc1
	s_mov_b64 s[28:29], 0
	s_waitcnt vmcnt(0)
	v_lshlrev_b32_e32 v58, 16, v62
	v_and_b32_e32 v59, 0xffff0000, v62
	v_lshlrev_b32_e32 v60, 16, v63
	v_and_b32_e32 v61, 0xffff0000, v63
	v_lshlrev_b32_e32 v62, 16, v64
	v_and_b32_e32 v63, 0xffff0000, v64
	v_lshlrev_b32_e32 v64, 16, v65
	v_and_b32_e32 v65, 0xffff0000, v65

.LBB0_294:
.LBB0_295:
	v_or_b32_e32 v50, 0x80, v66
	v_mov_b32_e32 v51, v67
	s_mov_b64 s[28:29], -1
	s_and_b64 vcc, exec, s[40:41]
	v_lshl_add_u64 v[68:69], v[50:51], 1, s[16:17]
	s_cbranch_vccnz .LBB0_297
	global_load_dwordx4 v[54:57], v[68:69], off sc1
	s_mov_b64 s[28:29], 0
	s_waitcnt vmcnt(0)
	v_lshlrev_b32_e32 v50, 16, v54
	v_and_b32_e32 v51, 0xffff0000, v54
	v_lshlrev_b32_e32 v52, 16, v55
	v_and_b32_e32 v53, 0xffff0000, v55
	v_lshlrev_b32_e32 v54, 16, v56
	v_and_b32_e32 v55, 0xffff0000, v56
	v_lshlrev_b32_e32 v56, 16, v57
	v_and_b32_e32 v57, 0xffff0000, v57

.LBB0_302:
.LBB0_303:
	s_mov_b64 s[28:29], -1
	s_and_b64 vcc, exec, s[40:41]
	v_lshl_add_u64 v[60:61], v[50:51], 1, s[16:17]
	s_cbranch_vccnz .LBB0_305
	global_load_dwordx4 v[46:49], v[60:61], off sc1
	s_mov_b64 s[28:29], 0
	s_waitcnt vmcnt(0)
	v_lshlrev_b32_e32 v42, 16, v46
	v_and_b32_e32 v43, 0xffff0000, v46
	v_lshlrev_b32_e32 v44, 16, v47
	v_and_b32_e32 v45, 0xffff0000, v47
	v_lshlrev_b32_e32 v46, 16, v48
	v_and_b32_e32 v47, 0xffff0000, v48
	v_lshlrev_b32_e32 v48, 16, v49
	v_and_b32_e32 v49, 0xffff0000, v49

.LBB0_310:
.LBB0_311:
	v_or_b32_e32 v34, 0x80, v50
	v_mov_b32_e32 v35, v51
	s_mov_b64 s[28:29], -1
	s_and_b64 vcc, exec, s[40:41]
	v_lshl_add_u64 v[52:53], v[34:35], 1, s[16:17]
	s_cbranch_vccnz .LBB0_313
	global_load_dwordx4 v[38:41], v[52:53], off sc1
	s_mov_b64 s[28:29], 0
	s_waitcnt vmcnt(0)
	v_lshlrev_b32_e32 v34, 16, v38
	v_and_b32_e32 v35, 0xffff0000, v38
	v_lshlrev_b32_e32 v36, 16, v39
	v_and_b32_e32 v37, 0xffff0000, v39
	v_lshlrev_b32_e32 v38, 16, v40
	v_and_b32_e32 v39, 0xffff0000, v40
	v_lshlrev_b32_e32 v40, 16, v41
	v_and_b32_e32 v41, 0xffff0000, v41

.LBB0_318:
.LBB0_319:
	s_mov_b64 s[28:29], -1
	s_and_b64 vcc, exec, s[40:41]
	v_lshl_add_u64 v[44:45], v[34:35], 1, s[16:17]
	s_cbranch_vccnz .LBB0_321
	global_load_dwordx4 v[30:33], v[44:45], off sc1
	s_mov_b64 s[28:29], 0
	s_waitcnt vmcnt(0)
	v_lshlrev_b32_e32 v26, 16, v30
	v_and_b32_e32 v27, 0xffff0000, v30
	v_lshlrev_b32_e32 v28, 16, v31
	v_and_b32_e32 v29, 0xffff0000, v31
	v_lshlrev_b32_e32 v30, 16, v32
	v_and_b32_e32 v31, 0xffff0000, v32
	v_lshlrev_b32_e32 v32, 16, v33
	v_and_b32_e32 v33, 0xffff0000, v33

.LBB0_326:
.LBB0_327:
	v_or_b32_e32 v18, 0x80, v34
	v_mov_b32_e32 v19, v35
	s_mov_b64 s[28:29], -1
	s_and_b64 vcc, exec, s[40:41]
	v_lshl_add_u64 v[36:37], v[18:19], 1, s[16:17]
	s_cbranch_vccnz .LBB0_329
	global_load_dwordx4 v[22:25], v[36:37], off sc1
	s_mov_b64 s[28:29], 0
	s_waitcnt vmcnt(0)
	v_lshlrev_b32_e32 v18, 16, v22
	v_and_b32_e32 v19, 0xffff0000, v22
	v_lshlrev_b32_e32 v20, 16, v23
	v_and_b32_e32 v21, 0xffff0000, v23
	v_lshlrev_b32_e32 v22, 16, v24
	v_and_b32_e32 v23, 0xffff0000, v24
	v_lshlrev_b32_e32 v24, 16, v25
	v_and_b32_e32 v25, 0xffff0000, v25

.LBB0_334:
.LBB0_335:
	s_mov_b64 s[28:29], -1
	s_and_b64 vcc, exec, s[40:41]
	v_lshl_add_u64 v[28:29], v[18:19], 1, s[16:17]
	s_cbranch_vccnz .LBB0_337
	global_load_dwordx4 v[14:17], v[28:29], off sc1
	s_mov_b64 s[28:29], 0
	s_waitcnt vmcnt(0)
	v_lshlrev_b32_e32 v10, 16, v14
	v_and_b32_e32 v11, 0xffff0000, v14
	v_lshlrev_b32_e32 v12, 16, v15
	v_and_b32_e32 v13, 0xffff0000, v15
	v_lshlrev_b32_e32 v14, 16, v16
	v_and_b32_e32 v15, 0xffff0000, v16
	v_lshlrev_b32_e32 v16, 16, v17
	v_and_b32_e32 v17, 0xffff0000, v17

.LBB0_342:
	s_nop 0
	v_or_b32_e32 v2, 0x80, v18
	v_mov_b32_e32 v3, v19
	s_mov_b64 s[12:13], -1
	s_and_b64 vcc, exec, s[40:41]
	v_lshl_add_u64 v[20:21], v[2:3], 1, s[16:17]
	s_cbranch_vccnz .LBB0_344
	global_load_dwordx4 v[6:9], v[20:21], off sc1
	s_mov_b64 s[12:13], 0
	s_waitcnt vmcnt(0)
	v_lshlrev_b32_e32 v2, 16, v6
	v_and_b32_e32 v3, 0xffff0000, v6
	v_lshlrev_b32_e32 v4, 16, v7
	v_and_b32_e32 v5, 0xffff0000, v7
	v_lshlrev_b32_e32 v6, 16, v8
	v_and_b32_e32 v7, 0xffff0000, v8
	v_lshlrev_b32_e32 v8, 16, v9
	v_and_b32_e32 v9, 0xffff0000, v9

.LBB0_363:
	v_ashrrev_i32_e32 v0, 31, v10
	v_lshrrev_b32_e32 v0, 26, v0
	v_add_u32_e32 v0, v10, v0
	v_ashrrev_i32_e32 v11, 6, v0
	v_bfe_i32 v0, v10, 27, 1
	v_lshlrev_b32_e32 v2, 4, v10
	v_lshrrev_b32_e32 v0, 22, v0
	v_add_u32_e32 v0, v2, v0
	v_and_b32_e32 v0, 0xfffffc00, v0
	v_sub_u32_e32 v0, v2, v0
	s_and_b64 s[4:5], s[28:29], exec
	v_lshrrev_b32_e32 v3, 4, v0
	s_cselect_b32 s4, 0x2580000, 0
	s_cmp_eq_u32 s50, 1
	v_bitop3_b32 v0, v3, v0, 32 bitop3:0x6c
	s_cselect_b32 s5, 0, 0x1500000
	s_waitcnt lgkmcnt(0)
	s_add_u32 s4, s6, s4
	v_ashrrev_i32_e32 v4, 31, v0
	s_addc_u32 s13, s7, 0
	v_lshrrev_b32_e32 v4, 26, v4
	s_add_u32 s37, s6, 0x9000000
	v_add_u32_e32 v4, v0, v4
	s_addc_u32 s40, s7, 0
	v_lshlrev_b32_e32 v3, 3, v11
	v_ashrrev_i32_e32 v12, 6, v4
	v_and_b32_e32 v4, 0xc0, v4
	s_add_u32 s4, s4, s5
	v_and_b32_e32 v3, -16, v3
	v_sub_u32_e32 v0, v0, v4
	s_addc_u32 s5, s13, 0
	v_add_u32_e32 v3, v12, v3
	v_ashrrev_i16_sdwa v0, v230, sext(v0) dst_sel:DWORD dst_unused:UNUSED_PAD src0_sel:DWORD src1_sel:BYTE_0
	s_add_u32 s41, s4, 0x100000
	v_lshlrev_b32_e32 v5, 5, v11
	v_bfe_i32 v13, v0, 0, 16
	v_lshlrev_b32_e32 v0, 1, v3
	v_lshrrev_b32_e32 v4, 2, v3
	v_and_b32_e32 v6, 3, v12
	s_mov_b32 s4, 0x1fffe0
	v_and_b32_e32 v5, 32, v5
	v_and_b32_e32 v0, 24, v0
	v_and_b32_e32 v4, 4, v4
	v_and_or_b32 v6, v3, s4, v6
	v_or3_b32 v0, v6, v4, v0
	v_add_lshl_u32 v4, v5, v13, 1
	v_add_u32_e32 v2, 0x2000, v2
	v_lshl_add_u32 v130, v3, 11, v4
	v_ashrrev_i32_e32 v3, 31, v2
	v_lshrrev_b32_e32 v3, 22, v3
	v_add_u32_e32 v3, v2, v3
	v_ashrrev_i32_e32 v14, 10, v3
	v_mul_i32_i24_e32 v3, 0x400, v14
	v_sub_u32_e32 v2, v2, v3
	v_lshrrev_b32_e32 v3, 4, v2
	v_bitop3_b32 v2, v3, v2, 32 bitop3:0x6c
	v_lshl_add_u32 v0, v0, 11, v4
	v_ashrrev_i32_e32 v4, 31, v2
	v_lshrrev_b32_e32 v4, 26, v4
	v_lshlrev_b32_e32 v3, 3, v14
	v_add_u32_e32 v4, v2, v4
	v_and_b32_e32 v3, -16, v3
	v_ashrrev_i32_e32 v15, 6, v4
	s_addc_u32 s42, s5, 0
	v_add_u32_e32 v3, v15, v3
	v_and_b32_e32 v6, 3, v15
	s_ashr_i32 s14, s12, 6
	s_ashr_i32 s27, s26, 31
	s_ashr_i32 s13, s12, 8
	v_and_or_b32 v6, v3, s4, v6
	s_lshl_b32 s43, s14, 10
	s_lshl_b64 s[4:5], s[26:27], 19
	s_mov_b64 s[62:63], s[28:29]
	s_add_u32 s28, s37, s4
	v_and_b32_e32 v4, 0xc0, v4
	s_addc_u32 s29, s40, s5
	s_ashr_i32 s25, s24, 31
	v_sub_u32_e32 v2, v2, v4
	s_lshl_b64 s[4:5], s[24:25], 19
	v_ashrrev_i16_sdwa v2, v230, sext(v2) dst_sel:DWORD dst_unused:UNUSED_PAD src0_sel:DWORD src1_sel:BYTE_0
	s_add_u32 s30, s41, s4
	v_lshlrev_b32_e32 v5, 5, v14
	v_bfe_i32 v16, v2, 0, 16
	v_lshlrev_b32_e32 v2, 1, v3
	v_lshrrev_b32_e32 v4, 2, v3
	s_addc_u32 s31, s42, s5
	s_add_i32 s27, s43, 0
	v_and_b32_e32 v5, 32, v5
	v_and_b32_e32 v2, 24, v2
	v_and_b32_e32 v4, 4, v4
	s_add_i32 m0, s27, 0x10000
	v_or3_b32 v2, v6, v4, v2
	v_add_lshl_u32 v4, v5, v16, 1
	global_load_lds_dwordx4 v0, s[30:31] sc1
	s_add_i32 m0, s27, 0x12000
	v_lshl_add_u32 v134, v2, 11, v4
	s_add_u32 s4, s30, 0x40000
	global_load_lds_dwordx4 v134, s[30:31] sc1
	s_addc_u32 s5, s31, 0
	s_add_i32 m0, s27, 0x14000
	s_add_i32 s44, s27, 0x2000
	global_load_lds_dwordx4 v0, s[4:5] sc1
	s_add_i32 m0, s27, 0x16000
	v_lshl_add_u32 v132, v3, 11, v4
	global_load_lds_dwordx4 v134, s[4:5] sc1
	s_mov_b32 m0, s27
	s_add_u32 s4, s28, 0x40000
	global_load_lds_dwordx4 v130, s[28:29] sc1
	s_mov_b32 m0, s44
	s_addc_u32 s5, s29, 0
	s_add_i32 s45, s27, 0x4000
	global_load_lds_dwordx4 v132, s[28:29] sc1
	s_mov_b32 m0, s45
	s_add_i32 s47, s27, 0x6000
	global_load_lds_dwordx4 v130, s[4:5] sc1
	s_mov_b32 m0, s47
	v_mov_b32_e32 v135, v1
	global_load_lds_dwordx4 v132, s[4:5] sc1
	v_mov_b32_e32 v131, v1
	v_mov_b32_e32 v133, v1
	s_cmp_eq_u32 s13, 1
	v_lshl_add_u64 v[8:9], s[30:31], 0, v[0:1]
	v_lshl_add_u64 v[6:7], s[30:31], 0, v[134:135]
	v_lshl_add_u64 v[2:3], s[28:29], 0, v[130:131]
	s_cselect_b64 s[4:5], -1, 0
	s_cmp_lg_u32 s13, 1
	v_lshl_add_u64 v[4:5], s[28:29], 0, v[132:133]
	s_cbranch_scc1 .LBB0_365
	s_barrier
.LBB0_365:
	s_add_u32 s6, s6, 0xb200000
	s_addc_u32 s7, s7, 0
	s_lshl_b32 s14, s14, 5
	s_and_b32 s17, s14, 0x60
	s_add_i32 m0, s27, 0x18000
	v_lshl_add_u64 v[8:9], v[8:9], 0, s[98:99]
	s_lshl_b32 s16, s13, 13
	s_lshl_b32 s18, s17, 7
	s_waitcnt vmcnt(2)
	s_barrier
	global_load_lds_dwordx4 v[8:9], off sc1
	v_lshl_add_u64 v[6:7], v[6:7], 0, s[98:99]
	s_add_i32 m0, s27, 0x1a000
	s_add_i32 s49, s27, 0x8000
	s_add_i32 s51, s27, 0xa000
	global_load_lds_dwordx4 v[6:7], off sc1
	v_lshl_add_u64 v[2:3], v[2:3], 0, s[98:99]
	s_mov_b32 m0, s49
	s_add_u32 s14, s30, 0x40080
	global_load_lds_dwordx4 v[2:3], off sc1
	v_lshl_add_u64 v[2:3], v[4:5], 0, s[98:99]
	s_mov_b32 m0, s51
	s_addc_u32 s15, s31, 0
	global_load_lds_dwordx4 v[2:3], off sc1
	s_add_i32 m0, s27, 0x1c000
	v_lshl_add_u64 v[2:3], s[14:15], 0, v[0:1]
	global_load_lds_dwordx4 v[2:3], off sc1
	v_lshl_add_u64 v[2:3], s[14:15], 0, v[134:135]
	s_add_i32 m0, s27, 0x1e000
	s_cmpk_lt_u32 s12, 0x100
	global_load_lds_dwordx4 v[2:3], off sc1
	v_lshrrev_b32_e32 v3, 1, v10
	v_and_b32_e32 v3, 24, v3
	v_and_b32_e32 v2, 15, v10
	v_lshlrev_b32_e32 v4, 1, v3
	v_lshl_or_b32 v144, s13, 6, v2
	v_lshl_or_b32 v2, v2, 6, v4
	v_lshlrev_b32_e32 v4, 2, v10
	v_and_b32_e32 v4, 32, v4
	v_bitop3_b32 v5, v2, s16, v4 bitop3:0xde
	v_bitop3_b32 v145, v2, s18, v4 bitop3:0xde
	v_lshlrev_b32_e32 v2, 14, v11
	v_and_b32_e32 v2, 0xffff8000, v2
	v_or_b32_e32 v146, s17, v3
	v_lshl_add_u32 v2, v12, 11, v2
	v_and_b32_e32 v3, 1, v11
	v_lshl_or_b32 v2, v3, 6, v2
	v_lshl_add_u32 v136, v13, 1, v2
	v_lshlrev_b32_e32 v2, 14, v14
	v_and_b32_e32 v2, 0xffff8000, v2
	s_waitcnt vmcnt(6)
	v_lshl_add_u32 v2, v15, 11, v2
	v_and_b32_e32 v3, 1, v14
	v_lshl_or_b32 v2, v3, 6, v2
	s_cselect_b64 s[12:13], -1, 0
	v_mov_b32_e32 v137, v1
	v_lshl_add_u32 v138, v16, 1, v2
	v_mov_b32_e32 v139, v1
	s_mov_b32 s52, 0
	v_add_u32_e32 v147, 0, v5
	s_barrier
	s_branch .LBB0_368

.LBB0_374:
	s_add_u32 s30, s28, 0xfffc0080
	s_addc_u32 s31, s29, -1
	s_add_i32 s57, 0, 0x10000
	s_cmp_eq_u32 s56, 12
	s_cselect_b32 s39, s17, s31
	s_cselect_b32 s38, s25, s30
	s_cselect_b32 s31, s15, s55
	s_cselect_b32 s30, s53, s54
	s_add_i32 s60, 0, 0x14000
	v_add_u32_e32 v156, s57, v145
	v_add_u32_e32 v172, s60, v145
	ds_read_b128 v[140:143], v156
	ds_read_b128 v[148:151], v156 offset:1024
	ds_read_b128 v[152:155], v156 offset:2048
	ds_read_b128 v[156:159], v156 offset:3072
	ds_read_b128 v[160:163], v172
	ds_read_b128 v[164:167], v172 offset:1024
	ds_read_b128 v[168:171], v172 offset:2048
	ds_read_b128 v[172:175], v172 offset:3072
	v_lshl_add_u64 v[208:209], s[28:29], 0, v[136:137]
	s_add_i32 m0, s27, 0xc000
	ds_read_b128 v[176:179], v147
	ds_read_b128 v[180:183], v147 offset:1024
	ds_read_b128 v[184:187], v147 offset:2048
	ds_read_b128 v[188:191], v147 offset:3072
	ds_read_b128 v[192:195], v147 offset:4096
	ds_read_b128 v[196:199], v147 offset:5120
	ds_read_b128 v[200:203], v147 offset:6144
	ds_read_b128 v[204:207], v147 offset:7168
	global_load_lds_dwordx4 v[208:209], off sc1
	v_lshl_add_u64 v[208:209], s[28:29], 0, v[138:139]
	s_add_i32 m0, s27, 0xe000
	s_nop 0
	global_load_lds_dwordx4 v[208:209], off sc1
	s_waitcnt vmcnt(8)
	s_waitcnt lgkmcnt(0)
	s_barrier
	s_setprio 1
	s_waitcnt lgkmcnt(0)
	v_mfma_f32_16x16x32_bf16 v[122:125], v[140:143], v[176:179], v[122:125]
	v_mfma_f32_16x16x32_bf16 v[114:117], v[152:155], v[176:179], v[114:117]
	v_mfma_f32_16x16x32_bf16 v[106:109], v[140:143], v[184:187], v[106:109]
	v_mfma_f32_16x16x32_bf16 v[98:101], v[152:155], v[184:187], v[98:101]
	v_mfma_f32_16x16x32_bf16 v[90:93], v[140:143], v[192:195], v[90:93]
	v_mfma_f32_16x16x32_bf16 v[82:85], v[152:155], v[192:195], v[82:85]
	v_mfma_f32_16x16x32_bf16 v[74:77], v[140:143], v[200:203], v[74:77]
	v_mfma_f32_16x16x32_bf16 v[66:69], v[152:155], v[200:203], v[66:69]
	v_mfma_f32_16x16x32_bf16 v[122:125], v[148:151], v[180:183], v[122:125]
	v_mfma_f32_16x16x32_bf16 v[114:117], v[156:159], v[180:183], v[114:117]
	v_mfma_f32_16x16x32_bf16 v[106:109], v[148:151], v[188:191], v[106:109]
	v_mfma_f32_16x16x32_bf16 v[98:101], v[156:159], v[188:191], v[98:101]
	v_mfma_f32_16x16x32_bf16 v[90:93], v[148:151], v[196:199], v[90:93]
	v_mfma_f32_16x16x32_bf16 v[82:85], v[156:159], v[196:199], v[82:85]
	v_mfma_f32_16x16x32_bf16 v[74:77], v[148:151], v[204:207], v[74:77]
	v_mfma_f32_16x16x32_bf16 v[66:69], v[156:159], v[204:207], v[66:69]
	s_setprio 0
	s_setprio 1
	v_mfma_f32_16x16x32_bf16 v[126:129], v[160:163], v[176:179], v[126:129]
	v_mfma_f32_16x16x32_bf16 v[118:121], v[168:171], v[176:179], v[118:121]
	v_mfma_f32_16x16x32_bf16 v[110:113], v[160:163], v[184:187], v[110:113]
	v_mfma_f32_16x16x32_bf16 v[102:105], v[168:171], v[184:187], v[102:105]
	v_mfma_f32_16x16x32_bf16 v[94:97], v[160:163], v[192:195], v[94:97]
	v_mfma_f32_16x16x32_bf16 v[86:89], v[168:171], v[192:195], v[86:89]
	v_mfma_f32_16x16x32_bf16 v[78:81], v[160:163], v[200:203], v[78:81]
	v_mfma_f32_16x16x32_bf16 v[70:73], v[168:171], v[200:203], v[70:73]
	v_mfma_f32_16x16x32_bf16 v[126:129], v[164:167], v[180:183], v[126:129]
	v_mfma_f32_16x16x32_bf16 v[118:121], v[172:175], v[180:183], v[118:121]
	v_mfma_f32_16x16x32_bf16 v[110:113], v[164:167], v[188:191], v[110:113]
	v_mfma_f32_16x16x32_bf16 v[102:105], v[172:175], v[188:191], v[102:105]
	v_mfma_f32_16x16x32_bf16 v[94:97], v[164:167], v[196:199], v[94:97]
	v_mfma_f32_16x16x32_bf16 v[86:89], v[172:175], v[196:199], v[86:89]
	v_mfma_f32_16x16x32_bf16 v[78:81], v[164:167], v[204:207], v[78:81]
	v_mfma_f32_16x16x32_bf16 v[70:73], v[172:175], v[204:207], v[70:73]
	s_setprio 0
	s_barrier
	s_add_i32 s57, s57, s43
	v_lshl_add_u64 v[208:209], s[30:31], 0, v[0:1]
	s_mov_b32 m0, s57
	ds_read_b128 v[176:179], v147 offset:16384
	ds_read_b128 v[180:183], v147 offset:17408
	ds_read_b128 v[184:187], v147 offset:18432
	ds_read_b128 v[188:191], v147 offset:19456
	ds_read_b128 v[192:195], v147 offset:20480
	ds_read_b128 v[196:199], v147 offset:21504
	ds_read_b128 v[200:203], v147 offset:22528
	ds_read_b128 v[204:207], v147 offset:23552
	global_load_lds_dwordx4 v[208:209], off sc1
	s_add_i32 m0, s57, 0x2000
	s_add_u32 s58, s30, 0x40000
	v_lshl_add_u64 v[210:211], s[30:31], 0, v[134:135]
	s_addc_u32 s59, s31, 0
	s_add_i32 s57, s60, s43
	global_load_lds_dwordx4 v[210:211], off sc1
	v_lshl_add_u64 v[212:213], s[58:59], 0, v[0:1]
	s_mov_b32 m0, s57
	v_lshl_add_u64 v[214:215], s[38:39], 0, v[132:133]
	global_load_lds_dwordx4 v[212:213], off sc1
	v_lshl_add_u64 v[212:213], s[58:59], 0, v[134:135]
	s_add_i32 m0, s57, 0x2000
	s_nop 0
	global_load_lds_dwordx4 v[212:213], off sc1
	v_lshl_add_u64 v[212:213], s[38:39], 0, v[130:131]
	s_mov_b32 m0, s27
	s_nop 0
	global_load_lds_dwordx4 v[212:213], off sc1
	s_mov_b32 m0, s44
	s_nop 0
	global_load_lds_dwordx4 v[214:215], off sc1
	s_waitcnt vmcnt(8)
	s_waitcnt lgkmcnt(0)
	s_barrier
	s_setprio 1
	s_waitcnt lgkmcnt(0)
	v_mfma_f32_16x16x32_bf16 v[58:61], v[140:143], v[176:179], v[58:61]
	v_mfma_f32_16x16x32_bf16 v[50:53], v[152:155], v[176:179], v[50:53]
	v_mfma_f32_16x16x32_bf16 v[42:45], v[140:143], v[184:187], v[42:45]
	v_mfma_f32_16x16x32_bf16 v[34:37], v[152:155], v[184:187], v[34:37]
	v_mfma_f32_16x16x32_bf16 v[26:29], v[140:143], v[192:195], v[26:29]
	v_mfma_f32_16x16x32_bf16 v[18:21], v[152:155], v[192:195], v[18:21]
	v_mfma_f32_16x16x32_bf16 v[10:13], v[140:143], v[200:203], v[10:13]
	v_mfma_f32_16x16x32_bf16 v[6:9], v[152:155], v[200:203], v[6:9]
	v_mfma_f32_16x16x32_bf16 v[58:61], v[148:151], v[180:183], v[58:61]
	v_mfma_f32_16x16x32_bf16 v[50:53], v[156:159], v[180:183], v[50:53]
	v_mfma_f32_16x16x32_bf16 v[42:45], v[148:151], v[188:191], v[42:45]
	v_mfma_f32_16x16x32_bf16 v[34:37], v[156:159], v[188:191], v[34:37]
	v_mfma_f32_16x16x32_bf16 v[26:29], v[148:151], v[196:199], v[26:29]
	v_mfma_f32_16x16x32_bf16 v[18:21], v[156:159], v[196:199], v[18:21]
	v_mfma_f32_16x16x32_bf16 v[10:13], v[148:151], v[204:207], v[10:13]
	v_mfma_f32_16x16x32_bf16 v[6:9], v[156:159], v[204:207], v[6:9]
	s_setprio 0
	s_setprio 1
	v_mfma_f32_16x16x32_bf16 v[62:65], v[160:163], v[176:179], v[62:65]
	v_mfma_f32_16x16x32_bf16 v[54:57], v[168:171], v[176:179], v[54:57]
	v_mfma_f32_16x16x32_bf16 v[46:49], v[160:163], v[184:187], v[46:49]
	v_mfma_f32_16x16x32_bf16 v[38:41], v[168:171], v[184:187], v[38:41]
	v_mfma_f32_16x16x32_bf16 v[30:33], v[160:163], v[192:195], v[30:33]
	v_mfma_f32_16x16x32_bf16 v[22:25], v[168:171], v[192:195], v[22:25]
	v_mfma_f32_16x16x32_bf16 v[14:17], v[160:163], v[200:203], v[14:17]
	v_mfma_f32_16x16x32_bf16 v[2:5], v[168:171], v[200:203], v[2:5]
	v_mfma_f32_16x16x32_bf16 v[62:65], v[164:167], v[180:183], v[62:65]
	v_mfma_f32_16x16x32_bf16 v[54:57], v[172:175], v[180:183], v[54:57]
	v_mfma_f32_16x16x32_bf16 v[46:49], v[164:167], v[188:191], v[46:49]
	v_mfma_f32_16x16x32_bf16 v[38:41], v[172:175], v[188:191], v[38:41]
	v_mfma_f32_16x16x32_bf16 v[30:33], v[164:167], v[196:199], v[30:33]
	v_mfma_f32_16x16x32_bf16 v[22:25], v[172:175], v[196:199], v[22:25]
	v_mfma_f32_16x16x32_bf16 v[14:17], v[164:167], v[204:207], v[14:17]
	v_mfma_f32_16x16x32_bf16 v[2:5], v[172:175], v[204:207], v[2:5]
	s_setprio 0
	s_barrier
	s_add_i32 s57, 0, 0x18000
	s_add_i32 s58, 0, 0x1c000
	v_add_u32_e32 v156, s57, v145
	v_add_u32_e32 v172, s58, v145
	ds_read_b128 v[140:143], v156
	ds_read_b128 v[148:151], v156 offset:1024
	ds_read_b128 v[152:155], v156 offset:2048
	ds_read_b128 v[156:159], v156 offset:3072
	ds_read_b128 v[160:163], v172
	ds_read_b128 v[164:167], v172 offset:1024
	ds_read_b128 v[168:171], v172 offset:2048
	ds_read_b128 v[172:175], v172 offset:3072
	s_add_u32 s38, s38, 0x40000
	s_addc_u32 s39, s39, 0
	s_mov_b32 m0, s45
	v_lshl_add_u64 v[216:217], s[38:39], 0, v[130:131]
	ds_read_b128 v[176:179], v147 offset:32768
	ds_read_b128 v[180:183], v147 offset:33792
	ds_read_b128 v[184:187], v147 offset:34816
	ds_read_b128 v[188:191], v147 offset:35840
	ds_read_b128 v[192:195], v147 offset:36864
	ds_read_b128 v[196:199], v147 offset:37888
	ds_read_b128 v[200:203], v147 offset:38912
	ds_read_b128 v[204:207], v147 offset:39936
	global_load_lds_dwordx4 v[216:217], off sc1
	v_lshl_add_u64 v[216:217], s[38:39], 0, v[132:133]
	s_mov_b32 m0, s47
	s_nop 0
	global_load_lds_dwordx4 v[216:217], off sc1
	s_waitcnt vmcnt(8)
	s_waitcnt lgkmcnt(0)
	s_barrier
	s_setprio 1
	s_waitcnt lgkmcnt(0)
	v_mfma_f32_16x16x32_bf16 v[122:125], v[140:143], v[176:179], v[122:125]
	v_mfma_f32_16x16x32_bf16 v[114:117], v[152:155], v[176:179], v[114:117]
	v_mfma_f32_16x16x32_bf16 v[106:109], v[140:143], v[184:187], v[106:109]
	v_mfma_f32_16x16x32_bf16 v[98:101], v[152:155], v[184:187], v[98:101]
	v_mfma_f32_16x16x32_bf16 v[90:93], v[140:143], v[192:195], v[90:93]
	v_mfma_f32_16x16x32_bf16 v[82:85], v[152:155], v[192:195], v[82:85]
	v_mfma_f32_16x16x32_bf16 v[74:77], v[140:143], v[200:203], v[74:77]
	v_mfma_f32_16x16x32_bf16 v[66:69], v[152:155], v[200:203], v[66:69]
	v_mfma_f32_16x16x32_bf16 v[122:125], v[148:151], v[180:183], v[122:125]
	v_mfma_f32_16x16x32_bf16 v[114:117], v[156:159], v[180:183], v[114:117]
	v_mfma_f32_16x16x32_bf16 v[106:109], v[148:151], v[188:191], v[106:109]
	v_mfma_f32_16x16x32_bf16 v[98:101], v[156:159], v[188:191], v[98:101]
	v_mfma_f32_16x16x32_bf16 v[90:93], v[148:151], v[196:199], v[90:93]
	v_mfma_f32_16x16x32_bf16 v[82:85], v[156:159], v[196:199], v[82:85]
	v_mfma_f32_16x16x32_bf16 v[74:77], v[148:151], v[204:207], v[74:77]
	v_mfma_f32_16x16x32_bf16 v[66:69], v[156:159], v[204:207], v[66:69]
	s_setprio 0
	s_setprio 1
	v_mfma_f32_16x16x32_bf16 v[126:129], v[160:163], v[176:179], v[126:129]
	v_mfma_f32_16x16x32_bf16 v[118:121], v[168:171], v[176:179], v[118:121]
	v_mfma_f32_16x16x32_bf16 v[110:113], v[160:163], v[184:187], v[110:113]
	v_mfma_f32_16x16x32_bf16 v[102:105], v[168:171], v[184:187], v[102:105]
	v_mfma_f32_16x16x32_bf16 v[94:97], v[160:163], v[192:195], v[94:97]
	v_mfma_f32_16x16x32_bf16 v[86:89], v[168:171], v[192:195], v[86:89]
	v_mfma_f32_16x16x32_bf16 v[78:81], v[160:163], v[200:203], v[78:81]
	v_mfma_f32_16x16x32_bf16 v[70:73], v[168:171], v[200:203], v[70:73]
	v_mfma_f32_16x16x32_bf16 v[126:129], v[164:167], v[180:183], v[126:129]
	v_mfma_f32_16x16x32_bf16 v[118:121], v[172:175], v[180:183], v[118:121]
	v_mfma_f32_16x16x32_bf16 v[110:113], v[164:167], v[188:191], v[110:113]
	v_mfma_f32_16x16x32_bf16 v[102:105], v[172:175], v[188:191], v[102:105]
	v_mfma_f32_16x16x32_bf16 v[94:97], v[164:167], v[196:199], v[94:97]
	v_mfma_f32_16x16x32_bf16 v[86:89], v[172:175], v[196:199], v[86:89]
	v_mfma_f32_16x16x32_bf16 v[78:81], v[164:167], v[204:207], v[78:81]
	v_mfma_f32_16x16x32_bf16 v[70:73], v[172:175], v[204:207], v[70:73]
	s_setprio 0
	s_barrier
	s_add_i32 s38, s57, s43
	v_lshl_add_u64 v[208:209], v[208:209], 0, s[98:99]
	s_mov_b32 m0, s38
	ds_read_b128 v[176:179], v147 offset:49152
	ds_read_b128 v[180:183], v147 offset:50176
	ds_read_b128 v[184:187], v147 offset:51200
	ds_read_b128 v[188:191], v147 offset:52224
	ds_read_b128 v[192:195], v147 offset:53248
	ds_read_b128 v[196:199], v147 offset:54272
	ds_read_b128 v[200:203], v147 offset:55296
	ds_read_b128 v[204:207], v147 offset:56320
	global_load_lds_dwordx4 v[208:209], off sc1
	s_add_i32 m0, s38, 0x2000
	s_add_u32 s30, s30, 0x40080
	v_lshl_add_u64 v[208:209], v[210:211], 0, s[98:99]
	s_addc_u32 s31, s31, 0
	s_add_i32 s38, s58, s43
	global_load_lds_dwordx4 v[208:209], off sc1
	v_lshl_add_u64 v[208:209], s[30:31], 0, v[0:1]
	s_mov_b32 m0, s38
	s_nop 0
	global_load_lds_dwordx4 v[208:209], off sc1
	v_lshl_add_u64 v[208:209], s[30:31], 0, v[134:135]
	s_add_i32 m0, s38, 0x2000
	s_nop 0
	global_load_lds_dwordx4 v[208:209], off sc1
	v_lshl_add_u64 v[208:209], v[212:213], 0, s[98:99]
	s_mov_b32 m0, s49
	s_nop 0
	global_load_lds_dwordx4 v[208:209], off sc1
	v_lshl_add_u64 v[208:209], v[214:215], 0, s[98:99]
	s_mov_b32 m0, s51
	s_nop 0
	global_load_lds_dwordx4 v[208:209], off sc1
	s_waitcnt vmcnt(8)
	s_waitcnt lgkmcnt(0)
	s_barrier
	s_setprio 1
	s_waitcnt lgkmcnt(0)
	v_mfma_f32_16x16x32_bf16 v[58:61], v[140:143], v[176:179], v[58:61]
	v_mfma_f32_16x16x32_bf16 v[50:53], v[152:155], v[176:179], v[50:53]
	v_mfma_f32_16x16x32_bf16 v[42:45], v[140:143], v[184:187], v[42:45]
	v_mfma_f32_16x16x32_bf16 v[34:37], v[152:155], v[184:187], v[34:37]
	v_mfma_f32_16x16x32_bf16 v[26:29], v[140:143], v[192:195], v[26:29]
	v_mfma_f32_16x16x32_bf16 v[18:21], v[152:155], v[192:195], v[18:21]
	v_mfma_f32_16x16x32_bf16 v[10:13], v[140:143], v[200:203], v[10:13]
	v_mfma_f32_16x16x32_bf16 v[6:9], v[152:155], v[200:203], v[6:9]
	v_mfma_f32_16x16x32_bf16 v[58:61], v[148:151], v[180:183], v[58:61]
	v_mfma_f32_16x16x32_bf16 v[50:53], v[156:159], v[180:183], v[50:53]
	v_mfma_f32_16x16x32_bf16 v[42:45], v[148:151], v[188:191], v[42:45]
	v_mfma_f32_16x16x32_bf16 v[34:37], v[156:159], v[188:191], v[34:37]
	v_mfma_f32_16x16x32_bf16 v[26:29], v[148:151], v[196:199], v[26:29]
	v_mfma_f32_16x16x32_bf16 v[18:21], v[156:159], v[196:199], v[18:21]
	v_mfma_f32_16x16x32_bf16 v[10:13], v[148:151], v[204:207], v[10:13]
	v_mfma_f32_16x16x32_bf16 v[6:9], v[156:159], v[204:207], v[6:9]
	s_setprio 0
	s_setprio 1
	v_mfma_f32_16x16x32_bf16 v[62:65], v[160:163], v[176:179], v[62:65]
	v_mfma_f32_16x16x32_bf16 v[54:57], v[168:171], v[176:179], v[54:57]
	v_mfma_f32_16x16x32_bf16 v[46:49], v[160:163], v[184:187], v[46:49]
	v_mfma_f32_16x16x32_bf16 v[38:41], v[168:171], v[184:187], v[38:41]
	v_mfma_f32_16x16x32_bf16 v[30:33], v[160:163], v[192:195], v[30:33]
	v_mfma_f32_16x16x32_bf16 v[22:25], v[168:171], v[192:195], v[22:25]
	v_mfma_f32_16x16x32_bf16 v[14:17], v[160:163], v[200:203], v[14:17]
	v_mfma_f32_16x16x32_bf16 v[2:5], v[168:171], v[200:203], v[2:5]
	v_mfma_f32_16x16x32_bf16 v[62:65], v[164:167], v[180:183], v[62:65]
	v_mfma_f32_16x16x32_bf16 v[54:57], v[172:175], v[180:183], v[54:57]
	v_mfma_f32_16x16x32_bf16 v[46:49], v[164:167], v[188:191], v[46:49]
	v_mfma_f32_16x16x32_bf16 v[38:41], v[172:175], v[188:191], v[38:41]
	v_mfma_f32_16x16x32_bf16 v[30:33], v[164:167], v[196:199], v[30:33]
	v_mfma_f32_16x16x32_bf16 v[22:25], v[172:175], v[196:199], v[22:25]
	v_mfma_f32_16x16x32_bf16 v[14:17], v[164:167], v[204:207], v[14:17]
	v_mfma_f32_16x16x32_bf16 v[2:5], v[172:175], v[204:207], v[2:5]
	s_setprio 0
	s_barrier
	s_add_i32 s56, s56, 2
	s_add_u32 s28, s28, 0x100
	s_addc_u32 s29, s29, 0
	s_add_u32 s54, s54, 0x100
	s_addc_u32 s55, s55, 0
	s_cmp_gt_u32 s56, 13
	s_cbranch_scc0 .LBB0_374
	s_and_b64 vcc, exec, s[12:13]
	s_cbranch_vccz .LBB0_377
	s_barrier

.LBB0_388:
	s_cmpk_gt_i32 s31, 0x1ff
	s_mov_b64 s[8:9], -1
	s_cbranch_scc0 .LBB0_530
	s_cmp_ge_i32 s31, s21
	s_cbranch_scc0 .LBB0_521
	s_add_i32 s8, s31, s22
	s_lshl_b32 s16, s8, 6
	s_cmpk_lt_i32 s8, 0x100
	s_movk_i32 s8, 0x1000
	s_cselect_b32 s14, s8, 0x100
	s_movk_i32 s8, 0xf000
	s_cselect_b32 s8, s8, 0x7fffff00
	s_and_b32 s15, s8, s16
	s_sub_i32 s8, s16, s15
	v_or_b32_e32 v243, s8, v153
	s_mov_b64 s[8:9], -1
	s_and_b64 vcc, exec, s[4:5]
	s_cbranch_vccz .LBB0_500
	s_mov_b64 s[12:13], -1
	s_mov_b64 s[8:9], 0
	s_cmp_lt_i32 s25, 2
	s_mov_b64 s[10:11], 0
	s_cbranch_scc1 .LBB0_473
	s_cmp_eq_u32 s25, 2
	s_mov_b64 s[10:11], -1
	s_cbranch_scc0 .LBB0_424
	v_add_u32_e32 v0, -4, v243
	v_cmp_gt_u32_e32 vcc, s14, v0
	v_mov_b32_e32 v26, 0
	v_mov_b32_e32 v30, 0
	v_mov_b32_e32 v31, 0
	v_mov_b32_e32 v32, 0
	v_mov_b32_e32 v33, 0
	s_and_saveexec_b64 s[10:11], vcc
	s_cbranch_execz .LBB0_395
	v_add_u32_e32 v0, s15, v0
	v_mad_i64_i32 v[2:3], s[12:13], v0, s91, v[140:141]
	global_load_dwordx4 v[30:33], v[2:3], off sc1
.LBB0_395:
	s_or_b64 exec, exec, s[10:11]
	v_add_u32_e32 v0, -3, v243
	v_cmp_gt_u32_e32 vcc, s14, v0
	v_mov_b32_e32 v27, 0
	v_mov_b32_e32 v28, 0
	v_mov_b32_e32 v29, 0
	s_and_saveexec_b64 s[10:11], vcc
	s_cbranch_execz .LBB0_397
	v_add_u32_e32 v0, s15, v0
	v_mad_i64_i32 v[2:3], s[12:13], v0, s91, v[140:141]
	global_load_dwordx4 v[26:29], v[2:3], off sc1
.LBB0_397:
	s_or_b64 exec, exec, s[10:11]
	v_add_u32_e32 v0, -2, v243
	v_cmp_gt_u32_e32 vcc, s14, v0
	v_mov_b32_e32 v42, 0
	v_mov_b32_e32 v46, 0
	v_mov_b32_e32 v47, 0
	v_mov_b32_e32 v48, 0
	v_mov_b32_e32 v49, 0
	s_and_saveexec_b64 s[10:11], vcc
	s_cbranch_execz .LBB0_399
	v_add_u32_e32 v0, s15, v0
	v_mad_i64_i32 v[2:3], s[12:13], v0, s91, v[140:141]
	global_load_dwordx4 v[46:49], v[2:3], off sc1
.LBB0_399:
	s_or_b64 exec, exec, s[10:11]
	v_add_u32_e32 v0, -1, v243
	v_cmp_gt_u32_e32 vcc, s14, v0
	v_mov_b32_e32 v43, 0
	v_mov_b32_e32 v44, 0
	v_mov_b32_e32 v45, 0
	s_and_saveexec_b64 s[10:11], vcc
	s_cbranch_execz .LBB0_401
	v_add_u32_e32 v0, s15, v0
	v_mad_i64_i32 v[2:3], s[12:13], v0, s91, v[140:141]
	global_load_dwordx4 v[42:45], v[2:3], off sc1
.LBB0_401:
	s_or_b64 exec, exec, s[10:11]
	v_cmp_gt_u32_e32 vcc, s14, v243
	v_mov_b32_e32 v58, 0
	v_mov_b32_e32 v38, 0
	v_mov_b32_e32 v39, 0
	v_mov_b32_e32 v40, 0
	v_mov_b32_e32 v41, 0
	s_and_saveexec_b64 s[10:11], vcc
	s_cbranch_execz .LBB0_403
	v_or_b32_e32 v0, s16, v153
	v_mad_i64_i32 v[2:3], s[12:13], v0, s91, v[140:141]
	global_load_dwordx4 v[38:41], v[2:3], off sc1
.LBB0_403:
	s_or_b64 exec, exec, s[10:11]
	v_or_b32_e32 v71, 1, v243
	v_cmp_gt_u32_e32 vcc, s14, v71
	v_add_u32_e32 v72, s15, v71
	v_mov_b32_e32 v59, 0
	v_mov_b32_e32 v60, 0
	v_mov_b32_e32 v61, 0
	s_and_saveexec_b64 s[10:11], vcc
	s_cbranch_execz .LBB0_405
	v_mad_i64_i32 v[2:3], s[12:13], v72, s91, v[140:141]
	global_load_dwordx4 v[58:61], v[2:3], off sc1
.LBB0_405:
	s_or_b64 exec, exec, s[10:11]
	v_or_b32_e32 v69, 2, v243
	v_cmp_gt_u32_e32 vcc, s14, v69
	v_mov_b32_e32 v50, 0
	v_add_u32_e32 v70, s15, v69
	v_mov_b32_e32 v54, 0
	v_mov_b32_e32 v55, 0
	v_mov_b32_e32 v56, 0
	v_mov_b32_e32 v57, 0
	s_and_saveexec_b64 s[10:11], vcc
	s_cbranch_execz .LBB0_407
	v_mad_i64_i32 v[2:3], s[12:13], v70, s91, v[140:141]
	global_load_dwordx4 v[54:57], v[2:3], off sc1
.LBB0_407:
	s_or_b64 exec, exec, s[10:11]
	v_or_b32_e32 v0, 3, v243
	v_cmp_gt_u32_e32 vcc, s14, v0
	v_add_u32_e32 v68, s15, v0
	v_mov_b32_e32 v51, 0
	v_mov_b32_e32 v52, 0
	v_mov_b32_e32 v53, 0
	s_and_saveexec_b64 s[10:11], vcc
	s_cbranch_execz .LBB0_409
	v_mad_i64_i32 v[2:3], s[12:13], v68, s91, v[140:141]
	global_load_dwordx4 v[50:53], v[2:3], off sc1
.LBB0_409:
	s_or_b64 exec, exec, s[10:11]
	v_or_b32_e32 v67, 4, v243
	v_cmp_gt_u32_e32 vcc, s14, v67
	v_mov_b32_e32 v22, 0
	v_add_u32_e32 v66, s15, v67
	v_mov_b32_e32 v34, 0
	v_mov_b32_e32 v35, 0
	v_mov_b32_e32 v36, 0
	v_mov_b32_e32 v37, 0
	s_and_saveexec_b64 s[10:11], vcc
	s_cbranch_execz .LBB0_411
	v_mad_i64_i32 v[2:3], s[12:13], v66, s91, v[140:141]
	global_load_dwordx4 v[34:37], v[2:3], off sc1
.LBB0_411:
	s_or_b64 exec, exec, s[10:11]
	v_or_b32_e32 v65, 5, v243
	v_cmp_gt_u32_e32 vcc, s14, v65
	v_add_u32_e32 v64, s15, v65
	v_mov_b32_e32 v23, 0
	v_mov_b32_e32 v24, 0
	v_mov_b32_e32 v25, 0
	s_and_saveexec_b64 s[10:11], vcc
	s_cbranch_execz .LBB0_413
	v_mad_i64_i32 v[2:3], s[12:13], v64, s91, v[140:141]
	global_load_dwordx4 v[22:25], v[2:3], off sc1
.LBB0_413:
	s_or_b64 exec, exec, s[10:11]
	v_or_b32_e32 v63, 6, v243
	v_cmp_gt_u32_e32 vcc, s14, v63
	v_mov_b32_e32 v14, 0
	v_add_u32_e32 v62, s15, v63
	v_mov_b32_e32 v18, 0
	v_mov_b32_e32 v19, 0
	v_mov_b32_e32 v20, 0
	v_mov_b32_e32 v21, 0
	s_and_saveexec_b64 s[10:11], vcc
	s_cbranch_execz .LBB0_415
	v_mad_i64_i32 v[2:3], s[12:13], v62, s91, v[140:141]
	global_load_dwordx4 v[18:21], v[2:3], off sc1
.LBB0_415:
	s_or_b64 exec, exec, s[10:11]
	s_waitcnt vmcnt(0)
	v_or_b32_e32 v95, 7, v243
	v_cmp_gt_u32_e32 vcc, s14, v95
	v_add_u32_e32 v94, s15, v95
	v_mov_b32_e32 v15, 0
	v_mov_b32_e32 v16, 0
	v_mov_b32_e32 v17, 0
	s_and_saveexec_b64 s[10:11], vcc
	s_cbranch_execz .LBB0_417
	v_mad_i64_i32 v[2:3], s[12:13], v94, s91, v[140:141]
	global_load_dwordx4 v[14:17], v[2:3], off sc1
.LBB0_417:
	s_or_b64 exec, exec, s[10:11]
	v_add_u32_e32 v106, 8, v243
	v_cmp_gt_u32_e32 vcc, s14, v106
	v_mov_b32_e32 v2, 0
	v_mov_b32_e32 v6, 0
	v_mov_b32_e32 v7, 0
	v_mov_b32_e32 v8, 0
	v_mov_b32_e32 v9, 0
	s_and_saveexec_b64 s[10:11], vcc
	s_cbranch_execz .LBB0_419
	v_add_u32_e32 v3, s15, v106
	v_mad_i64_i32 v[4:5], s[12:13], v3, s91, v[140:141]
	global_load_dwordx4 v[6:9], v[4:5], off sc1
.LBB0_419:
	s_or_b64 exec, exec, s[10:11]
	v_add_u32_e32 v105, 9, v243
	v_cmp_gt_u32_e32 vcc, s14, v105
	v_mov_b32_e32 v3, 0
	v_mov_b32_e32 v4, 0
	v_mov_b32_e32 v5, 0
	s_and_saveexec_b64 s[10:11], vcc
	s_cbranch_execz .LBB0_421
	v_add_u32_e32 v2, s15, v105
	v_mad_i64_i32 v[2:3], s[12:13], v2, s91, v[140:141]
	global_load_dwordx4 v[2:5], v[2:3], off sc1
.LBB0_421:
	s_or_b64 exec, exec, s[10:11]
	v_add_u32_e32 v104, 10, v243
	v_cmp_gt_u32_e32 vcc, s14, v104
	v_mov_b32_e32 v10, 0
	v_mov_b32_e32 v11, 0
	v_mov_b32_e32 v12, 0
	v_mov_b32_e32 v13, 0
	s_and_saveexec_b64 s[10:11], vcc
	s_cbranch_execz .LBB0_423
	v_add_u32_e32 v10, s15, v104
	v_mad_i64_i32 v[10:11], s[12:13], v10, s91, v[140:141]
	global_load_dwordx4 v[10:13], v[10:11], off sc1

.LBB0_426:
	v_add_u32_e32 v0, -8, v243
	v_cmp_gt_u32_e32 vcc, s14, v0
	v_mov_b32_e32 v70, 0
	v_mov_b32_e32 v74, 0
	v_mov_b32_e32 v75, 0
	v_mov_b32_e32 v76, 0
	v_mov_b32_e32 v77, 0
	s_and_saveexec_b64 s[8:9], vcc
	s_cbranch_execz .LBB0_428
	v_add_u32_e32 v0, s15, v0
	v_mad_i64_i32 v[2:3], s[10:11], v0, s91, v[140:141]
	global_load_dwordx4 v[74:77], v[2:3], off sc1
.LBB0_428:
	s_or_b64 exec, exec, s[8:9]
	v_add_u32_e32 v0, -7, v243
	v_cmp_gt_u32_e32 vcc, s14, v0
	v_mov_b32_e32 v71, 0
	v_mov_b32_e32 v72, 0
	v_mov_b32_e32 v73, 0
	s_and_saveexec_b64 s[8:9], vcc
	s_cbranch_execz .LBB0_430
	v_add_u32_e32 v0, s15, v0
	v_mad_i64_i32 v[2:3], s[10:11], v0, s91, v[140:141]
	global_load_dwordx4 v[70:73], v[2:3], off sc1
.LBB0_430:
	s_or_b64 exec, exec, s[8:9]
	v_add_u32_e32 v0, -6, v243
	v_cmp_gt_u32_e32 vcc, s14, v0
	v_mov_b32_e32 v2, 0
	v_mov_b32_e32 v78, 0
	v_mov_b32_e32 v79, 0
	v_mov_b32_e32 v80, 0
	v_mov_b32_e32 v81, 0
	s_and_saveexec_b64 s[8:9], vcc
	s_cbranch_execz .LBB0_432
	v_add_u32_e32 v0, s15, v0
	v_mad_i64_i32 v[4:5], s[10:11], v0, s91, v[140:141]
	global_load_dwordx4 v[78:81], v[4:5], off sc1
.LBB0_432:
	s_or_b64 exec, exec, s[8:9]
	v_add_u32_e32 v0, -5, v243
	v_cmp_gt_u32_e32 vcc, s14, v0
	v_mov_b32_e32 v3, 0
	v_mov_b32_e32 v4, 0
	v_mov_b32_e32 v5, 0
	s_and_saveexec_b64 s[8:9], vcc
	s_cbranch_execz .LBB0_434
	v_add_u32_e32 v0, s15, v0
	v_mad_i64_i32 v[2:3], s[10:11], v0, s91, v[140:141]
	global_load_dwordx4 v[2:5], v[2:3], off sc1
.LBB0_434:
	s_or_b64 exec, exec, s[8:9]
	v_add_u32_e32 v0, -4, v243
	v_cmp_gt_u32_e32 vcc, s14, v0
	v_mov_b32_e32 v6, 0
	v_mov_b32_e32 v10, 0
	v_mov_b32_e32 v11, 0
	v_mov_b32_e32 v12, 0
	v_mov_b32_e32 v13, 0
	s_and_saveexec_b64 s[8:9], vcc
	s_cbranch_execz .LBB0_436
	v_add_u32_e32 v0, s15, v0
	v_mad_i64_i32 v[8:9], s[10:11], v0, s91, v[140:141]
	global_load_dwordx4 v[10:13], v[8:9], off sc1
.LBB0_436:
	s_or_b64 exec, exec, s[8:9]
	v_add_u32_e32 v0, -3, v243
	v_cmp_gt_u32_e32 vcc, s14, v0
	v_mov_b32_e32 v7, 0
	v_mov_b32_e32 v8, 0
	v_mov_b32_e32 v9, 0
	s_and_saveexec_b64 s[8:9], vcc
	s_cbranch_execz .LBB0_438
	v_add_u32_e32 v0, s15, v0
	v_mad_i64_i32 v[6:7], s[10:11], v0, s91, v[140:141]
	global_load_dwordx4 v[6:9], v[6:7], off sc1
.LBB0_438:
	s_or_b64 exec, exec, s[8:9]
	v_add_u32_e32 v0, -2, v243
	v_cmp_gt_u32_e32 vcc, s14, v0
	v_mov_b32_e32 v14, 0
	v_mov_b32_e32 v18, 0
	v_mov_b32_e32 v19, 0
	v_mov_b32_e32 v20, 0
	v_mov_b32_e32 v21, 0
	s_and_saveexec_b64 s[8:9], vcc
	s_cbranch_execz .LBB0_440
	v_add_u32_e32 v0, s15, v0
	v_mad_i64_i32 v[16:17], s[10:11], v0, s91, v[140:141]
	global_load_dwordx4 v[18:21], v[16:17], off sc1
.LBB0_440:
	s_or_b64 exec, exec, s[8:9]
	v_add_u32_e32 v0, -1, v243
	v_cmp_gt_u32_e32 vcc, s14, v0
	v_mov_b32_e32 v15, 0
	v_mov_b32_e32 v16, 0
	v_mov_b32_e32 v17, 0
	s_and_saveexec_b64 s[8:9], vcc
	s_cbranch_execz .LBB0_442
	v_add_u32_e32 v0, s15, v0
	v_mad_i64_i32 v[14:15], s[10:11], v0, s91, v[140:141]
	global_load_dwordx4 v[14:17], v[14:15], off sc1
.LBB0_442:
	s_or_b64 exec, exec, s[8:9]
	v_cmp_gt_u32_e32 vcc, s14, v243
	v_mov_b32_e32 v26, 0
	v_mov_b32_e32 v54, 0
	v_mov_b32_e32 v55, 0
	v_mov_b32_e32 v56, 0
	v_mov_b32_e32 v57, 0
	s_and_saveexec_b64 s[8:9], vcc
	s_cbranch_execz .LBB0_444
	v_or_b32_e32 v0, s16, v153
	v_mad_i64_i32 v[22:23], s[10:11], v0, s91, v[140:141]
	global_load_dwordx4 v[54:57], v[22:23], off sc1
.LBB0_444:
	s_or_b64 exec, exec, s[8:9]
	s_waitcnt vmcnt(0)
	v_or_b32_e32 v116, 1, v243
	v_cmp_gt_u32_e32 vcc, s14, v116
	v_add_u32_e32 v118, s15, v116
	v_mov_b32_e32 v27, 0
	v_mov_b32_e32 v28, 0
	v_mov_b32_e32 v29, 0
	s_and_saveexec_b64 s[8:9], vcc
	s_cbranch_execz .LBB0_446
	v_mad_i64_i32 v[22:23], s[10:11], v118, s91, v[140:141]
	global_load_dwordx4 v[26:29], v[22:23], off sc1
.LBB0_446:
	s_or_b64 exec, exec, s[8:9]
	v_or_b32_e32 v121, 2, v243
	v_cmp_gt_u32_e32 vcc, s14, v121
	v_mov_b32_e32 v22, 0
	v_add_u32_e32 v120, s15, v121
	v_mov_b32_e32 v34, 0
	v_mov_b32_e32 v35, 0
	v_mov_b32_e32 v36, 0
	v_mov_b32_e32 v37, 0
	s_and_saveexec_b64 s[8:9], vcc
	s_cbranch_execz .LBB0_448
	v_mad_i64_i32 v[24:25], s[10:11], v120, s91, v[140:141]
	global_load_dwordx4 v[34:37], v[24:25], off sc1
.LBB0_448:
	s_or_b64 exec, exec, s[8:9]
	v_or_b32_e32 v123, 3, v243
	v_cmp_gt_u32_e32 vcc, s14, v123
	v_add_u32_e32 v122, s15, v123
	v_mov_b32_e32 v23, 0
	v_mov_b32_e32 v24, 0
	v_mov_b32_e32 v25, 0
	s_and_saveexec_b64 s[8:9], vcc
	s_cbranch_execz .LBB0_450
	v_mad_i64_i32 v[22:23], s[10:11], v122, s91, v[140:141]
	global_load_dwordx4 v[22:25], v[22:23], off sc1
.LBB0_450:
	s_or_b64 exec, exec, s[8:9]
	v_or_b32_e32 v115, 4, v243
	v_cmp_gt_u32_e32 vcc, s14, v115
	v_mov_b32_e32 v82, 0
	v_add_u32_e32 v114, s15, v115
	v_mov_b32_e32 v58, 0
	v_mov_b32_e32 v59, 0
	v_mov_b32_e32 v60, 0
	v_mov_b32_e32 v61, 0
	s_and_saveexec_b64 s[8:9], vcc
	s_cbranch_execz .LBB0_452
	v_mad_i64_i32 v[30:31], s[10:11], v114, s91, v[140:141]
	global_load_dwordx4 v[58:61], v[30:31], off sc1
.LBB0_452:
	s_or_b64 exec, exec, s[8:9]
	v_or_b32_e32 v113, 5, v243
	v_cmp_gt_u32_e32 vcc, s14, v113
	v_add_u32_e32 v112, s15, v113
	v_mov_b32_e32 v83, 0
	v_mov_b32_e32 v84, 0
	v_mov_b32_e32 v85, 0
	s_and_saveexec_b64 s[8:9], vcc
	s_cbranch_execz .LBB0_454
	v_mad_i64_i32 v[30:31], s[10:11], v112, s91, v[140:141]
	global_load_dwordx4 v[82:85], v[30:31], off sc1
.LBB0_454:
	s_or_b64 exec, exec, s[8:9]
	v_or_b32_e32 v95, 6, v243
	v_cmp_gt_u32_e32 vcc, s14, v95
	v_mov_b32_e32 v62, 0
	v_add_u32_e32 v136, s15, v95
	v_mov_b32_e32 v66, 0
	v_mov_b32_e32 v67, 0
	v_mov_b32_e32 v68, 0
	v_mov_b32_e32 v69, 0
	s_and_saveexec_b64 s[8:9], vcc
	s_cbranch_execz .LBB0_456
	v_mad_i64_i32 v[30:31], s[10:11], v136, s91, v[140:141]
	global_load_dwordx4 v[66:69], v[30:31], off sc1
.LBB0_456:
	s_or_b64 exec, exec, s[8:9]
	v_or_b32_e32 v137, 7, v243
	v_cmp_gt_u32_e32 vcc, s14, v137
	v_add_u32_e32 v94, s15, v137
	v_mov_b32_e32 v63, 0
	v_mov_b32_e32 v64, 0
	v_mov_b32_e32 v65, 0
	s_and_saveexec_b64 s[8:9], vcc
	s_cbranch_execz .LBB0_458
	v_mad_i64_i32 v[30:31], s[10:11], v94, s91, v[140:141]
	global_load_dwordx4 v[62:65], v[30:31], off sc1
.LBB0_458:
	s_or_b64 exec, exec, s[8:9]
	v_add_u32_e32 v0, 8, v243
	v_cmp_gt_u32_e32 vcc, s14, v0
	v_mov_b32_e32 v30, 0
	v_mov_b32_e32 v50, 0
	v_mov_b32_e32 v51, 0
	v_mov_b32_e32 v52, 0
	v_mov_b32_e32 v53, 0
	s_and_saveexec_b64 s[8:9], vcc
	s_cbranch_execz .LBB0_460
	v_add_u32_e32 v31, s15, v0
	v_mad_i64_i32 v[32:33], s[10:11], v31, s91, v[140:141]
	global_load_dwordx4 v[50:53], v[32:33], off sc1
.LBB0_460:
	s_or_b64 exec, exec, s[8:9]
	v_add_u32_e32 v117, 9, v243
	v_cmp_gt_u32_e32 vcc, s14, v117
	v_mov_b32_e32 v31, 0
	v_mov_b32_e32 v32, 0
	v_mov_b32_e32 v33, 0
	s_and_saveexec_b64 s[8:9], vcc
	s_cbranch_execz .LBB0_462
	v_add_u32_e32 v30, s15, v117
	v_mad_i64_i32 v[30:31], s[10:11], v30, s91, v[140:141]
	global_load_dwordx4 v[30:33], v[30:31], off sc1
.LBB0_462:
	s_or_b64 exec, exec, s[8:9]
	v_add_u32_e32 v174, 10, v243
	v_cmp_gt_u32_e32 vcc, s14, v174
	v_mov_b32_e32 v86, 0
	v_mov_b32_e32 v90, 0
	v_mov_b32_e32 v91, 0
	v_mov_b32_e32 v92, 0
	v_mov_b32_e32 v93, 0
	s_and_saveexec_b64 s[8:9], vcc
	s_cbranch_execz .LBB0_464
	v_add_u32_e32 v38, s15, v174
	v_mad_i64_i32 v[38:39], s[10:11], v38, s91, v[140:141]
	global_load_dwordx4 v[90:93], v[38:39], off sc1
.LBB0_464:
	s_or_b64 exec, exec, s[8:9]
	v_add_u32_e32 v178, 11, v243
	v_cmp_gt_u32_e32 vcc, s14, v178
	v_mov_b32_e32 v87, 0
	v_mov_b32_e32 v88, 0
	v_mov_b32_e32 v89, 0
	s_and_saveexec_b64 s[8:9], vcc
	s_cbranch_execz .LBB0_466
	v_add_u32_e32 v38, s15, v178
	v_mad_i64_i32 v[38:39], s[10:11], v38, s91, v[140:141]
	global_load_dwordx4 v[86:89], v[38:39], off sc1
.LBB0_466:
	s_or_b64 exec, exec, s[8:9]
	v_add_u32_e32 v179, 12, v243
	v_cmp_gt_u32_e32 vcc, s14, v179
	v_mov_b32_e32 v38, 0
	v_mov_b32_e32 v46, 0
	v_mov_b32_e32 v47, 0
	v_mov_b32_e32 v48, 0
	v_mov_b32_e32 v49, 0
	s_and_saveexec_b64 s[8:9], vcc
	s_cbranch_execz .LBB0_468
	v_add_u32_e32 v39, s15, v179
	v_mad_i64_i32 v[40:41], s[10:11], v39, s91, v[140:141]
	global_load_dwordx4 v[46:49], v[40:41], off sc1
.LBB0_468:
	s_or_b64 exec, exec, s[8:9]
	v_add_u32_e32 v188, 13, v243
	v_cmp_gt_u32_e32 vcc, s14, v188
	v_mov_b32_e32 v39, 0
	v_mov_b32_e32 v40, 0
	v_mov_b32_e32 v41, 0
	s_and_saveexec_b64 s[8:9], vcc
	s_cbranch_execz .LBB0_470
	v_add_u32_e32 v38, s15, v188
	v_mad_i64_i32 v[38:39], s[10:11], v38, s91, v[140:141]
	global_load_dwordx4 v[38:41], v[38:39], off sc1
.LBB0_470:
	s_or_b64 exec, exec, s[8:9]
	v_add_u32_e32 v208, 14, v243
	v_cmp_gt_u32_e32 vcc, s14, v208
	v_mov_b32_e32 v42, 0
	v_mov_b32_e32 v43, 0
	v_mov_b32_e32 v44, 0
	v_mov_b32_e32 v45, 0
	s_and_saveexec_b64 s[8:9], vcc
	s_cbranch_execz .LBB0_472
	v_add_u32_e32 v42, s15, v208
	v_mad_i64_i32 v[42:43], s[10:11], v42, s91, v[140:141]
	global_load_dwordx4 v[42:45], v[42:43], off sc1

.LBB0_475:
	s_and_b64 vcc, exec, s[8:9]
	s_cbranch_vccz .LBB0_499
	v_add_u32_e32 v0, -2, v243
	v_cmp_gt_u32_e32 vcc, s14, v0
	v_mov_b32_e32 v34, 0
	v_mov_b32_e32 v42, 0
	v_mov_b32_e32 v43, 0
	v_mov_b32_e32 v44, 0
	v_mov_b32_e32 v45, 0
	s_and_saveexec_b64 s[8:9], vcc
	s_cbranch_execz .LBB0_478
	v_add_u32_e32 v0, s15, v0
	v_mad_i64_i32 v[2:3], s[10:11], v0, s91, v[140:141]
	global_load_dwordx4 v[42:45], v[2:3], off sc1
.LBB0_478:
	s_or_b64 exec, exec, s[8:9]
	v_add_u32_e32 v0, -1, v243
	v_cmp_gt_u32_e32 vcc, s14, v0
	v_mov_b32_e32 v35, 0
	v_mov_b32_e32 v36, 0
	v_mov_b32_e32 v37, 0
	s_and_saveexec_b64 s[8:9], vcc
	s_cbranch_execz .LBB0_480
	v_add_u32_e32 v0, s15, v0
	v_mad_i64_i32 v[2:3], s[10:11], v0, s91, v[140:141]
	global_load_dwordx4 v[34:37], v[2:3], off sc1
.LBB0_480:
	s_or_b64 exec, exec, s[8:9]
	v_cmp_gt_u32_e32 vcc, s14, v243
	v_mov_b32_e32 v30, 0
	v_mov_b32_e32 v38, 0
	v_mov_b32_e32 v39, 0
	v_mov_b32_e32 v40, 0
	v_mov_b32_e32 v41, 0
	s_and_saveexec_b64 s[8:9], vcc
	s_cbranch_execz .LBB0_482
	v_or_b32_e32 v0, s16, v153
	v_mad_i64_i32 v[2:3], s[10:11], v0, s91, v[140:141]
	global_load_dwordx4 v[38:41], v[2:3], off sc1
.LBB0_482:
	s_or_b64 exec, exec, s[8:9]
	v_or_b32_e32 v55, 1, v243
	v_cmp_gt_u32_e32 vcc, s14, v55
	v_add_u32_e32 v56, s15, v55
	v_mov_b32_e32 v31, 0
	v_mov_b32_e32 v32, 0
	v_mov_b32_e32 v33, 0
	s_and_saveexec_b64 s[8:9], vcc
	s_cbranch_execz .LBB0_484
	v_mad_i64_i32 v[2:3], s[10:11], v56, s91, v[140:141]
	global_load_dwordx4 v[30:33], v[2:3], off sc1
.LBB0_484:
	s_or_b64 exec, exec, s[8:9]
	v_or_b32_e32 v53, 2, v243
	v_cmp_gt_u32_e32 vcc, s14, v53
	v_mov_b32_e32 v22, 0
	v_add_u32_e32 v54, s15, v53
	v_mov_b32_e32 v26, 0
	v_mov_b32_e32 v27, 0
	v_mov_b32_e32 v28, 0
	v_mov_b32_e32 v29, 0
	s_and_saveexec_b64 s[8:9], vcc
	s_cbranch_execz .LBB0_486
	v_mad_i64_i32 v[2:3], s[10:11], v54, s91, v[140:141]
	global_load_dwordx4 v[26:29], v[2:3], off sc1
.LBB0_486:
	s_or_b64 exec, exec, s[8:9]
	v_or_b32_e32 v51, 3, v243
	v_cmp_gt_u32_e32 vcc, s14, v51
	v_add_u32_e32 v52, s15, v51
	v_mov_b32_e32 v23, 0
	v_mov_b32_e32 v24, 0
	v_mov_b32_e32 v25, 0
	s_and_saveexec_b64 s[8:9], vcc
	s_cbranch_execz .LBB0_488
	v_mad_i64_i32 v[2:3], s[10:11], v52, s91, v[140:141]
	global_load_dwordx4 v[22:25], v[2:3], off sc1
.LBB0_488:
	s_or_b64 exec, exec, s[8:9]
	v_or_b32_e32 v0, 4, v243
	v_cmp_gt_u32_e32 vcc, s14, v0
	v_mov_b32_e32 v14, 0
	v_add_u32_e32 v50, s15, v0
	v_mov_b32_e32 v18, 0
	v_mov_b32_e32 v19, 0
	v_mov_b32_e32 v20, 0
	v_mov_b32_e32 v21, 0
	s_and_saveexec_b64 s[8:9], vcc
	s_cbranch_execz .LBB0_490
	v_mad_i64_i32 v[2:3], s[10:11], v50, s91, v[140:141]
	global_load_dwordx4 v[18:21], v[2:3], off sc1
.LBB0_490:
	s_or_b64 exec, exec, s[8:9]
	v_or_b32_e32 v49, 5, v243
	v_cmp_gt_u32_e32 vcc, s14, v49
	v_add_u32_e32 v48, s15, v49
	v_mov_b32_e32 v15, 0
	v_mov_b32_e32 v16, 0
	v_mov_b32_e32 v17, 0
	s_and_saveexec_b64 s[8:9], vcc
	s_cbranch_execz .LBB0_492
	v_mad_i64_i32 v[2:3], s[10:11], v48, s91, v[140:141]
	global_load_dwordx4 v[14:17], v[2:3], off sc1
.LBB0_492:
	s_or_b64 exec, exec, s[8:9]
	v_or_b32_e32 v47, 6, v243
	v_cmp_gt_u32_e32 vcc, s14, v47
	v_mov_b32_e32 v2, 0
	v_add_u32_e32 v46, s15, v47
	v_mov_b32_e32 v6, 0
	v_mov_b32_e32 v7, 0
	v_mov_b32_e32 v8, 0
	v_mov_b32_e32 v9, 0
	s_and_saveexec_b64 s[8:9], vcc
	s_cbranch_execz .LBB0_494
	v_mad_i64_i32 v[4:5], s[10:11], v46, s91, v[140:141]
	global_load_dwordx4 v[6:9], v[4:5], off sc1
.LBB0_494:
	s_or_b64 exec, exec, s[8:9]
	v_or_b32_e32 v58, 7, v243
	v_cmp_gt_u32_e32 vcc, s14, v58
	s_waitcnt vmcnt(0)
	v_add_u32_e32 v94, s15, v58
	v_mov_b32_e32 v3, 0
	v_mov_b32_e32 v4, 0
	v_mov_b32_e32 v5, 0
	s_and_saveexec_b64 s[8:9], vcc
	s_cbranch_execz .LBB0_496
	v_mad_i64_i32 v[2:3], s[10:11], v94, s91, v[140:141]
	global_load_dwordx4 v[2:5], v[2:3], off sc1
.LBB0_496:
	s_or_b64 exec, exec, s[8:9]
	v_add_u32_e32 v59, 8, v243
	v_cmp_gt_u32_e32 vcc, s14, v59
	v_mov_b32_e32 v10, 0
	v_mov_b32_e32 v11, 0
	v_mov_b32_e32 v12, 0
	v_mov_b32_e32 v13, 0
	s_and_saveexec_b64 s[8:9], vcc
	s_cbranch_execz .LBB0_498
	v_add_u32_e32 v10, s15, v59
	v_mad_i64_i32 v[10:11], s[10:11], v10, s91, v[140:141]
	global_load_dwordx4 v[10:13], v[10:11], off sc1

.LBB0_500:
	s_and_b64 vcc, exec, s[8:9]
	v_mov_b64_e32 v[6:7], v[138:139]
	s_cbranch_vccz .LBB0_520
	v_add_u32_e32 v0, -1, v243
	v_cmp_gt_u32_e32 vcc, s14, v0
	v_mov_b32_e32 v30, 0
	v_mov_b32_e32 v34, 0
	v_mov_b32_e32 v35, 0
	v_mov_b32_e32 v36, 0
	v_mov_b32_e32 v37, 0
	s_and_saveexec_b64 s[8:9], vcc
	s_cbranch_execz .LBB0_503
	v_add_u32_e32 v0, s15, v0
	v_mad_i64_i32 v[2:3], s[10:11], v0, s91, v[146:147]
	global_load_dwordx4 v[34:37], v[2:3], off sc1
.LBB0_503:
	s_or_b64 exec, exec, s[8:9]
	v_cmp_gt_u32_e32 vcc, s14, v243
	v_or_b32_e32 v50, s16, v153
	v_mov_b32_e32 v31, 0
	v_mov_b32_e32 v32, 0
	v_mov_b32_e32 v33, 0
	s_and_saveexec_b64 s[8:9], vcc
	s_cbranch_execz .LBB0_505
	v_mad_i64_i32 v[2:3], s[10:11], v50, s91, v[146:147]
	global_load_dwordx4 v[30:33], v[2:3], off sc1
.LBB0_505:
	s_or_b64 exec, exec, s[8:9]
	v_or_b32_e32 v49, 1, v243
	v_cmp_gt_u32_e32 vcc, s14, v49
	v_mov_b32_e32 v22, 0
	v_add_u32_e32 v48, s15, v49
	v_mov_b32_e32 v26, 0
	v_mov_b32_e32 v27, 0
	v_mov_b32_e32 v28, 0
	v_mov_b32_e32 v29, 0
	s_and_saveexec_b64 s[8:9], vcc
	s_cbranch_execz .LBB0_507
	v_mad_i64_i32 v[2:3], s[10:11], v48, s91, v[146:147]
	global_load_dwordx4 v[26:29], v[2:3], off sc1
.LBB0_507:
	s_or_b64 exec, exec, s[8:9]
	v_or_b32_e32 v47, 2, v243
	v_cmp_gt_u32_e32 vcc, s14, v47
	v_add_u32_e32 v46, s15, v47
	v_mov_b32_e32 v23, 0
	v_mov_b32_e32 v24, 0
	v_mov_b32_e32 v25, 0
	s_and_saveexec_b64 s[8:9], vcc
	s_cbranch_execz .LBB0_509
	v_mad_i64_i32 v[2:3], s[10:11], v46, s91, v[146:147]
	global_load_dwordx4 v[22:25], v[2:3], off sc1
.LBB0_509:
	s_or_b64 exec, exec, s[8:9]
	v_or_b32_e32 v45, 3, v243
	v_cmp_gt_u32_e32 vcc, s14, v45
	v_mov_b32_e32 v14, 0
	v_add_u32_e32 v44, s15, v45
	v_mov_b32_e32 v18, 0
	v_mov_b32_e32 v19, 0
	v_mov_b32_e32 v20, 0
	v_mov_b32_e32 v21, 0
	s_and_saveexec_b64 s[8:9], vcc
	s_cbranch_execz .LBB0_511
	v_mad_i64_i32 v[2:3], s[10:11], v44, s91, v[146:147]
	global_load_dwordx4 v[18:21], v[2:3], off sc1
.LBB0_511:
	s_or_b64 exec, exec, s[8:9]
	v_or_b32_e32 v43, 4, v243
	v_cmp_gt_u32_e32 vcc, s14, v43
	v_add_u32_e32 v42, s15, v43
	v_mov_b32_e32 v15, 0
	v_mov_b32_e32 v16, 0
	v_mov_b32_e32 v17, 0
	s_and_saveexec_b64 s[8:9], vcc
	s_cbranch_execz .LBB0_513
	v_mad_i64_i32 v[2:3], s[10:11], v42, s91, v[146:147]
	global_load_dwordx4 v[14:17], v[2:3], off sc1
.LBB0_513:
	s_or_b64 exec, exec, s[8:9]
	v_or_b32_e32 v41, 5, v243
	v_cmp_gt_u32_e32 vcc, s14, v41
	v_mov_b32_e32 v2, 0
	v_add_u32_e32 v40, s15, v41
	v_mov_b32_e32 v10, 0
	v_mov_b32_e32 v11, 0
	v_mov_b32_e32 v12, 0
	v_mov_b32_e32 v13, 0
	s_and_saveexec_b64 s[8:9], vcc
	s_cbranch_execz .LBB0_515
	v_mad_i64_i32 v[4:5], s[10:11], v40, s91, v[146:147]
	global_load_dwordx4 v[10:13], v[4:5], off sc1
.LBB0_515:
	s_or_b64 exec, exec, s[8:9]
	v_or_b32_e32 v39, 6, v243
	v_cmp_gt_u32_e32 vcc, s14, v39
	v_add_u32_e32 v38, s15, v39
	v_mov_b32_e32 v3, 0
	v_mov_b32_e32 v4, 0
	v_mov_b32_e32 v5, 0
	s_and_saveexec_b64 s[8:9], vcc
	s_cbranch_execz .LBB0_517
	v_mad_i64_i32 v[2:3], s[10:11], v38, s91, v[146:147]
	global_load_dwordx4 v[2:5], v[2:3], off sc1
.LBB0_517:
	s_or_b64 exec, exec, s[8:9]
	v_or_b32_e32 v0, 7, v243
	s_waitcnt vmcnt(0)
	v_add_u32_e32 v94, s15, v0
	v_cmp_gt_u32_e32 vcc, s14, v0
	v_ashrrev_i32_e32 v95, 31, v94
	v_mov_b32_e32 v6, 0
	v_mov_b32_e32 v7, 0
	v_mov_b32_e32 v8, 0
	v_mov_b32_e32 v9, 0
	s_and_saveexec_b64 s[8:9], vcc
	s_cbranch_execz .LBB0_519
	v_mad_i64_i32 v[6:7], s[10:11], v94, s91, v[146:147]
	global_load_dwordx4 v[6:9], v[6:7], off sc1

.LBB0_521:
	s_and_b64 vcc, exec, s[8:9]
	s_cbranch_vccz .LBB0_529
	s_bfe_u32 s11, s31, 0x10002
	s_lshl_b32 s8, s11, 2
	s_add_i32 s10, s8, s25
	s_lshl_b32 s8, s31, 5
	s_and_b32 s15, s8, 0x7fffff00
	s_lshl_b32 s8, s31, 6
	s_and_b32 s8, s8, 0xc0
	v_or_b32_e32 v0, s8, v242
	v_or_b32_e32 v0, s15, v0
	v_mov_b64_e32 v[10:11], s[38:39]
	v_mad_u64_u32 v[2:3], s[8:9], v0, s91, v[10:11]
	s_lshl_b32 s8, s10, 6
	s_ashr_i32 s9, s8, 31
	s_lshl_b32 s96, s11, 7
	s_ashr_i32 s11, s10, 31
	v_lshl_add_u64 v[2:3], s[8:9], 1, v[2:3]
	v_lshlrev_b32_e32 v4, 1, v150
	v_mov_b32_e32 v5, v1
	s_or_b32 s12, s15, 64
	s_lshl_b64 s[10:11], s[10:11], 2
	v_lshl_add_u64 v[2:3], v[2:3], 0, v[4:5]
	s_add_u32 s10, s23, s10
	global_load_dwordx4 v[90:93], v[2:3], off offset:1024 sc1
	global_load_dwordx4 v[94:97], v[2:3], off offset:1056 sc1
	global_load_dwordx4 v[98:101], v[2:3], off offset:1088 sc1
	global_load_dwordx4 v[102:105], v[2:3], off offset:1120 sc1
	s_addc_u32 s11, s24, s11
	v_add_u32_e32 v2, s15, v236
	global_load_dword v9, v1, s[10:11] sc1
	v_mad_i64_i32 v[2:3], s[10:11], v2, s91, v[10:11]
	v_or_b32_e32 v4, s15, v151
	v_lshl_add_u64 v[2:3], v[2:3], 0, s[96:97]
	v_lshlrev_b32_e32 v12, 1, v152
	v_mov_b32_e32 v13, v1
	v_mad_u64_u32 v[4:5], s[10:11], v4, s91, v[10:11]
	v_lshl_add_u64 v[2:3], v[2:3], 0, v[12:13]
	v_lshl_add_u64 v[4:5], v[4:5], 0, s[96:97]
	v_lshl_add_u64 v[4:5], v[4:5], 0, s[6:7]
	global_load_dwordx4 v[106:109], v[2:3], off offset:2048 sc1
	global_load_dwordx4 v[110:113], v[4:5], off offset:2304 sc1
	v_add_u32_e32 v2, s12, v236
	v_mad_i64_i32 v[2:3], s[10:11], v2, s91, v[10:11]
	v_or_b32_e32 v4, s12, v151
	v_lshl_add_u64 v[2:3], v[2:3], 0, s[96:97]
	v_mad_u64_u32 v[4:5], s[10:11], v4, s91, v[10:11]
	v_lshl_add_u64 v[2:3], v[2:3], 0, v[12:13]
	v_lshl_add_u64 v[4:5], v[4:5], 0, s[96:97]
	v_lshl_add_u64 v[4:5], v[4:5], 0, s[6:7]
	global_load_dwordx4 v[114:117], v[2:3], off offset:2048 sc1
	global_load_dwordx4 v[118:121], v[4:5], off offset:2304 sc1
	s_or_b32 s10, s15, 0x80
	s_or_b32 s11, s15, 0xc0
	v_add_u32_e32 v14, s10, v236
	v_or_b32_e32 v16, s10, v151
	v_add_u32_e32 v18, s11, v236
	v_or_b32_e32 v20, s11, v151
	v_mad_i64_i32 v[14:15], s[10:11], v14, s91, v[10:11]
	v_mad_u64_u32 v[16:17], s[10:11], v16, s91, v[10:11]
	v_mad_i64_i32 v[18:19], s[10:11], v18, s91, v[10:11]
	v_mad_u64_u32 v[10:11], s[10:11], v20, s91, v[10:11]
	v_mov_b32_e32 v2, 0
	v_lshl_add_u64 v[14:15], v[14:15], 0, s[96:97]
	v_lshl_add_u64 v[16:17], v[16:17], 0, s[96:97]
	v_lshl_add_u64 v[18:19], v[18:19], 0, s[96:97]
	v_lshl_add_u64 v[10:11], v[10:11], 0, s[96:97]
	s_mov_b32 s14, 0
	s_mov_b64 s[12:13], -1
	v_mov_b32_e32 v165, v237
	v_mov_b32_e32 v3, v2
	v_mov_b32_e32 v4, v2
	v_mov_b32_e32 v5, v2
	v_mov_b32_e32 v6, v2
	v_mov_b32_e32 v7, v2
	v_mov_b32_e32 v8, v2
	v_lshl_add_u64 v[160:161], v[14:15], 0, v[12:13]
	v_lshl_add_u64 v[162:163], v[16:17], 0, s[6:7]
	v_lshl_add_u64 v[166:167], v[18:19], 0, v[12:13]
	v_lshl_add_u64 v[168:169], v[10:11], 0, s[6:7]
	v_mov_b32_e32 v10, v2
	v_mov_b32_e32 v11, v2
	v_mov_b32_e32 v12, v2
	v_mov_b32_e32 v13, v2
	v_mov_b32_e32 v14, v2
	v_mov_b32_e32 v15, v2
	v_mov_b32_e32 v16, v2
	v_mov_b32_e32 v17, v2
	v_mov_b32_e32 v18, v2
	v_mov_b32_e32 v19, v2
	v_mov_b32_e32 v20, v2
	v_mov_b32_e32 v21, v2
	v_mov_b32_e32 v22, v2
	v_mov_b32_e32 v23, v2
	v_mov_b32_e32 v24, v2
	v_mov_b32_e32 v25, v2
	v_mov_b32_e32 v26, v2
	v_mov_b32_e32 v27, v2
	v_mov_b32_e32 v28, v2
	v_mov_b32_e32 v29, v2
	v_mov_b32_e32 v30, v2
	v_mov_b32_e32 v31, v2
	v_mov_b32_e32 v32, v2
	v_mov_b32_e32 v33, v2
	s_waitcnt vmcnt(0)
	v_mul_f32_e32 v213, 0x3fb8aa3b, v9
	v_mov_b32_e32 v9, v2
	s_branch .LBB0_524

.LBB0_524:
	s_mul_i32 s15, s14, 0x4800
	s_add_i32 s15, s15, 0
	s_add_i32 s16, s15, s27
	v_add3_u32 v34, s15, v238, v154
	v_add_u32_e32 v35, s16, v239
	s_waitcnt vmcnt(1)
	ds_write_b128 v34, v[106:109]
	s_waitcnt vmcnt(0)
	ds_write_b16 v35, v110 offset:9216
	ds_write_b16_d16_hi v35, v110 offset:9360
	ds_write_b16 v35, v111 offset:9504
	ds_write_b16_d16_hi v35, v111 offset:9648
	ds_write_b16 v35, v112 offset:9792
	ds_write_b16_d16_hi v35, v112 offset:9936
	ds_write_b16 v35, v113 offset:10080
	ds_write_b16_d16_hi v35, v113 offset:10224
	ds_write_b128 v34, v[114:117] offset:18432
	ds_write_b16 v35, v118 offset:27648
	ds_write_b16_d16_hi v35, v118 offset:27792
	ds_write_b16 v35, v119 offset:27936
	ds_write_b16_d16_hi v35, v119 offset:28080
	ds_write_b16 v35, v120 offset:28224
	ds_write_b16_d16_hi v35, v120 offset:28368
	ds_write_b16 v35, v121 offset:28512
	ds_write_b16_d16_hi v35, v121 offset:28656
	s_waitcnt lgkmcnt(0)
	s_barrier
	s_xor_b64 s[10:11], s[12:13], -1
	s_and_b64 vcc, exec, s[10:11]
	s_cbranch_vccnz .LBB0_526
	global_load_dwordx4 v[106:109], v[160:161], off offset:2048 sc1
	global_load_dwordx4 v[110:113], v[162:163], off offset:2304 sc1
.LBB0_526:
	s_andn2_b64 vcc, exec, s[12:13]
	s_cbranch_vccnz .LBB0_523
	global_load_dwordx4 v[114:117], v[166:167], off offset:2048 sc1
	global_load_dwordx4 v[118:121], v[168:169], off offset:2304 sc1
	s_branch .LBB0_523

.LBB0_530:
	s_andn2_b64 vcc, exec, s[8:9]
	s_cbranch_vccnz .LBB0_387
	s_and_b32 s8, s31, 63
	s_bfe_u32 s11, s31, 0x10006
	s_ashr_i32 s16, s31, 7
	s_lshl_b32 s9, s11, 2
	s_lshl_b32 s34, s16, 12
	v_sub_u32_e64 v0, s8, 2 clamp
	s_add_i32 s10, s9, s25
	v_readfirstlane_b32 s35, v0
	s_min_u32 s9, s8, 61
	v_lshl_or_b32 v0, s8, 6, v157
	s_or_b32 s8, s34, s26
	v_or_b32_e32 v98, s8, v0
	v_mov_b64_e32 v[2:3], s[38:39]
	s_sub_i32 s36, s9, s35
	v_mad_i64_i32 v[2:3], s[8:9], v98, s91, v[2:3]
	s_lshl_b32 s8, s10, 6
	s_ashr_i32 s9, s8, 31
	v_lshl_add_u64 v[2:3], s[8:9], 1, v[2:3]
	v_lshlrev_b32_e32 v0, 1, v150
	v_lshl_add_u64 v[2:3], v[2:3], 0, v[0:1]
	global_load_dwordx4 v[66:69], v[2:3], off offset:1024 sc1
	global_load_dwordx4 v[70:73], v[2:3], off offset:1056 sc1
	global_load_dwordx4 v[74:77], v[2:3], off offset:1088 sc1
	global_load_dwordx4 v[78:81], v[2:3], off offset:1120 sc1
	s_add_i32 s36, s36, 3
	s_cmp_lt_i32 s36, 1
	s_cselect_b64 s[12:13], -1, 0
	s_mov_b64 s[14:15], -1
	s_and_b64 vcc, exec, s[12:13]
	s_cbranch_vccz .LBB0_533
	s_lshl_b32 s14, s16, 8
	s_lshl_b32 s15, s36, 6
	s_sub_i32 s14, s14, s15
	s_add_i32 s17, s14, 0x4000
	s_mov_b64 s[14:15], 0

.LBB0_535:
	v_add_u32_e32 v0, s17, v236
	v_mov_b64_e32 v[2:3], s[38:39]
	v_mad_i64_i32 v[2:3], s[14:15], v0, s91, v[2:3]
	s_lshl_b32 s96, s11, 7
	v_lshl_add_u64 v[2:3], v[2:3], 0, s[96:97]
	v_lshlrev_b32_e32 v0, 1, v152
	v_lshl_add_u64 v[2:3], v[2:3], 0, v[0:1]
	global_load_dwordx4 v[82:85], v[2:3], off offset:2048 sc1
	s_mov_b64 s[14:15], -1
	s_and_b64 vcc, exec, s[12:13]
	s_cbranch_vccz .LBB0_537
	s_lshl_b32 s12, s16, 8
	s_lshl_b32 s13, s36, 6
	s_sub_i32 s12, s12, s13
	s_addk_i32 s12, 0x4000
	s_mov_b64 s[14:15], 0

.LBB0_539:
	s_lshl_b32 s11, s11, 6
	v_add_u32_e32 v4, s12, v151
	v_mov_b64_e32 v[2:3], s[38:39]
	v_mad_i64_i32 v[2:3], s[12:13], v4, s91, v[2:3]
	s_lshl_b32 s96, s11, 1
	v_lshl_add_u64 v[2:3], v[2:3], 0, s[96:97]
	v_lshl_add_u64 v[2:3], s[42:43], 1, v[2:3]
	global_load_dwordx4 v[86:89], v[2:3], off offset:2304 sc1
	s_cmp_lt_i32 s36, 2
	s_cselect_b64 s[12:13], -1, 0
	s_mov_b64 s[14:15], -1
	s_and_b64 vcc, exec, s[12:13]
	s_cbranch_vccz .LBB0_541
	s_lshl_b32 s11, s16, 8
	s_lshl_b32 s14, s36, 6
	s_sub_i32 s11, s11, s14
	s_addk_i32 s11, 0x4040
	s_mov_b64 s[14:15], 0

.LBB0_543:
	v_add_u32_e32 v4, s11, v236
	v_mov_b64_e32 v[2:3], s[38:39]
	v_mad_i64_i32 v[2:3], s[14:15], v4, s91, v[2:3]
	v_lshl_add_u64 v[2:3], v[2:3], 0, s[96:97]
	v_lshl_add_u64 v[2:3], v[2:3], 0, v[0:1]
	global_load_dwordx4 v[90:93], v[2:3], off offset:2048 sc1
	s_mov_b64 s[14:15], -1
	s_and_b64 vcc, exec, s[12:13]
	s_cbranch_vccz .LBB0_545
	s_lshl_b32 s11, s16, 8
	s_lshl_b32 s12, s36, 6
	s_sub_i32 s11, s11, s12
	s_add_i32 s17, s11, 0x4040
	s_cbranch_execnz .LBB0_547
	s_branch .LBB0_546

.LBB0_549:
	v_mov_b32_e32 v17, 0
	s_andn2_b64 vcc, exec, s[12:13]
	v_mov_b32_e32 v16, v17
	v_mov_b32_e32 v15, v17
	v_mov_b32_e32 v14, v17
	v_mov_b32_e32 v13, v17
	v_mov_b32_e32 v12, v17
	v_mov_b32_e32 v11, v17
	v_mov_b32_e32 v10, v17
	v_mov_b32_e32 v9, v17
	v_mov_b32_e32 v8, v17
	v_mov_b32_e32 v7, v17
	v_mov_b32_e32 v6, v17
	v_mov_b32_e32 v5, v17
	v_mov_b32_e32 v4, v17
	v_mov_b32_e32 v3, v17
	v_mov_b32_e32 v2, v17
	v_mov_b32_e32 v33, v17
	v_mov_b32_e32 v32, v17
	v_mov_b32_e32 v31, v17
	v_mov_b32_e32 v30, v17
	v_mov_b32_e32 v29, v17
	v_mov_b32_e32 v28, v17
	v_mov_b32_e32 v27, v17
	v_mov_b32_e32 v26, v17
	v_mov_b32_e32 v25, v17
	v_mov_b32_e32 v24, v17
	v_mov_b32_e32 v23, v17
	v_mov_b32_e32 v22, v17
	v_mov_b32_e32 v21, v17
	v_mov_b32_e32 v20, v17
	v_mov_b32_e32 v19, v17
	v_mov_b32_e32 v18, v17
	s_waitcnt vmcnt(0)
	v_mov_b32_e32 v106, v237
	s_cbranch_vccnz .LBB0_386
	s_and_b32 s11, s30, 63
	s_min_u32 s11, s11, 2
	s_lshl_b32 s12, s11, 6
	s_sub_i32 s44, 0, s11
	s_ashr_i32 s11, s10, 31
	s_add_i32 s37, s36, 4
	s_lshl_b64 s[10:11], s[10:11], 2
	s_add_u32 s10, s23, s10
	s_addc_u32 s11, s24, s11
	v_add_u32_e32 v4, s17, v151
	v_mov_b64_e32 v[2:3], s[38:39]
	global_load_dword v0, v1, s[10:11] sc1
	v_mad_i64_i32 v[2:3], s[10:11], v4, s91, v[2:3]
	v_lshl_add_u64 v[2:3], v[2:3], 0, s[96:97]
	v_lshl_add_u64 v[2:3], s[42:43], 1, v[2:3]
	global_load_dwordx4 v[94:97], v[2:3], off offset:2304 sc1
	s_lshl_b32 s49, s16, 8
	s_sub_i32 s47, 0, s36
	s_addk_i32 s49, 0x4000
	v_mov_b32_e32 v2, 0
	s_add_u32 s10, s28, s96
	s_mov_b32 s52, 0
	v_lshl_add_u64 v[100:101], v[158:159], 0, s[96:97]
	v_mov_b32_e32 v111, v237
	s_mov_b32 s45, 0
	v_mov_b32_e32 v3, v2
	v_mov_b32_e32 v4, v2
	v_mov_b32_e32 v5, v2
	v_mov_b32_e32 v6, v2
	v_mov_b32_e32 v7, v2
	v_mov_b32_e32 v8, v2
	v_mov_b32_e32 v9, v2
	v_mov_b32_e32 v10, v2
	v_mov_b32_e32 v11, v2
	v_mov_b32_e32 v12, v2
	v_mov_b32_e32 v13, v2
	v_mov_b32_e32 v14, v2
	v_mov_b32_e32 v15, v2
	v_mov_b32_e32 v16, v2
	v_mov_b32_e32 v17, v2
	v_mov_b32_e32 v18, v2
	v_mov_b32_e32 v19, v2
	v_mov_b32_e32 v20, v2
	v_mov_b32_e32 v21, v2
	v_mov_b32_e32 v22, v2
	v_mov_b32_e32 v23, v2
	v_mov_b32_e32 v24, v2
	v_mov_b32_e32 v25, v2
	v_mov_b32_e32 v26, v2
	v_mov_b32_e32 v27, v2
	v_mov_b32_e32 v28, v2
	v_mov_b32_e32 v29, v2
	v_mov_b32_e32 v30, v2
	v_mov_b32_e32 v31, v2
	v_mov_b32_e32 v32, v2
	v_subrev_u32_e32 v99, s12, v155
	s_addc_u32 s11, s29, 0
	v_mov_b32_e32 v33, v2
	s_waitcnt vmcnt(1)
	v_mul_f32_e32 v0, 0x3fb8aa3b, v0

.LBB0_553:
	s_add_i32 s51, s52, 2
	s_waitcnt lgkmcnt(0)
	s_barrier
	s_cmp_ge_i32 s51, s37
	s_cselect_b64 s[12:13], -1, 0
	s_and_b64 vcc, exec, s[12:13]
	s_cbranch_vccnz .LBB0_555
	s_cmp_lt_i32 s51, s36
	s_cselect_b32 s17, s35, s47
	s_cselect_b32 s18, s34, s49
	s_add_i32 s17, s17, s52
	s_lshl_b32 s17, s17, 6
	s_add_i32 s17, s17, s18
	s_addk_i32 s17, 0x80
	v_add_u32_e32 v34, s17, v236
	v_mad_i64_i32 v[34:35], s[18:19], v34, s91, v[100:101]
	v_or_b32_e32 v38, s17, v151
	v_mov_b64_e32 v[36:37], s[10:11]
	v_mad_i64_i32 v[36:37], s[18:19], v38, s91, v[36:37]
	global_load_dwordx4 v[82:85], v[34:35], off offset:2048 sc1
	global_load_dwordx4 v[86:89], v[36:37], off offset:2304 sc1
.LBB0_555:
	s_add_i32 s17, s52, 3
	s_cmp_ge_i32 s17, s37
	s_cbranch_scc1 .LBB0_557
	s_cmp_lt_i32 s17, s36
	s_cselect_b32 s17, s35, s47
	s_cselect_b32 s18, s34, s49
	s_add_i32 s17, s17, s52
	s_lshl_b32 s17, s17, 6
	s_add_i32 s17, s17, s18
	s_addk_i32 s17, 0xc0
	v_add_u32_e32 v34, s17, v236
	v_mad_i64_i32 v[34:35], s[18:19], v34, s91, v[100:101]
	v_or_b32_e32 v38, s17, v151
	v_mov_b64_e32 v[36:37], s[10:11]
	v_mad_i64_i32 v[36:37], s[18:19], v38, s91, v[36:37]
	global_load_dwordx4 v[90:93], v[34:35], off offset:2048 sc1
	global_load_dwordx4 v[94:97], v[36:37], off offset:2304 sc1

.LBB0_584:
	s_ashr_i32 s17, s20, 6
	s_add_i32 s17, s17, s92
	v_readlane_b32 s18, v249, 49
	s_mul_i32 s19, s18, s17
	s_add_i32 s18, s19, s18
	s_min_i32 s23, s19, 0x4000
	s_cmp_lt_i32 s18, s23
	s_cbranch_scc1 .LBB0_605
	s_min_i32 s22, s18, 0x4000
	s_and_b64 s[6:7], s[6:7], exec
	s_movk_i32 s6, 0xc00
	s_cselect_b32 s18, s6, 0x1800
	s_and_b64 s[6:7], s[28:29], exec
	s_cselect_b32 s6, 0x2d000, 0
	s_waitcnt lgkmcnt(0)
	s_add_u32 s6, s8, s6
	s_addc_u32 s7, s9, 0
	s_and_b64 s[4:5], s[4:5], exec
	s_cselect_b32 s4, 0, s18
	s_lshl_b32 s4, s4, 2
	s_add_u32 s18, s6, s4
	s_addc_u32 s19, s7, 0
	s_and_b64 s[4:5], s[28:29], exec
	s_cselect_b32 s4, 0x1000, 0
	s_cmp_eq_u32 s3, 17
	s_movk_i32 s5, 0x4400
	s_cselect_b32 s24, 0x4000, s5
	s_add_i32 s6, s24, 0xffffc000
	s_add_u32 s14, s14, s4
	s_addc_u32 s15, s15, 0
	s_add_i32 s25, s17, 0x4000
	v_lshlrev_b32_e32 v0, 2, v2
	s_cmp_lg_u64 s[10:11], 0
	v_and_b32_e32 v3, 0xfc, v0
	s_cselect_b64 s[4:5], -1, 0
	s_cmp_lg_u32 s16, 0
	v_lshlrev_b32_e32 v0, 1, v3
	s_cselect_b64 s[20:21], -1, 0
	s_cmp_lt_i32 s17, s6
	v_lshl_add_u64 v[4:5], s[8:9], 0, v[0:1]
	v_lshl_add_u64 v[58:59], s[12:13], 0, v[0:1]
	v_and_b32_e32 v0, 63, v2
	s_cselect_b64 s[6:7], -1, 0
	s_mov_b64 s[8:9], 0x9000000
	s_and_b32 s26, s16, 3
	v_lshlrev_b32_e32 v0, 3, v0
	v_lshl_add_u64 v[50:51], v[4:5], 0, s[8:9]
	v_lshlrev_b32_e32 v6, 2, v3
	v_mov_b32_e32 v7, v1
	s_mov_b64 s[8:9], 0x4c00000
	s_cmp_gt_u32 s16, 3
	v_lshl_add_u64 v[2:3], s[12:13], 0, v[0:1]
	s_mov_b64 s[12:13], 0x400
	v_lshl_add_u64 v[52:53], s[14:15], 0, v[6:7]
	v_lshl_add_u64 v[54:55], v[4:5], 0, s[8:9]
	v_lshl_add_u64 v[56:57], s[10:11], 0, v[6:7]
	s_cselect_b64 s[8:9], -1, 0
	s_cmp_lg_u32 s26, 0
	v_lshl_add_u64 v[60:61], s[18:19], 0, v[6:7]
	s_mov_b64 s[14:15], 0x1000
	v_lshl_add_u64 v[64:65], v[2:3], 0, s[12:13]
	v_mov_b32_e32 v2, v1
	v_mov_b32_e32 v3, v1
	v_mov_b32_e32 v4, v1
	v_mov_b32_e32 v5, v1
	v_mov_b32_e32 v6, v1
	v_mov_b32_e32 v8, v1
	v_mov_b32_e32 v9, v1
	v_mov_b32_e32 v10, v1
	v_mov_b32_e32 v11, v1
	v_mov_b32_e32 v12, v1
	v_mov_b32_e32 v13, v1
	v_mov_b32_e32 v14, v1
	v_mov_b32_e32 v15, v1
	s_cselect_b64 s[10:11], -1, 0
	v_lshl_add_u64 v[62:63], v[60:61], 0, s[14:15]
	s_lshl_b32 s14, s16, 21
	v_mov_b32_e32 v0, v1
	v_mov_b64_e32 v[16:17], v[14:15]
	s_and_b32 s27, s14, 0x1800000
	s_mov_b32 s28, -1
	s_xor_b64 s[12:13], s[20:21], -1
	v_mov_b64_e32 v[14:15], v[12:13]
	v_mov_b64_e32 v[12:13], v[10:11]
	v_mov_b64_e32 v[10:11], v[8:9]
	v_mov_b64_e32 v[8:9], v[6:7]
	v_mov_b64_e32 v[6:7], v[4:5]
	v_mov_b64_e32 v[4:5], v[2:3]
	v_mov_b64_e32 v[2:3], v[0:1]
	s_and_b64 vcc, exec, s[4:5]
	s_cbranch_vccnz .Lnf_skip
	s_sub_i32 vcc_lo, s22, s23
	s_cmp_lg_u32 vcc_lo, 8
	s_cbranch_scc1 .Lnf_skip
	s_lshr_b32 vcc_lo, s23, 12
	s_add_i32 vcc_hi, s22, -1
	s_lshr_b32 vcc_hi, vcc_hi, 12
	s_cmp_lg_u32 vcc_lo, vcc_hi
	s_cbranch_scc1 .Lnf_skip
	s_mul_i32 vcc_lo, vcc_lo, 0x9000
	s_mov_b32 vcc_hi, 0
	v_and_b32_e32 v114, 63, v224
	v_mov_b32_e32 v115, 0
	v_mov_b32_e32 v117, 0
	v_lshlrev_b32_e32 v116, 4, v114
	v_lshlrev_b32_e32 v114, 3, v114
	v_lshl_add_u64 v[118:119], v[52:53], 0, v[116:117]
	v_lshl_add_u64 v[120:121], v[62:63], 0, v[116:117]
	v_lshl_add_u64 v[194:195], v[60:61], 0, v[116:117]
	v_lshl_add_u64 v[120:121], v[120:121], 0, vcc
	v_lshl_add_u64 v[194:195], v[194:195], 0, vcc
	global_load_dwordx4 v[66:69], v[118:119], off sc1
	global_load_dwordx4 v[70:73], v[118:119], off offset:16 sc1
	global_load_dwordx4 v[74:77], v[118:119], off offset:2048 sc1
	global_load_dwordx4 v[78:81], v[118:119], off offset:2064 sc1
	global_load_dwordx4 v[82:85], v[120:121], off sc1
	global_load_dwordx4 v[86:89], v[120:121], off offset:16 sc1
	global_load_dwordx4 v[90:93], v[120:121], off offset:2048 sc1
	global_load_dwordx4 v[94:97], v[120:121], off offset:2064 sc1
	global_load_dwordx4 v[98:101], v[194:195], off sc1
	global_load_dwordx4 v[102:105], v[194:195], off offset:16 sc1
	global_load_dwordx4 v[106:109], v[194:195], off offset:2048 sc1
	global_load_dwordx4 v[110:113], v[194:195], off offset:2064 sc1
	s_mov_b32 vcc_lo, s23
	s_lshl_b64 vcc, vcc, 11
	v_lshl_add_u64 v[186:187], v[54:55], 0, v[114:115]
	v_lshl_add_u64 v[186:187], v[186:187], 0, vcc
	s_mov_b64 vcc, 0x1000
	v_lshl_add_u64 v[188:189], v[186:187], 0, vcc
	v_lshl_add_u64 v[190:191], v[188:189], 0, vcc
	v_lshl_add_u64 v[192:193], v[190:191], 0, vcc
	global_load_dwordx4 v[122:125], v[186:187], off sc1
	global_load_dwordx4 v[126:129], v[186:187], off offset:1024 sc1
	global_load_dwordx4 v[130:133], v[186:187], off offset:2048 sc1
	global_load_dwordx4 v[134:137], v[186:187], off offset:3072 sc1
	global_load_dwordx4 v[138:141], v[188:189], off sc1
	global_load_dwordx4 v[142:145], v[188:189], off offset:1024 sc1
	global_load_dwordx4 v[146:149], v[188:189], off offset:2048 sc1
	global_load_dwordx4 v[150:153], v[188:189], off offset:3072 sc1
	global_load_dwordx4 v[154:157], v[190:191], off sc1
	global_load_dwordx4 v[158:161], v[190:191], off offset:1024 sc1
	global_load_dwordx4 v[162:165], v[190:191], off offset:2048 sc1
	global_load_dwordx4 v[166:169], v[190:191], off offset:3072 sc1
	global_load_dwordx4 v[170:173], v[192:193], off sc1
	global_load_dwordx4 v[174:177], v[192:193], off offset:1024 sc1
	global_load_dwordx4 v[178:181], v[192:193], off offset:2048 sc1
	global_load_dwordx4 v[182:185], v[192:193], off offset:3072 sc1
	v_mov_b32_e32 v220, 0x3a800000
	v_mov_b32_e32 v221, 0x358637bd
	s_mov_b64 vcc, 0x4400000
	v_lshl_add_u64 v[186:187], v[186:187], 0, vcc
	v_lshl_add_u64 v[188:189], v[188:189], 0, vcc
	v_lshl_add_u64 v[190:191], v[190:191], 0, vcc
	v_lshl_add_u64 v[192:193], v[192:193], 0, vcc
	s_waitcnt vmcnt(16)
	v_pk_add_f32 v[82:83], v[82:83], 1.0 op_sel_hi:[1,0]
	v_pk_add_f32 v[84:85], v[84:85], 1.0 op_sel_hi:[1,0]
	v_pk_add_f32 v[86:87], v[86:87], 1.0 op_sel_hi:[1,0]
	v_pk_add_f32 v[88:89], v[88:89], 1.0 op_sel_hi:[1,0]
	v_pk_add_f32 v[90:91], v[90:91], 1.0 op_sel_hi:[1,0]
	v_pk_add_f32 v[92:93], v[92:93], 1.0 op_sel_hi:[1,0]
	v_pk_add_f32 v[94:95], v[94:95], 1.0 op_sel_hi:[1,0]
	v_pk_add_f32 v[96:97], v[96:97], 1.0 op_sel_hi:[1,0]
	v_pk_mul_f32 v[66:67], v[66:67], v[82:83]
	v_pk_mul_f32 v[68:69], v[68:69], v[84:85]
	v_pk_mul_f32 v[70:71], v[70:71], v[86:87]
	v_pk_mul_f32 v[72:73], v[72:73], v[88:89]
	v_pk_mul_f32 v[74:75], v[74:75], v[90:91]
	v_pk_mul_f32 v[76:77], v[76:77], v[92:93]
	v_pk_mul_f32 v[78:79], v[78:79], v[94:95]
	v_pk_mul_f32 v[80:81], v[80:81], v[96:97]
	s_waitcnt vmcnt(14)
	v_lshlrev_b32_e32 v212, 16, v122
	v_and_b32_e32 v213, 0xffff0000, v122
	v_mul_f32_e32 v82, v212, v212
	v_mul_f32_e32 v83, v213, v213
	v_lshlrev_b32_e32 v214, 16, v123
	v_and_b32_e32 v215, 0xffff0000, v123
	v_fmac_f32_e32 v82, v214, v214
	v_fmac_f32_e32 v83, v215, v215
	v_lshlrev_b32_e32 v216, 16, v124
	v_and_b32_e32 v217, 0xffff0000, v124
	v_fmac_f32_e32 v82, v216, v216
	v_fmac_f32_e32 v83, v217, v217
	v_lshlrev_b32_e32 v218, 16, v125
	v_and_b32_e32 v219, 0xffff0000, v125
	v_fmac_f32_e32 v82, v218, v218
	v_fmac_f32_e32 v83, v219, v219
	v_lshlrev_b32_e32 v212, 16, v126
	v_and_b32_e32 v213, 0xffff0000, v126
	v_fmac_f32_e32 v82, v212, v212
	v_fmac_f32_e32 v83, v213, v213
	v_lshlrev_b32_e32 v214, 16, v127
	v_and_b32_e32 v215, 0xffff0000, v127
	v_fmac_f32_e32 v82, v214, v214
	v_fmac_f32_e32 v83, v215, v215
	v_lshlrev_b32_e32 v216, 16, v128
	v_and_b32_e32 v217, 0xffff0000, v128
	v_fmac_f32_e32 v82, v216, v216
	v_fmac_f32_e32 v83, v217, v217
	v_lshlrev_b32_e32 v218, 16, v129
	v_and_b32_e32 v219, 0xffff0000, v129
	v_fmac_f32_e32 v82, v218, v218
	v_fmac_f32_e32 v83, v219, v219
	s_waitcnt vmcnt(12)
	v_lshlrev_b32_e32 v212, 16, v130
	v_and_b32_e32 v213, 0xffff0000, v130
	v_mul_f32_e32 v84, v212, v212
	v_mul_f32_e32 v85, v213, v213
	v_lshlrev_b32_e32 v214, 16, v131
	v_and_b32_e32 v215, 0xffff0000, v131
	v_fmac_f32_e32 v84, v214, v214
	v_fmac_f32_e32 v85, v215, v215
	v_lshlrev_b32_e32 v216, 16, v132
	v_and_b32_e32 v217, 0xffff0000, v132
	v_fmac_f32_e32 v84, v216, v216
	v_fmac_f32_e32 v85, v217, v217
	v_lshlrev_b32_e32 v218, 16, v133
	v_and_b32_e32 v219, 0xffff0000, v133
	v_fmac_f32_e32 v84, v218, v218
	v_fmac_f32_e32 v85, v219, v219
	v_lshlrev_b32_e32 v212, 16, v134
	v_and_b32_e32 v213, 0xffff0000, v134
	v_fmac_f32_e32 v84, v212, v212
	v_fmac_f32_e32 v85, v213, v213
	v_lshlrev_b32_e32 v214, 16, v135
	v_and_b32_e32 v215, 0xffff0000, v135
	v_fmac_f32_e32 v84, v214, v214
	v_fmac_f32_e32 v85, v215, v215
	v_lshlrev_b32_e32 v216, 16, v136
	v_and_b32_e32 v217, 0xffff0000, v136
	v_fmac_f32_e32 v84, v216, v216
	v_fmac_f32_e32 v85, v217, v217
	v_lshlrev_b32_e32 v218, 16, v137
	v_and_b32_e32 v219, 0xffff0000, v137
	v_fmac_f32_e32 v84, v218, v218
	v_fmac_f32_e32 v85, v219, v219
	s_waitcnt vmcnt(10)
	v_lshlrev_b32_e32 v212, 16, v138
	v_and_b32_e32 v213, 0xffff0000, v138
	v_mul_f32_e32 v86, v212, v212
	v_mul_f32_e32 v87, v213, v213
	v_lshlrev_b32_e32 v214, 16, v139
	v_and_b32_e32 v215, 0xffff0000, v139
	v_fmac_f32_e32 v86, v214, v214
	v_fmac_f32_e32 v87, v215, v215
	v_lshlrev_b32_e32 v216, 16, v140
	v_and_b32_e32 v217, 0xffff0000, v140
	v_fmac_f32_e32 v86, v216, v216
	v_fmac_f32_e32 v87, v217, v217
	v_lshlrev_b32_e32 v218, 16, v141
	v_and_b32_e32 v219, 0xffff0000, v141
	v_fmac_f32_e32 v86, v218, v218
	v_fmac_f32_e32 v87, v219, v219
	v_lshlrev_b32_e32 v212, 16, v142
	v_and_b32_e32 v213, 0xffff0000, v142
	v_fmac_f32_e32 v86, v212, v212
	v_fmac_f32_e32 v87, v213, v213
	v_lshlrev_b32_e32 v214, 16, v143
	v_and_b32_e32 v215, 0xffff0000, v143
	v_fmac_f32_e32 v86, v214, v214
	v_fmac_f32_e32 v87, v215, v215
	v_lshlrev_b32_e32 v216, 16, v144
	v_and_b32_e32 v217, 0xffff0000, v144
	v_fmac_f32_e32 v86, v216, v216
	v_fmac_f32_e32 v87, v217, v217
	v_lshlrev_b32_e32 v218, 16, v145
	v_and_b32_e32 v219, 0xffff0000, v145
	v_fmac_f32_e32 v86, v218, v218
	v_fmac_f32_e32 v87, v219, v219
	s_waitcnt vmcnt(8)
	v_lshlrev_b32_e32 v212, 16, v146
	v_and_b32_e32 v213, 0xffff0000, v146
	v_mul_f32_e32 v88, v212, v212
	v_mul_f32_e32 v89, v213, v213
	v_lshlrev_b32_e32 v214, 16, v147
	v_and_b32_e32 v215, 0xffff0000, v147
	v_fmac_f32_e32 v88, v214, v214
	v_fmac_f32_e32 v89, v215, v215
	v_lshlrev_b32_e32 v216, 16, v148
	v_and_b32_e32 v217, 0xffff0000, v148
	v_fmac_f32_e32 v88, v216, v216
	v_fmac_f32_e32 v89, v217, v217
	v_lshlrev_b32_e32 v218, 16, v149
	v_and_b32_e32 v219, 0xffff0000, v149
	v_fmac_f32_e32 v88, v218, v218
	v_fmac_f32_e32 v89, v219, v219
	v_lshlrev_b32_e32 v212, 16, v150
	v_and_b32_e32 v213, 0xffff0000, v150
	v_fmac_f32_e32 v88, v212, v212
	v_fmac_f32_e32 v89, v213, v213
	v_lshlrev_b32_e32 v214, 16, v151
	v_and_b32_e32 v215, 0xffff0000, v151
	v_fmac_f32_e32 v88, v214, v214
	v_fmac_f32_e32 v89, v215, v215
	v_lshlrev_b32_e32 v216, 16, v152
	v_and_b32_e32 v217, 0xffff0000, v152
	v_fmac_f32_e32 v88, v216, v216
	v_fmac_f32_e32 v89, v217, v217
	v_lshlrev_b32_e32 v218, 16, v153
	v_and_b32_e32 v219, 0xffff0000, v153
	v_fmac_f32_e32 v88, v218, v218
	v_fmac_f32_e32 v89, v219, v219
	s_waitcnt vmcnt(6)
	v_lshlrev_b32_e32 v212, 16, v154
	v_and_b32_e32 v213, 0xffff0000, v154
	v_mul_f32_e32 v90, v212, v212
	v_mul_f32_e32 v91, v213, v213
	v_lshlrev_b32_e32 v214, 16, v155
	v_and_b32_e32 v215, 0xffff0000, v155
	v_fmac_f32_e32 v90, v214, v214
	v_fmac_f32_e32 v91, v215, v215
	v_lshlrev_b32_e32 v216, 16, v156
	v_and_b32_e32 v217, 0xffff0000, v156
	v_fmac_f32_e32 v90, v216, v216
	v_fmac_f32_e32 v91, v217, v217
	v_lshlrev_b32_e32 v218, 16, v157
	v_and_b32_e32 v219, 0xffff0000, v157
	v_fmac_f32_e32 v90, v218, v218
	v_fmac_f32_e32 v91, v219, v219
	v_lshlrev_b32_e32 v212, 16, v158
	v_and_b32_e32 v213, 0xffff0000, v158
	v_fmac_f32_e32 v90, v212, v212
	v_fmac_f32_e32 v91, v213, v213
	v_lshlrev_b32_e32 v214, 16, v159
	v_and_b32_e32 v215, 0xffff0000, v159
	v_fmac_f32_e32 v90, v214, v214
	v_fmac_f32_e32 v91, v215, v215
	v_lshlrev_b32_e32 v216, 16, v160
	v_and_b32_e32 v217, 0xffff0000, v160
	v_fmac_f32_e32 v90, v216, v216
	v_fmac_f32_e32 v91, v217, v217
	v_lshlrev_b32_e32 v218, 16, v161
	v_and_b32_e32 v219, 0xffff0000, v161
	v_fmac_f32_e32 v90, v218, v218
	v_fmac_f32_e32 v91, v219, v219
	s_waitcnt vmcnt(4)
	v_lshlrev_b32_e32 v212, 16, v162
	v_and_b32_e32 v213, 0xffff0000, v162
	v_mul_f32_e32 v92, v212, v212
	v_mul_f32_e32 v93, v213, v213
	v_lshlrev_b32_e32 v214, 16, v163
	v_and_b32_e32 v215, 0xffff0000, v163
	v_fmac_f32_e32 v92, v214, v214
	v_fmac_f32_e32 v93, v215, v215
	v_lshlrev_b32_e32 v216, 16, v164
	v_and_b32_e32 v217, 0xffff0000, v164
	v_fmac_f32_e32 v92, v216, v216
	v_fmac_f32_e32 v93, v217, v217
	v_lshlrev_b32_e32 v218, 16, v165
	v_and_b32_e32 v219, 0xffff0000, v165
	v_fmac_f32_e32 v92, v218, v218
	v_fmac_f32_e32 v93, v219, v219
	v_lshlrev_b32_e32 v212, 16, v166
	v_and_b32_e32 v213, 0xffff0000, v166
	v_fmac_f32_e32 v92, v212, v212
	v_fmac_f32_e32 v93, v213, v213
	v_lshlrev_b32_e32 v214, 16, v167
	v_and_b32_e32 v215, 0xffff0000, v167
	v_fmac_f32_e32 v92, v214, v214
	v_fmac_f32_e32 v93, v215, v215
	v_lshlrev_b32_e32 v216, 16, v168
	v_and_b32_e32 v217, 0xffff0000, v168
	v_fmac_f32_e32 v92, v216, v216
	v_fmac_f32_e32 v93, v217, v217
	v_lshlrev_b32_e32 v218, 16, v169
	v_and_b32_e32 v219, 0xffff0000, v169
	v_fmac_f32_e32 v92, v218, v218
	v_fmac_f32_e32 v93, v219, v219
	s_waitcnt vmcnt(2)
	v_lshlrev_b32_e32 v212, 16, v170
	v_and_b32_e32 v213, 0xffff0000, v170
	v_mul_f32_e32 v94, v212, v212
	v_mul_f32_e32 v95, v213, v213
	v_lshlrev_b32_e32 v214, 16, v171
	v_and_b32_e32 v215, 0xffff0000, v171
	v_fmac_f32_e32 v94, v214, v214
	v_fmac_f32_e32 v95, v215, v215
	v_lshlrev_b32_e32 v216, 16, v172
	v_and_b32_e32 v217, 0xffff0000, v172
	v_fmac_f32_e32 v94, v216, v216
	v_fmac_f32_e32 v95, v217, v217
	v_lshlrev_b32_e32 v218, 16, v173
	v_and_b32_e32 v219, 0xffff0000, v173
	v_fmac_f32_e32 v94, v218, v218
	v_fmac_f32_e32 v95, v219, v219
	v_lshlrev_b32_e32 v212, 16, v174
	v_and_b32_e32 v213, 0xffff0000, v174
	v_fmac_f32_e32 v94, v212, v212
	v_fmac_f32_e32 v95, v213, v213
	v_lshlrev_b32_e32 v214, 16, v175
	v_and_b32_e32 v215, 0xffff0000, v175
	v_fmac_f32_e32 v94, v214, v214
	v_fmac_f32_e32 v95, v215, v215
	v_lshlrev_b32_e32 v216, 16, v176
	v_and_b32_e32 v217, 0xffff0000, v176
	v_fmac_f32_e32 v94, v216, v216
	v_fmac_f32_e32 v95, v217, v217
	v_lshlrev_b32_e32 v218, 16, v177
	v_and_b32_e32 v219, 0xffff0000, v177
	v_fmac_f32_e32 v94, v218, v218
	v_fmac_f32_e32 v95, v219, v219
	s_waitcnt vmcnt(0)
	v_lshlrev_b32_e32 v212, 16, v178
	v_and_b32_e32 v213, 0xffff0000, v178
	v_mul_f32_e32 v96, v212, v212
	v_mul_f32_e32 v97, v213, v213
	v_lshlrev_b32_e32 v214, 16, v179
	v_and_b32_e32 v215, 0xffff0000, v179
	v_fmac_f32_e32 v96, v214, v214
	v_fmac_f32_e32 v97, v215, v215
	v_lshlrev_b32_e32 v216, 16, v180
	v_and_b32_e32 v217, 0xffff0000, v180
	v_fmac_f32_e32 v96, v216, v216
	v_fmac_f32_e32 v97, v217, v217
	v_lshlrev_b32_e32 v218, 16, v181
	v_and_b32_e32 v219, 0xffff0000, v181
	v_fmac_f32_e32 v96, v218, v218
	v_fmac_f32_e32 v97, v219, v219
	v_lshlrev_b32_e32 v212, 16, v182
	v_and_b32_e32 v213, 0xffff0000, v182
	v_fmac_f32_e32 v96, v212, v212
	v_fmac_f32_e32 v97, v213, v213
	v_lshlrev_b32_e32 v214, 16, v183
	v_and_b32_e32 v215, 0xffff0000, v183
	v_fmac_f32_e32 v96, v214, v214
	v_fmac_f32_e32 v97, v215, v215
	v_lshlrev_b32_e32 v216, 16, v184
	v_and_b32_e32 v217, 0xffff0000, v184
	v_fmac_f32_e32 v96, v216, v216
	v_fmac_f32_e32 v97, v217, v217
	v_lshlrev_b32_e32 v218, 16, v185
	v_and_b32_e32 v219, 0xffff0000, v185
	v_fmac_f32_e32 v96, v218, v218
	v_fmac_f32_e32 v97, v219, v219
	v_add_f32_e32 v82, v82, v83
	v_add_f32_e32 v84, v84, v85
	v_add_f32_e32 v86, v86, v87
	v_add_f32_e32 v88, v88, v89
	v_add_f32_e32 v90, v90, v91
	v_add_f32_e32 v92, v92, v93
	v_add_f32_e32 v94, v94, v95
	v_add_f32_e32 v96, v96, v97
	v_add_f32_dpp v82, v82, v82 quad_perm:[1,0,3,2] row_mask:0xf bank_mask:0xf
	v_add_f32_dpp v84, v84, v84 quad_perm:[1,0,3,2] row_mask:0xf bank_mask:0xf
	v_add_f32_dpp v86, v86, v86 quad_perm:[1,0,3,2] row_mask:0xf bank_mask:0xf
	v_add_f32_dpp v88, v88, v88 quad_perm:[1,0,3,2] row_mask:0xf bank_mask:0xf
	v_add_f32_dpp v90, v90, v90 quad_perm:[1,0,3,2] row_mask:0xf bank_mask:0xf
	v_add_f32_dpp v92, v92, v92 quad_perm:[1,0,3,2] row_mask:0xf bank_mask:0xf
	v_add_f32_dpp v94, v94, v94 quad_perm:[1,0,3,2] row_mask:0xf bank_mask:0xf
	v_add_f32_dpp v96, v96, v96 quad_perm:[1,0,3,2] row_mask:0xf bank_mask:0xf
	v_add_f32_dpp v82, v82, v82 quad_perm:[2,3,0,1] row_mask:0xf bank_mask:0xf
	v_add_f32_dpp v84, v84, v84 quad_perm:[2,3,0,1] row_mask:0xf bank_mask:0xf
	v_add_f32_dpp v86, v86, v86 quad_perm:[2,3,0,1] row_mask:0xf bank_mask:0xf
	v_add_f32_dpp v88, v88, v88 quad_perm:[2,3,0,1] row_mask:0xf bank_mask:0xf
	v_add_f32_dpp v90, v90, v90 quad_perm:[2,3,0,1] row_mask:0xf bank_mask:0xf
	v_add_f32_dpp v92, v92, v92 quad_perm:[2,3,0,1] row_mask:0xf bank_mask:0xf
	v_add_f32_dpp v94, v94, v94 quad_perm:[2,3,0,1] row_mask:0xf bank_mask:0xf
	v_add_f32_dpp v96, v96, v96 quad_perm:[2,3,0,1] row_mask:0xf bank_mask:0xf
	v_add_f32_dpp v82, v82, v82 row_half_mirror row_mask:0xf bank_mask:0xf
	v_add_f32_dpp v84, v84, v84 row_half_mirror row_mask:0xf bank_mask:0xf
	v_add_f32_dpp v86, v86, v86 row_half_mirror row_mask:0xf bank_mask:0xf
	v_add_f32_dpp v88, v88, v88 row_half_mirror row_mask:0xf bank_mask:0xf
	v_add_f32_dpp v90, v90, v90 row_half_mirror row_mask:0xf bank_mask:0xf
	v_add_f32_dpp v92, v92, v92 row_half_mirror row_mask:0xf bank_mask:0xf
	v_add_f32_dpp v94, v94, v94 row_half_mirror row_mask:0xf bank_mask:0xf
	v_add_f32_dpp v96, v96, v96 row_half_mirror row_mask:0xf bank_mask:0xf
	v_add_f32_dpp v82, v82, v82 row_mirror row_mask:0xf bank_mask:0xf
	v_add_f32_dpp v84, v84, v84 row_mirror row_mask:0xf bank_mask:0xf
	v_add_f32_dpp v86, v86, v86 row_mirror row_mask:0xf bank_mask:0xf
	v_add_f32_dpp v88, v88, v88 row_mirror row_mask:0xf bank_mask:0xf
	v_add_f32_dpp v90, v90, v90 row_mirror row_mask:0xf bank_mask:0xf
	v_add_f32_dpp v92, v92, v92 row_mirror row_mask:0xf bank_mask:0xf
	v_add_f32_dpp v94, v94, v94 row_mirror row_mask:0xf bank_mask:0xf
	v_add_f32_dpp v96, v96, v96 row_mirror row_mask:0xf bank_mask:0xf
	v_add_f32_dpp v82, v82, v82 row_bcast:15 row_mask:0xa bank_mask:0xf
	v_add_f32_dpp v84, v84, v84 row_bcast:15 row_mask:0xa bank_mask:0xf
	v_add_f32_dpp v86, v86, v86 row_bcast:15 row_mask:0xa bank_mask:0xf
	v_add_f32_dpp v88, v88, v88 row_bcast:15 row_mask:0xa bank_mask:0xf
	v_add_f32_dpp v90, v90, v90 row_bcast:15 row_mask:0xa bank_mask:0xf
	v_add_f32_dpp v92, v92, v92 row_bcast:15 row_mask:0xa bank_mask:0xf
	v_add_f32_dpp v94, v94, v94 row_bcast:15 row_mask:0xa bank_mask:0xf
	v_add_f32_dpp v96, v96, v96 row_bcast:15 row_mask:0xa bank_mask:0xf
	v_add_f32_dpp v82, v82, v82 row_bcast:31 row_mask:0xc bank_mask:0xf
	v_add_f32_dpp v84, v84, v84 row_bcast:31 row_mask:0xc bank_mask:0xf
	v_add_f32_dpp v86, v86, v86 row_bcast:31 row_mask:0xc bank_mask:0xf
	v_add_f32_dpp v88, v88, v88 row_bcast:31 row_mask:0xc bank_mask:0xf
	v_add_f32_dpp v90, v90, v90 row_bcast:31 row_mask:0xc bank_mask:0xf
	v_add_f32_dpp v92, v92, v92 row_bcast:31 row_mask:0xc bank_mask:0xf
	v_add_f32_dpp v94, v94, v94 row_bcast:31 row_mask:0xc bank_mask:0xf
	v_add_f32_dpp v96, v96, v96 row_bcast:31 row_mask:0xc bank_mask:0xf
	v_readlane_b32 vcc_lo, v82, 63
	v_readlane_b32 vcc_hi, v84, 63
	s_nop 1
	v_fma_f32 v196, vcc_lo, v220, v221
	v_fma_f32 v198, vcc_hi, v220, v221
	s_nop 1
	v_readlane_b32 vcc_lo, v86, 63
	v_readlane_b32 vcc_hi, v88, 63
	s_nop 1
	v_fma_f32 v200, vcc_lo, v220, v221
	v_fma_f32 v202, vcc_hi, v220, v221
	s_nop 1
	v_readlane_b32 vcc_lo, v90, 63
	v_readlane_b32 vcc_hi, v92, 63
	s_nop 1
	v_fma_f32 v204, vcc_lo, v220, v221
	v_fma_f32 v206, vcc_hi, v220, v221
	s_nop 1
	v_readlane_b32 vcc_lo, v94, 63
	v_readlane_b32 vcc_hi, v96, 63
	s_nop 1
	v_fma_f32 v208, vcc_lo, v220, v221
	v_fma_f32 v210, vcc_hi, v220, v221
	s_nop 1
	v_rsq_f32_e32 v196, v196
	v_rsq_f32_e32 v198, v198
	v_rsq_f32_e32 v200, v200
	v_rsq_f32_e32 v202, v202
	v_rsq_f32_e32 v204, v204
	v_rsq_f32_e32 v206, v206
	v_rsq_f32_e32 v208, v208
	v_rsq_f32_e32 v210, v210
	s_nop 1
	v_lshlrev_b32_e32 v212, 16, v122
	v_and_b32_e32 v213, 0xffff0000, v122
	v_pk_mul_f32 v[212:213], v[212:213], v[196:197] op_sel_hi:[1,0]
	v_pk_fma_f32 v[212:213], v[212:213], v[66:67], v[98:99]
	v_cvt_pk_bf16_f32 v122, v212, v213
	v_lshlrev_b32_e32 v214, 16, v123
	v_and_b32_e32 v215, 0xffff0000, v123
	v_pk_mul_f32 v[214:215], v[214:215], v[196:197] op_sel_hi:[1,0]
	v_pk_fma_f32 v[214:215], v[214:215], v[68:69], v[100:101]
	v_cvt_pk_bf16_f32 v123, v214, v215
	v_lshlrev_b32_e32 v216, 16, v124
	v_and_b32_e32 v217, 0xffff0000, v124
	v_pk_mul_f32 v[216:217], v[216:217], v[196:197] op_sel_hi:[1,0]
	v_pk_fma_f32 v[216:217], v[216:217], v[70:71], v[102:103]
	v_cvt_pk_bf16_f32 v124, v216, v217
	v_lshlrev_b32_e32 v218, 16, v125
	v_and_b32_e32 v219, 0xffff0000, v125
	v_pk_mul_f32 v[218:219], v[218:219], v[196:197] op_sel_hi:[1,0]
	v_pk_fma_f32 v[218:219], v[218:219], v[72:73], v[104:105]
	v_cvt_pk_bf16_f32 v125, v218, v219
	v_lshlrev_b32_e32 v212, 16, v126
	v_and_b32_e32 v213, 0xffff0000, v126
	v_pk_mul_f32 v[212:213], v[212:213], v[196:197] op_sel_hi:[1,0]
	v_pk_fma_f32 v[212:213], v[212:213], v[74:75], v[106:107]
	v_cvt_pk_bf16_f32 v126, v212, v213
	v_lshlrev_b32_e32 v214, 16, v127
	v_and_b32_e32 v215, 0xffff0000, v127
	v_pk_mul_f32 v[214:215], v[214:215], v[196:197] op_sel_hi:[1,0]
	v_pk_fma_f32 v[214:215], v[214:215], v[76:77], v[108:109]
	v_cvt_pk_bf16_f32 v127, v214, v215
	v_lshlrev_b32_e32 v216, 16, v128
	v_and_b32_e32 v217, 0xffff0000, v128
	v_pk_mul_f32 v[216:217], v[216:217], v[196:197] op_sel_hi:[1,0]
	v_pk_fma_f32 v[216:217], v[216:217], v[78:79], v[110:111]
	v_cvt_pk_bf16_f32 v128, v216, v217
	v_lshlrev_b32_e32 v218, 16, v129
	v_and_b32_e32 v219, 0xffff0000, v129
	v_pk_mul_f32 v[218:219], v[218:219], v[196:197] op_sel_hi:[1,0]
	v_pk_fma_f32 v[218:219], v[218:219], v[80:81], v[112:113]
	v_cvt_pk_bf16_f32 v129, v218, v219
	global_store_dwordx4 v[186:187], v[122:125], off
	global_store_dwordx4 v[186:187], v[126:129], off offset:1024
	v_lshlrev_b32_e32 v212, 16, v130
	v_and_b32_e32 v213, 0xffff0000, v130
	v_pk_mul_f32 v[212:213], v[212:213], v[198:199] op_sel_hi:[1,0]
	v_pk_fma_f32 v[212:213], v[212:213], v[66:67], v[98:99]
	v_cvt_pk_bf16_f32 v130, v212, v213
	v_lshlrev_b32_e32 v214, 16, v131
	v_and_b32_e32 v215, 0xffff0000, v131
	v_pk_mul_f32 v[214:215], v[214:215], v[198:199] op_sel_hi:[1,0]
	v_pk_fma_f32 v[214:215], v[214:215], v[68:69], v[100:101]
	v_cvt_pk_bf16_f32 v131, v214, v215
	v_lshlrev_b32_e32 v216, 16, v132
	v_and_b32_e32 v217, 0xffff0000, v132
	v_pk_mul_f32 v[216:217], v[216:217], v[198:199] op_sel_hi:[1,0]
	v_pk_fma_f32 v[216:217], v[216:217], v[70:71], v[102:103]
	v_cvt_pk_bf16_f32 v132, v216, v217
	v_lshlrev_b32_e32 v218, 16, v133
	v_and_b32_e32 v219, 0xffff0000, v133
	v_pk_mul_f32 v[218:219], v[218:219], v[198:199] op_sel_hi:[1,0]
	v_pk_fma_f32 v[218:219], v[218:219], v[72:73], v[104:105]
	v_cvt_pk_bf16_f32 v133, v218, v219
	v_lshlrev_b32_e32 v212, 16, v134
	v_and_b32_e32 v213, 0xffff0000, v134
	v_pk_mul_f32 v[212:213], v[212:213], v[198:199] op_sel_hi:[1,0]
	v_pk_fma_f32 v[212:213], v[212:213], v[74:75], v[106:107]
	v_cvt_pk_bf16_f32 v134, v212, v213
	v_lshlrev_b32_e32 v214, 16, v135
	v_and_b32_e32 v215, 0xffff0000, v135
	v_pk_mul_f32 v[214:215], v[214:215], v[198:199] op_sel_hi:[1,0]
	v_pk_fma_f32 v[214:215], v[214:215], v[76:77], v[108:109]
	v_cvt_pk_bf16_f32 v135, v214, v215
	v_lshlrev_b32_e32 v216, 16, v136
	v_and_b32_e32 v217, 0xffff0000, v136
	v_pk_mul_f32 v[216:217], v[216:217], v[198:199] op_sel_hi:[1,0]
	v_pk_fma_f32 v[216:217], v[216:217], v[78:79], v[110:111]
	v_cvt_pk_bf16_f32 v136, v216, v217
	v_lshlrev_b32_e32 v218, 16, v137
	v_and_b32_e32 v219, 0xffff0000, v137
	v_pk_mul_f32 v[218:219], v[218:219], v[198:199] op_sel_hi:[1,0]
	v_pk_fma_f32 v[218:219], v[218:219], v[80:81], v[112:113]
	v_cvt_pk_bf16_f32 v137, v218, v219
	global_store_dwordx4 v[186:187], v[130:133], off offset:2048
	global_store_dwordx4 v[186:187], v[134:137], off offset:3072
	v_lshlrev_b32_e32 v212, 16, v138
	v_and_b32_e32 v213, 0xffff0000, v138
	v_pk_mul_f32 v[212:213], v[212:213], v[200:201] op_sel_hi:[1,0]
	v_pk_fma_f32 v[212:213], v[212:213], v[66:67], v[98:99]
	v_cvt_pk_bf16_f32 v138, v212, v213
	v_lshlrev_b32_e32 v214, 16, v139
	v_and_b32_e32 v215, 0xffff0000, v139
	v_pk_mul_f32 v[214:215], v[214:215], v[200:201] op_sel_hi:[1,0]
	v_pk_fma_f32 v[214:215], v[214:215], v[68:69], v[100:101]
	v_cvt_pk_bf16_f32 v139, v214, v215
	v_lshlrev_b32_e32 v216, 16, v140
	v_and_b32_e32 v217, 0xffff0000, v140
	v_pk_mul_f32 v[216:217], v[216:217], v[200:201] op_sel_hi:[1,0]
	v_pk_fma_f32 v[216:217], v[216:217], v[70:71], v[102:103]
	v_cvt_pk_bf16_f32 v140, v216, v217
	v_lshlrev_b32_e32 v218, 16, v141
	v_and_b32_e32 v219, 0xffff0000, v141
	v_pk_mul_f32 v[218:219], v[218:219], v[200:201] op_sel_hi:[1,0]
	v_pk_fma_f32 v[218:219], v[218:219], v[72:73], v[104:105]
	v_cvt_pk_bf16_f32 v141, v218, v219
	v_lshlrev_b32_e32 v212, 16, v142
	v_and_b32_e32 v213, 0xffff0000, v142
	v_pk_mul_f32 v[212:213], v[212:213], v[200:201] op_sel_hi:[1,0]
	v_pk_fma_f32 v[212:213], v[212:213], v[74:75], v[106:107]
	v_cvt_pk_bf16_f32 v142, v212, v213
	v_lshlrev_b32_e32 v214, 16, v143
	v_and_b32_e32 v215, 0xffff0000, v143
	v_pk_mul_f32 v[214:215], v[214:215], v[200:201] op_sel_hi:[1,0]
	v_pk_fma_f32 v[214:215], v[214:215], v[76:77], v[108:109]
	v_cvt_pk_bf16_f32 v143, v214, v215
	v_lshlrev_b32_e32 v216, 16, v144
	v_and_b32_e32 v217, 0xffff0000, v144
	v_pk_mul_f32 v[216:217], v[216:217], v[200:201] op_sel_hi:[1,0]
	v_pk_fma_f32 v[216:217], v[216:217], v[78:79], v[110:111]
	v_cvt_pk_bf16_f32 v144, v216, v217
	v_lshlrev_b32_e32 v218, 16, v145
	v_and_b32_e32 v219, 0xffff0000, v145
	v_pk_mul_f32 v[218:219], v[218:219], v[200:201] op_sel_hi:[1,0]
	v_pk_fma_f32 v[218:219], v[218:219], v[80:81], v[112:113]
	v_cvt_pk_bf16_f32 v145, v218, v219
	global_store_dwordx4 v[188:189], v[138:141], off
	global_store_dwordx4 v[188:189], v[142:145], off offset:1024
	v_lshlrev_b32_e32 v212, 16, v146
	v_and_b32_e32 v213, 0xffff0000, v146
	v_pk_mul_f32 v[212:213], v[212:213], v[202:203] op_sel_hi:[1,0]
	v_pk_fma_f32 v[212:213], v[212:213], v[66:67], v[98:99]
	v_cvt_pk_bf16_f32 v146, v212, v213
	v_lshlrev_b32_e32 v214, 16, v147
	v_and_b32_e32 v215, 0xffff0000, v147
	v_pk_mul_f32 v[214:215], v[214:215], v[202:203] op_sel_hi:[1,0]
	v_pk_fma_f32 v[214:215], v[214:215], v[68:69], v[100:101]
	v_cvt_pk_bf16_f32 v147, v214, v215
	v_lshlrev_b32_e32 v216, 16, v148
	v_and_b32_e32 v217, 0xffff0000, v148
	v_pk_mul_f32 v[216:217], v[216:217], v[202:203] op_sel_hi:[1,0]
	v_pk_fma_f32 v[216:217], v[216:217], v[70:71], v[102:103]
	v_cvt_pk_bf16_f32 v148, v216, v217
	v_lshlrev_b32_e32 v218, 16, v149
	v_and_b32_e32 v219, 0xffff0000, v149
	v_pk_mul_f32 v[218:219], v[218:219], v[202:203] op_sel_hi:[1,0]
	v_pk_fma_f32 v[218:219], v[218:219], v[72:73], v[104:105]
	v_cvt_pk_bf16_f32 v149, v218, v219
	v_lshlrev_b32_e32 v212, 16, v150
	v_and_b32_e32 v213, 0xffff0000, v150
	v_pk_mul_f32 v[212:213], v[212:213], v[202:203] op_sel_hi:[1,0]
	v_pk_fma_f32 v[212:213], v[212:213], v[74:75], v[106:107]
	v_cvt_pk_bf16_f32 v150, v212, v213
	v_lshlrev_b32_e32 v214, 16, v151
	v_and_b32_e32 v215, 0xffff0000, v151
	v_pk_mul_f32 v[214:215], v[214:215], v[202:203] op_sel_hi:[1,0]
	v_pk_fma_f32 v[214:215], v[214:215], v[76:77], v[108:109]
	v_cvt_pk_bf16_f32 v151, v214, v215
	v_lshlrev_b32_e32 v216, 16, v152
	v_and_b32_e32 v217, 0xffff0000, v152
	v_pk_mul_f32 v[216:217], v[216:217], v[202:203] op_sel_hi:[1,0]
	v_pk_fma_f32 v[216:217], v[216:217], v[78:79], v[110:111]
	v_cvt_pk_bf16_f32 v152, v216, v217
	v_lshlrev_b32_e32 v218, 16, v153
	v_and_b32_e32 v219, 0xffff0000, v153
	v_pk_mul_f32 v[218:219], v[218:219], v[202:203] op_sel_hi:[1,0]
	v_pk_fma_f32 v[218:219], v[218:219], v[80:81], v[112:113]
	v_cvt_pk_bf16_f32 v153, v218, v219
	global_store_dwordx4 v[188:189], v[146:149], off offset:2048
	global_store_dwordx4 v[188:189], v[150:153], off offset:3072
	v_lshlrev_b32_e32 v212, 16, v154
	v_and_b32_e32 v213, 0xffff0000, v154
	v_pk_mul_f32 v[212:213], v[212:213], v[204:205] op_sel_hi:[1,0]
	v_pk_fma_f32 v[212:213], v[212:213], v[66:67], v[98:99]
	v_cvt_pk_bf16_f32 v154, v212, v213
	v_lshlrev_b32_e32 v214, 16, v155
	v_and_b32_e32 v215, 0xffff0000, v155
	v_pk_mul_f32 v[214:215], v[214:215], v[204:205] op_sel_hi:[1,0]
	v_pk_fma_f32 v[214:215], v[214:215], v[68:69], v[100:101]
	v_cvt_pk_bf16_f32 v155, v214, v215
	v_lshlrev_b32_e32 v216, 16, v156
	v_and_b32_e32 v217, 0xffff0000, v156
	v_pk_mul_f32 v[216:217], v[216:217], v[204:205] op_sel_hi:[1,0]
	v_pk_fma_f32 v[216:217], v[216:217], v[70:71], v[102:103]
	v_cvt_pk_bf16_f32 v156, v216, v217
	v_lshlrev_b32_e32 v218, 16, v157
	v_and_b32_e32 v219, 0xffff0000, v157
	v_pk_mul_f32 v[218:219], v[218:219], v[204:205] op_sel_hi:[1,0]
	v_pk_fma_f32 v[218:219], v[218:219], v[72:73], v[104:105]
	v_cvt_pk_bf16_f32 v157, v218, v219
	v_lshlrev_b32_e32 v212, 16, v158
	v_and_b32_e32 v213, 0xffff0000, v158
	v_pk_mul_f32 v[212:213], v[212:213], v[204:205] op_sel_hi:[1,0]
	v_pk_fma_f32 v[212:213], v[212:213], v[74:75], v[106:107]
	v_cvt_pk_bf16_f32 v158, v212, v213
	v_lshlrev_b32_e32 v214, 16, v159
	v_and_b32_e32 v215, 0xffff0000, v159
	v_pk_mul_f32 v[214:215], v[214:215], v[204:205] op_sel_hi:[1,0]
	v_pk_fma_f32 v[214:215], v[214:215], v[76:77], v[108:109]
	v_cvt_pk_bf16_f32 v159, v214, v215
	v_lshlrev_b32_e32 v216, 16, v160
	v_and_b32_e32 v217, 0xffff0000, v160
	v_pk_mul_f32 v[216:217], v[216:217], v[204:205] op_sel_hi:[1,0]
	v_pk_fma_f32 v[216:217], v[216:217], v[78:79], v[110:111]
	v_cvt_pk_bf16_f32 v160, v216, v217
	v_lshlrev_b32_e32 v218, 16, v161
	v_and_b32_e32 v219, 0xffff0000, v161
	v_pk_mul_f32 v[218:219], v[218:219], v[204:205] op_sel_hi:[1,0]
	v_pk_fma_f32 v[218:219], v[218:219], v[80:81], v[112:113]
	v_cvt_pk_bf16_f32 v161, v218, v219
	global_store_dwordx4 v[190:191], v[154:157], off
	global_store_dwordx4 v[190:191], v[158:161], off offset:1024
	v_lshlrev_b32_e32 v212, 16, v162
	v_and_b32_e32 v213, 0xffff0000, v162
	v_pk_mul_f32 v[212:213], v[212:213], v[206:207] op_sel_hi:[1,0]
	v_pk_fma_f32 v[212:213], v[212:213], v[66:67], v[98:99]
	v_cvt_pk_bf16_f32 v162, v212, v213
	v_lshlrev_b32_e32 v214, 16, v163
	v_and_b32_e32 v215, 0xffff0000, v163
	v_pk_mul_f32 v[214:215], v[214:215], v[206:207] op_sel_hi:[1,0]
	v_pk_fma_f32 v[214:215], v[214:215], v[68:69], v[100:101]
	v_cvt_pk_bf16_f32 v163, v214, v215
	v_lshlrev_b32_e32 v216, 16, v164
	v_and_b32_e32 v217, 0xffff0000, v164
	v_pk_mul_f32 v[216:217], v[216:217], v[206:207] op_sel_hi:[1,0]
	v_pk_fma_f32 v[216:217], v[216:217], v[70:71], v[102:103]
	v_cvt_pk_bf16_f32 v164, v216, v217
	v_lshlrev_b32_e32 v218, 16, v165
	v_and_b32_e32 v219, 0xffff0000, v165
	v_pk_mul_f32 v[218:219], v[218:219], v[206:207] op_sel_hi:[1,0]
	v_pk_fma_f32 v[218:219], v[218:219], v[72:73], v[104:105]
	v_cvt_pk_bf16_f32 v165, v218, v219
	v_lshlrev_b32_e32 v212, 16, v166
	v_and_b32_e32 v213, 0xffff0000, v166
	v_pk_mul_f32 v[212:213], v[212:213], v[206:207] op_sel_hi:[1,0]
	v_pk_fma_f32 v[212:213], v[212:213], v[74:75], v[106:107]
	v_cvt_pk_bf16_f32 v166, v212, v213
	v_lshlrev_b32_e32 v214, 16, v167
	v_and_b32_e32 v215, 0xffff0000, v167
	v_pk_mul_f32 v[214:215], v[214:215], v[206:207] op_sel_hi:[1,0]
	v_pk_fma_f32 v[214:215], v[214:215], v[76:77], v[108:109]
	v_cvt_pk_bf16_f32 v167, v214, v215
	v_lshlrev_b32_e32 v216, 16, v168
	v_and_b32_e32 v217, 0xffff0000, v168
	v_pk_mul_f32 v[216:217], v[216:217], v[206:207] op_sel_hi:[1,0]
	v_pk_fma_f32 v[216:217], v[216:217], v[78:79], v[110:111]
	v_cvt_pk_bf16_f32 v168, v216, v217
	v_lshlrev_b32_e32 v218, 16, v169
	v_and_b32_e32 v219, 0xffff0000, v169
	v_pk_mul_f32 v[218:219], v[218:219], v[206:207] op_sel_hi:[1,0]
	v_pk_fma_f32 v[218:219], v[218:219], v[80:81], v[112:113]
	v_cvt_pk_bf16_f32 v169, v218, v219
	global_store_dwordx4 v[190:191], v[162:165], off offset:2048
	global_store_dwordx4 v[190:191], v[166:169], off offset:3072
	v_lshlrev_b32_e32 v212, 16, v170
	v_and_b32_e32 v213, 0xffff0000, v170
	v_pk_mul_f32 v[212:213], v[212:213], v[208:209] op_sel_hi:[1,0]
	v_pk_fma_f32 v[212:213], v[212:213], v[66:67], v[98:99]
	v_cvt_pk_bf16_f32 v170, v212, v213
	v_lshlrev_b32_e32 v214, 16, v171
	v_and_b32_e32 v215, 0xffff0000, v171
	v_pk_mul_f32 v[214:215], v[214:215], v[208:209] op_sel_hi:[1,0]
	v_pk_fma_f32 v[214:215], v[214:215], v[68:69], v[100:101]
	v_cvt_pk_bf16_f32 v171, v214, v215
	v_lshlrev_b32_e32 v216, 16, v172
	v_and_b32_e32 v217, 0xffff0000, v172
	v_pk_mul_f32 v[216:217], v[216:217], v[208:209] op_sel_hi:[1,0]
	v_pk_fma_f32 v[216:217], v[216:217], v[70:71], v[102:103]
	v_cvt_pk_bf16_f32 v172, v216, v217
	v_lshlrev_b32_e32 v218, 16, v173
	v_and_b32_e32 v219, 0xffff0000, v173
	v_pk_mul_f32 v[218:219], v[218:219], v[208:209] op_sel_hi:[1,0]
	v_pk_fma_f32 v[218:219], v[218:219], v[72:73], v[104:105]
	v_cvt_pk_bf16_f32 v173, v218, v219
	v_lshlrev_b32_e32 v212, 16, v174
	v_and_b32_e32 v213, 0xffff0000, v174
	v_pk_mul_f32 v[212:213], v[212:213], v[208:209] op_sel_hi:[1,0]
	v_pk_fma_f32 v[212:213], v[212:213], v[74:75], v[106:107]
	v_cvt_pk_bf16_f32 v174, v212, v213
	v_lshlrev_b32_e32 v214, 16, v175
	v_and_b32_e32 v215, 0xffff0000, v175
	v_pk_mul_f32 v[214:215], v[214:215], v[208:209] op_sel_hi:[1,0]
	v_pk_fma_f32 v[214:215], v[214:215], v[76:77], v[108:109]
	v_cvt_pk_bf16_f32 v175, v214, v215
	v_lshlrev_b32_e32 v216, 16, v176
	v_and_b32_e32 v217, 0xffff0000, v176
	v_pk_mul_f32 v[216:217], v[216:217], v[208:209] op_sel_hi:[1,0]
	v_pk_fma_f32 v[216:217], v[216:217], v[78:79], v[110:111]
	v_cvt_pk_bf16_f32 v176, v216, v217
	v_lshlrev_b32_e32 v218, 16, v177
	v_and_b32_e32 v219, 0xffff0000, v177
	v_pk_mul_f32 v[218:219], v[218:219], v[208:209] op_sel_hi:[1,0]
	v_pk_fma_f32 v[218:219], v[218:219], v[80:81], v[112:113]
	v_cvt_pk_bf16_f32 v177, v218, v219
	global_store_dwordx4 v[192:193], v[170:173], off
	global_store_dwordx4 v[192:193], v[174:177], off offset:1024
	v_lshlrev_b32_e32 v212, 16, v178
	v_and_b32_e32 v213, 0xffff0000, v178
	v_pk_mul_f32 v[212:213], v[212:213], v[210:211] op_sel_hi:[1,0]
	v_pk_fma_f32 v[212:213], v[212:213], v[66:67], v[98:99]
	v_cvt_pk_bf16_f32 v178, v212, v213
	v_lshlrev_b32_e32 v214, 16, v179
	v_and_b32_e32 v215, 0xffff0000, v179
	v_pk_mul_f32 v[214:215], v[214:215], v[210:211] op_sel_hi:[1,0]
	v_pk_fma_f32 v[214:215], v[214:215], v[68:69], v[100:101]
	v_cvt_pk_bf16_f32 v179, v214, v215
	v_lshlrev_b32_e32 v216, 16, v180
	v_and_b32_e32 v217, 0xffff0000, v180
	v_pk_mul_f32 v[216:217], v[216:217], v[210:211] op_sel_hi:[1,0]
	v_pk_fma_f32 v[216:217], v[216:217], v[70:71], v[102:103]
	v_cvt_pk_bf16_f32 v180, v216, v217
	v_lshlrev_b32_e32 v218, 16, v181
	v_and_b32_e32 v219, 0xffff0000, v181
	v_pk_mul_f32 v[218:219], v[218:219], v[210:211] op_sel_hi:[1,0]
	v_pk_fma_f32 v[218:219], v[218:219], v[72:73], v[104:105]
	v_cvt_pk_bf16_f32 v181, v218, v219
	v_lshlrev_b32_e32 v212, 16, v182
	v_and_b32_e32 v213, 0xffff0000, v182
	v_pk_mul_f32 v[212:213], v[212:213], v[210:211] op_sel_hi:[1,0]
	v_pk_fma_f32 v[212:213], v[212:213], v[74:75], v[106:107]
	v_cvt_pk_bf16_f32 v182, v212, v213
	v_lshlrev_b32_e32 v214, 16, v183
	v_and_b32_e32 v215, 0xffff0000, v183
	v_pk_mul_f32 v[214:215], v[214:215], v[210:211] op_sel_hi:[1,0]
	v_pk_fma_f32 v[214:215], v[214:215], v[76:77], v[108:109]
	v_cvt_pk_bf16_f32 v183, v214, v215
	v_lshlrev_b32_e32 v216, 16, v184
	v_and_b32_e32 v217, 0xffff0000, v184
	v_pk_mul_f32 v[216:217], v[216:217], v[210:211] op_sel_hi:[1,0]
	v_pk_fma_f32 v[216:217], v[216:217], v[78:79], v[110:111]
	v_cvt_pk_bf16_f32 v184, v216, v217
	v_lshlrev_b32_e32 v218, 16, v185
	v_and_b32_e32 v219, 0xffff0000, v185
	v_pk_mul_f32 v[218:219], v[218:219], v[210:211] op_sel_hi:[1,0]
	v_pk_fma_f32 v[218:219], v[218:219], v[80:81], v[112:113]
	v_cvt_pk_bf16_f32 v185, v218, v219
	global_store_dwordx4 v[192:193], v[178:181], off offset:2048
	global_store_dwordx4 v[192:193], v[182:185], off offset:3072
	s_mov_b32 s23, s22

.LBB0_592:
	s_min_i32 s15, s14, 0x4000
	s_ashr_i32 s15, s15, 12
	s_cmp_eq_u32 s15, s28
	s_cbranch_scc1 .LBB0_594
	v_mad_i64_i32 v[14:15], s[16:17], s15, v235, v[62:63]
	v_mad_i64_i32 v[46:47], s[16:17], s15, v235, v[60:61]
	global_load_dwordx4 v[2:5], v[14:15], off sc1
	global_load_dwordx4 v[6:9], v[14:15], off offset:1024 sc1
	global_load_dwordx4 v[10:13], v[14:15], off offset:2048 sc1
	s_nop 0
	global_load_dwordx4 v[14:17], v[14:15], off offset:3072 sc1
	s_nop 0
	global_load_dwordx4 v[18:21], v[52:53], off offset:3072 sc1
	global_load_dwordx4 v[22:25], v[52:53], off offset:2048 sc1
	global_load_dwordx4 v[26:29], v[52:53], off offset:1024 sc1
	global_load_dwordx4 v[30:33], v[52:53], off sc1
	global_load_dwordx4 v[42:45], v[46:47], off sc1
	global_load_dwordx4 v[38:41], v[46:47], off offset:1024 sc1
	global_load_dwordx4 v[34:37], v[46:47], off offset:2048 sc1
	s_nop 0
	global_load_dwordx4 v[46:49], v[46:47], off offset:3072 sc1
	s_mov_b32 s28, s15
	s_waitcnt vmcnt(0)
	v_pk_add_f32 v[4:5], v[4:5], 1.0 op_sel_hi:[1,0]
	v_pk_add_f32 v[8:9], v[8:9], 1.0 op_sel_hi:[1,0]
	v_pk_add_f32 v[12:13], v[12:13], 1.0 op_sel_hi:[1,0]
	v_pk_add_f32 v[16:17], v[16:17], 1.0 op_sel_hi:[1,0]
	v_pk_add_f32 v[2:3], v[2:3], 1.0 op_sel_hi:[1,0]
	v_pk_add_f32 v[6:7], v[6:7], 1.0 op_sel_hi:[1,0]
	v_pk_add_f32 v[10:11], v[10:11], 1.0 op_sel_hi:[1,0]
	v_pk_add_f32 v[14:15], v[14:15], 1.0 op_sel_hi:[1,0]
	v_pk_mul_f32 v[16:17], v[20:21], v[16:17]
	v_pk_mul_f32 v[12:13], v[24:25], v[12:13]
	v_pk_mul_f32 v[8:9], v[28:29], v[8:9]
	v_pk_mul_f32 v[4:5], v[32:33], v[4:5]
	v_pk_mul_f32 v[14:15], v[18:19], v[14:15]
	v_pk_mul_f32 v[10:11], v[22:23], v[10:11]
	v_pk_mul_f32 v[6:7], v[26:27], v[6:7]
	v_pk_mul_f32 v[2:3], v[30:31], v[2:3]
.LBB0_594:
	s_cmpk_lt_i32 s14, 0x4000
	s_cselect_b64 s[16:17], -1, 0
	s_and_b64 s[20:21], s[4:5], s[16:17]
	s_ashr_i32 s15, s14, 31
	s_mov_b64 s[18:19], -1
	s_and_b64 vcc, exec, s[20:21]
	s_cbranch_vccnz .LBB0_596
	s_lshl_b64 s[18:19], s[14:15], 11
	v_lshl_add_u64 v[18:19], v[54:55], 0, s[18:19]
	global_load_dwordx2 v[20:21], v[18:19], off sc1
	global_load_dwordx2 v[24:25], v[18:19], off offset:512 sc1
	global_load_dwordx2 v[28:29], v[18:19], off offset:1024 sc1
	global_load_dwordx2 v[32:33], v[18:19], off offset:1536 sc1
	s_mov_b64 s[18:19], 0
	s_waitcnt vmcnt(0)
	v_lshlrev_b32_e32 v18, 16, v20
	v_and_b32_e32 v19, 0xffff0000, v20
	v_lshlrev_b32_e32 v20, 16, v21
	v_and_b32_e32 v21, 0xffff0000, v21
	v_lshlrev_b32_e32 v22, 16, v24
	v_and_b32_e32 v23, 0xffff0000, v24
	v_lshlrev_b32_e32 v24, 16, v25
	v_and_b32_e32 v25, 0xffff0000, v25
	v_lshlrev_b32_e32 v26, 16, v28
	v_and_b32_e32 v27, 0xffff0000, v28
	v_lshlrev_b32_e32 v28, 16, v29
	v_and_b32_e32 v29, 0xffff0000, v29
	v_lshlrev_b32_e32 v30, 16, v32
	v_and_b32_e32 v31, 0xffff0000, v32
	v_lshlrev_b32_e32 v32, 16, v33
	v_and_b32_e32 v33, 0xffff0000, v33

.LBB0_636:
	s_or_b64 exec, exec, s[8:9]
	s_waitcnt vmcnt(0)
	s_nop 0
	s_waitcnt vmcnt(0)

.LBB0_654:
	s_or_b64 exec, exec, s[6:7]
	s_mov_b64 s[6:7], exec
	v_mbcnt_lo_u32_b32 v0, s6, 0
	v_mbcnt_hi_u32_b32 v0, s7, v0
	v_cmp_eq_u32_e32 vcc, 0, v0
	s_waitcnt vmcnt(0)
	s_nop 0
	s_and_saveexec_b64 s[8:9], vcc
	s_cbranch_execz .LBB0_132
	s_bcnt1_i32_b64 s6, s[6:7]
	v_mov_b32_e32 v0, s6
	global_atomic_add v1, v0, s[36:37]
	s_branch .LBB0_132
.LBB0_656:
	s_mov_b32 s8, 20
	v_readfirstlane_b32 s2, v224
	s_ashr_i32 s2, s2, 6
	s_add_i32 s2, s2, s92
	s_mov_b32 s6, 19
	s_mov_b32 s4, 18
	s_cmpk_gt_i32 s2, 0x3fff
	s_cbranch_scc1 .LBB0_659
	s_ashr_i32 s9, s8, 31
	s_lshl_b64 s[8:9], s[8:9], 3
	s_add_u32 s8, s0, s8
	s_addc_u32 s9, s1, s9
	s_ashr_i32 s7, s6, 31
	s_lshl_b64 s[6:7], s[6:7], 3
	s_add_u32 s6, s0, s6
	s_addc_u32 s7, s1, s7
	s_ashr_i32 s5, s4, 31
	s_lshl_b64 s[4:5], s[4:5], 3
	s_add_u32 s0, s0, s4
	s_addc_u32 s1, s1, s5
	s_load_dwordx2 s[0:1], s[0:1], 0x0
	v_lshlrev_b32_e32 v0, 4, v224
	v_and_b32_e32 v16, 0x3f0, v0
	s_waitcnt lgkmcnt(0)
	global_load_dwordx4 v[0:3], v16, s[0:1] sc1
	global_load_dwordx4 v[4:7], v16, s[0:1] offset:1024 sc1
	global_load_dwordx4 v[8:11], v16, s[0:1] offset:2048 sc1
	global_load_dwordx4 v[12:15], v16, s[0:1] offset:3072 sc1
	v_and_b32_e32 v16, 64, v226
	v_add_u32_e32 v16, 64, v16
	v_xor_b32_e32 v17, 1, v226
	v_cmp_lt_i32_e32 vcc, v17, v16
	s_load_dwordx2 s[0:1], s[8:9], 0x0
	s_load_dwordx2 s[10:11], s[6:7], 0x0
	v_cndmask_b32_e32 v17, v226, v17, vcc
	v_lshlrev_b32_e32 v20, 2, v17
	v_xor_b32_e32 v17, 2, v226
	v_cmp_lt_i32_e32 vcc, v17, v16
	s_ashr_i32 s3, s2, 31
	s_lshl_b64 s[4:5], s[2:3], 11
	v_cndmask_b32_e32 v17, v226, v17, vcc
	v_lshlrev_b32_e32 v21, 2, v17
	v_xor_b32_e32 v17, 4, v226
	v_cmp_lt_i32_e32 vcc, v17, v16
	v_and_b32_e32 v26, 63, v224
	s_waitcnt lgkmcnt(0)
	s_add_u32 s0, s0, s4
	v_cndmask_b32_e32 v17, v226, v17, vcc
	v_lshlrev_b32_e32 v22, 2, v17
	v_xor_b32_e32 v17, 8, v226
	v_cmp_lt_i32_e32 vcc, v17, v16
	v_lshlrev_b32_e32 v18, 3, v26
	v_mov_b32_e32 v19, 0
	v_cndmask_b32_e32 v17, v226, v17, vcc
	v_lshlrev_b32_e32 v23, 2, v17
	v_xor_b32_e32 v17, 16, v226
	v_cmp_lt_i32_e32 vcc, v17, v16
	s_addc_u32 s1, s1, s5
	s_ashr_i32 s49, s48, 31
	v_cndmask_b32_e32 v17, v226, v17, vcc
	v_lshlrev_b32_e32 v24, 2, v17
	v_xor_b32_e32 v17, 32, v226
	v_cmp_lt_i32_e32 vcc, v17, v16
	s_lshl_b64 s[4:5], s[48:49], 11
	v_mov_b32_e32 v27, 0x260
	v_cndmask_b32_e32 v16, v226, v17, vcc
	v_lshlrev_b32_e32 v25, 2, v16
	v_lshl_add_u64 v[16:17], s[0:1], 0, v[18:19]
	s_mov_b64 s[0:1], 0x4c00000
	v_lshl_add_u64 v[16:17], v[16:17], 0, s[0:1]
	s_lshl_b64 s[0:1], s[2:3], 12
	s_add_u32 s0, s10, s0
	v_lshlrev_b32_e32 v18, 4, v26
	s_addc_u32 s1, s11, s1
	v_lshl_add_u64 v[18:19], s[0:1], 0, v[18:19]
	s_mov_b64 s[0:1], 0xc00
	v_lshl_add_u64 v[18:19], v[18:19], 0, s[0:1]
	s_lshl_b64 s[6:7], s[48:49], 12
	v_mov_b32_e32 v26, 0x358637bd
	s_mov_b32 s3, 0xf800000
